# M1 epilogue store widening (permlane16_swap to dwordx4) + back-edge rotation (loop counter/test moved above the last barrier) in all 21 GEMM K-loops, on top of attention 3-slot ring
# baseline (speedup 1.0000x reference)
.LBB0_295:
	s_add_u32 s26, s22, 0x100
	s_addc_u32 s27, s23, 0
	s_add_u32 s42, s22, 0xfffff100
	ds_read_b128 v[150:153], v146
	ds_read_b128 v[154:157], v146 offset:1024
	ds_read_b128 v[158:161], v146 offset:2048
	ds_read_b128 v[162:165], v146 offset:3072
	ds_read_b128 v[166:169], v147
	ds_read_b128 v[170:173], v147 offset:1024
	ds_read_b128 v[174:177], v147 offset:2048
	ds_read_b128 v[178:181], v147 offset:3072
	v_cmp_gt_u64_e32 vcc, s[26:27], v[142:143]
	s_addc_u32 s43, s23, -1
	s_and_b64 s[40:41], vcc, exec
	s_cselect_b32 s40, s42, s26
	s_cselect_b32 s41, s43, s27
	s_add_u32 s26, s20, s40
	s_addc_u32 s27, s21, s41
	s_add_u32 s42, s18, s40
	s_addc_u32 s43, s19, s41
	s_cmp_eq_u32 s85, 28
	s_cselect_b32 s55, s11, s27
	s_cselect_b32 s54, s34, s26
	s_cselect_b32 s43, s9, s43
	s_cselect_b32 s42, s35, s42
	s_add_u32 s22, s20, s22
	s_addc_u32 s23, s21, s23
	s_add_u32 s22, s22, 0x80080
	s_addc_u32 s23, s23, 0
	v_lshl_add_u64 v[214:215], s[22:23], 0, v[130:131]
	s_add_i32 m0, s17, 0xc000
	ds_read_b128 v[182:185], v148
	ds_read_b128 v[186:189], v148 offset:1024
	ds_read_b128 v[190:193], v148 offset:2048
	ds_read_b128 v[194:197], v148 offset:3072
	ds_read_b128 v[198:201], v148 offset:4096
	ds_read_b128 v[202:205], v148 offset:5120
	ds_read_b128 v[206:209], v148 offset:6144
	ds_read_b128 v[210:213], v148 offset:7168
	global_load_lds_dwordx4 v[214:215], off
	v_lshl_add_u64 v[214:215], s[22:23], 0, v[134:135]
	s_add_i32 m0, s17, 0xe000
	s_nop 0
	global_load_lds_dwordx4 v[214:215], off
	s_waitcnt vmcnt(8)
	s_waitcnt lgkmcnt(0)
	s_barrier
	s_setprio 1
	s_waitcnt lgkmcnt(0)
	v_mfma_f32_16x16x32_bf16 v[126:129], v[150:153], v[182:185], v[126:129]
	v_mfma_f32_16x16x32_bf16 v[118:121], v[158:161], v[182:185], v[118:121]
	v_mfma_f32_16x16x32_bf16 v[110:113], v[150:153], v[190:193], v[110:113]
	v_mfma_f32_16x16x32_bf16 v[102:105], v[158:161], v[190:193], v[102:105]
	v_mfma_f32_16x16x32_bf16 v[94:97], v[150:153], v[198:201], v[94:97]
	v_mfma_f32_16x16x32_bf16 v[86:89], v[158:161], v[198:201], v[86:89]
	v_mfma_f32_16x16x32_bf16 v[78:81], v[150:153], v[206:209], v[78:81]
	v_mfma_f32_16x16x32_bf16 v[70:73], v[158:161], v[206:209], v[70:73]
	v_mfma_f32_16x16x32_bf16 v[126:129], v[154:157], v[186:189], v[126:129]
	v_mfma_f32_16x16x32_bf16 v[118:121], v[162:165], v[186:189], v[118:121]
	v_mfma_f32_16x16x32_bf16 v[110:113], v[154:157], v[194:197], v[110:113]
	v_mfma_f32_16x16x32_bf16 v[102:105], v[162:165], v[194:197], v[102:105]
	v_mfma_f32_16x16x32_bf16 v[94:97], v[154:157], v[202:205], v[94:97]
	v_mfma_f32_16x16x32_bf16 v[86:89], v[162:165], v[202:205], v[86:89]
	v_mfma_f32_16x16x32_bf16 v[78:81], v[154:157], v[210:213], v[78:81]
	v_mfma_f32_16x16x32_bf16 v[70:73], v[162:165], v[210:213], v[70:73]
	s_setprio 0
	s_setprio 1
	v_mfma_f32_16x16x32_bf16 v[122:125], v[166:169], v[182:185], v[122:125]
	v_mfma_f32_16x16x32_bf16 v[114:117], v[174:177], v[182:185], v[114:117]
	v_mfma_f32_16x16x32_bf16 v[106:109], v[166:169], v[190:193], v[106:109]
	v_mfma_f32_16x16x32_bf16 v[98:101], v[174:177], v[190:193], v[98:101]
	v_mfma_f32_16x16x32_bf16 v[90:93], v[166:169], v[198:201], v[90:93]
	v_mfma_f32_16x16x32_bf16 v[82:85], v[174:177], v[198:201], v[82:85]
	v_mfma_f32_16x16x32_bf16 v[74:77], v[166:169], v[206:209], v[74:77]
	v_mfma_f32_16x16x32_bf16 v[66:69], v[174:177], v[206:209], v[66:69]
	v_mfma_f32_16x16x32_bf16 v[122:125], v[170:173], v[186:189], v[122:125]
	v_mfma_f32_16x16x32_bf16 v[114:117], v[178:181], v[186:189], v[114:117]
	v_mfma_f32_16x16x32_bf16 v[106:109], v[170:173], v[194:197], v[106:109]
	v_mfma_f32_16x16x32_bf16 v[98:101], v[178:181], v[194:197], v[98:101]
	v_mfma_f32_16x16x32_bf16 v[90:93], v[170:173], v[202:205], v[90:93]
	v_mfma_f32_16x16x32_bf16 v[82:85], v[178:181], v[202:205], v[82:85]
	v_mfma_f32_16x16x32_bf16 v[74:77], v[170:173], v[210:213], v[74:77]
	v_mfma_f32_16x16x32_bf16 v[66:69], v[178:181], v[210:213], v[66:69]
	s_setprio 0
	s_barrier
	s_add_i32 s22, s71, s61
	v_lshl_add_u64 v[214:215], s[42:43], 0, v[132:133]
	s_mov_b32 m0, s22
	ds_read_b128 v[182:185], v148 offset:16384
	ds_read_b128 v[186:189], v148 offset:17408
	ds_read_b128 v[190:193], v148 offset:18432
	ds_read_b128 v[194:197], v148 offset:19456
	ds_read_b128 v[198:201], v148 offset:20480
	ds_read_b128 v[202:205], v148 offset:21504
	ds_read_b128 v[206:209], v148 offset:22528
	ds_read_b128 v[210:213], v148 offset:23552
	global_load_lds_dwordx4 v[214:215], off
	s_add_i32 m0, s22, 0x2000
	s_add_u32 s22, s42, 0x80000
	v_lshl_add_u64 v[216:217], s[42:43], 0, v[136:137]
	s_addc_u32 s23, s43, 0
	s_add_i32 s26, s77, s61
	global_load_lds_dwordx4 v[216:217], off
	v_lshl_add_u64 v[218:219], s[22:23], 0, v[132:133]
	s_mov_b32 m0, s26
	v_lshl_add_u64 v[220:221], s[54:55], 0, v[134:135]
	global_load_lds_dwordx4 v[218:219], off
	v_lshl_add_u64 v[218:219], s[22:23], 0, v[136:137]
	s_add_i32 m0, s26, 0x2000
	s_nop 0
	global_load_lds_dwordx4 v[218:219], off
	v_lshl_add_u64 v[218:219], s[54:55], 0, v[130:131]
	s_mov_b32 m0, s17
	s_nop 0
	global_load_lds_dwordx4 v[218:219], off
	s_mov_b32 m0, s62
	s_nop 0
	global_load_lds_dwordx4 v[220:221], off
	s_waitcnt vmcnt(8)
	s_waitcnt lgkmcnt(0)
	s_barrier
	s_setprio 1
	s_waitcnt lgkmcnt(0)
	v_mfma_f32_16x16x32_bf16 v[62:65], v[150:153], v[182:185], v[62:65]
	v_mfma_f32_16x16x32_bf16 v[54:57], v[158:161], v[182:185], v[54:57]
	v_mfma_f32_16x16x32_bf16 v[46:49], v[150:153], v[190:193], v[46:49]
	v_mfma_f32_16x16x32_bf16 v[38:41], v[158:161], v[190:193], v[38:41]
	v_mfma_f32_16x16x32_bf16 v[30:33], v[150:153], v[198:201], v[30:33]
	v_mfma_f32_16x16x32_bf16 v[22:25], v[158:161], v[198:201], v[22:25]
	v_mfma_f32_16x16x32_bf16 v[14:17], v[150:153], v[206:209], v[14:17]
	v_mfma_f32_16x16x32_bf16 v[6:9], v[158:161], v[206:209], v[6:9]
	v_mfma_f32_16x16x32_bf16 v[62:65], v[154:157], v[186:189], v[62:65]
	v_mfma_f32_16x16x32_bf16 v[54:57], v[162:165], v[186:189], v[54:57]
	v_mfma_f32_16x16x32_bf16 v[46:49], v[154:157], v[194:197], v[46:49]
	v_mfma_f32_16x16x32_bf16 v[38:41], v[162:165], v[194:197], v[38:41]
	v_mfma_f32_16x16x32_bf16 v[30:33], v[154:157], v[202:205], v[30:33]
	v_mfma_f32_16x16x32_bf16 v[22:25], v[162:165], v[202:205], v[22:25]
	v_mfma_f32_16x16x32_bf16 v[14:17], v[154:157], v[210:213], v[14:17]
	v_mfma_f32_16x16x32_bf16 v[6:9], v[162:165], v[210:213], v[6:9]
	s_setprio 0
	s_setprio 1
	v_mfma_f32_16x16x32_bf16 v[58:61], v[166:169], v[182:185], v[58:61]
	v_mfma_f32_16x16x32_bf16 v[50:53], v[174:177], v[182:185], v[50:53]
	v_mfma_f32_16x16x32_bf16 v[42:45], v[166:169], v[190:193], v[42:45]
	v_mfma_f32_16x16x32_bf16 v[34:37], v[174:177], v[190:193], v[34:37]
	v_mfma_f32_16x16x32_bf16 v[26:29], v[166:169], v[198:201], v[26:29]
	v_mfma_f32_16x16x32_bf16 v[18:21], v[174:177], v[198:201], v[18:21]
	v_mfma_f32_16x16x32_bf16 v[10:13], v[166:169], v[206:209], v[10:13]
	v_mfma_f32_16x16x32_bf16 v[2:5], v[174:177], v[206:209], v[2:5]
	v_mfma_f32_16x16x32_bf16 v[58:61], v[170:173], v[186:189], v[58:61]
	v_mfma_f32_16x16x32_bf16 v[50:53], v[178:181], v[186:189], v[50:53]
	v_mfma_f32_16x16x32_bf16 v[42:45], v[170:173], v[194:197], v[42:45]
	v_mfma_f32_16x16x32_bf16 v[34:37], v[178:181], v[194:197], v[34:37]
	v_mfma_f32_16x16x32_bf16 v[26:29], v[170:173], v[202:205], v[26:29]
	v_mfma_f32_16x16x32_bf16 v[18:21], v[178:181], v[202:205], v[18:21]
	v_mfma_f32_16x16x32_bf16 v[10:13], v[170:173], v[210:213], v[10:13]
	v_mfma_f32_16x16x32_bf16 v[2:5], v[178:181], v[210:213], v[2:5]
	s_setprio 0
	s_barrier
	s_add_i32 s26, 0, 0x18000
	v_add_u32_e32 v149, s26, v144
	s_add_i32 s27, 0, 0x1c000
	ds_read_b128 v[150:153], v149
	ds_read_b128 v[154:157], v149 offset:1024
	ds_read_b128 v[158:161], v149 offset:2048
	ds_read_b128 v[162:165], v149 offset:3072
	v_add_u32_e32 v149, s27, v144
	ds_read_b128 v[166:169], v149
	ds_read_b128 v[170:173], v149 offset:1024
	ds_read_b128 v[174:177], v149 offset:2048
	ds_read_b128 v[178:181], v149 offset:3072
	s_add_u32 s22, s54, 0x80000
	s_addc_u32 s23, s55, 0
	s_mov_b32 m0, s63
	v_lshl_add_u64 v[222:223], s[22:23], 0, v[130:131]
	ds_read_b128 v[182:185], v148 offset:32768
	ds_read_b128 v[186:189], v148 offset:33792
	ds_read_b128 v[190:193], v148 offset:34816
	ds_read_b128 v[194:197], v148 offset:35840
	ds_read_b128 v[198:201], v148 offset:36864
	ds_read_b128 v[202:205], v148 offset:37888
	ds_read_b128 v[206:209], v148 offset:38912
	ds_read_b128 v[210:213], v148 offset:39936
	global_load_lds_dwordx4 v[222:223], off
	v_lshl_add_u64 v[222:223], s[22:23], 0, v[134:135]
	s_mov_b32 m0, s66
	s_nop 0
	global_load_lds_dwordx4 v[222:223], off
	s_waitcnt vmcnt(8)
	s_waitcnt lgkmcnt(0)
	s_barrier
	s_setprio 1
	s_waitcnt lgkmcnt(0)
	v_mfma_f32_16x16x32_bf16 v[126:129], v[150:153], v[182:185], v[126:129]
	v_mfma_f32_16x16x32_bf16 v[118:121], v[158:161], v[182:185], v[118:121]
	v_mfma_f32_16x16x32_bf16 v[110:113], v[150:153], v[190:193], v[110:113]
	v_mfma_f32_16x16x32_bf16 v[102:105], v[158:161], v[190:193], v[102:105]
	v_mfma_f32_16x16x32_bf16 v[94:97], v[150:153], v[198:201], v[94:97]
	v_mfma_f32_16x16x32_bf16 v[86:89], v[158:161], v[198:201], v[86:89]
	v_mfma_f32_16x16x32_bf16 v[78:81], v[150:153], v[206:209], v[78:81]
	v_mfma_f32_16x16x32_bf16 v[70:73], v[158:161], v[206:209], v[70:73]
	v_mfma_f32_16x16x32_bf16 v[126:129], v[154:157], v[186:189], v[126:129]
	v_mfma_f32_16x16x32_bf16 v[118:121], v[162:165], v[186:189], v[118:121]
	v_mfma_f32_16x16x32_bf16 v[110:113], v[154:157], v[194:197], v[110:113]
	v_mfma_f32_16x16x32_bf16 v[102:105], v[162:165], v[194:197], v[102:105]
	v_mfma_f32_16x16x32_bf16 v[94:97], v[154:157], v[202:205], v[94:97]
	v_mfma_f32_16x16x32_bf16 v[86:89], v[162:165], v[202:205], v[86:89]
	v_mfma_f32_16x16x32_bf16 v[78:81], v[154:157], v[210:213], v[78:81]
	v_mfma_f32_16x16x32_bf16 v[70:73], v[162:165], v[210:213], v[70:73]
	s_setprio 0
	s_setprio 1
	v_mfma_f32_16x16x32_bf16 v[122:125], v[166:169], v[182:185], v[122:125]
	v_mfma_f32_16x16x32_bf16 v[114:117], v[174:177], v[182:185], v[114:117]
	v_mfma_f32_16x16x32_bf16 v[106:109], v[166:169], v[190:193], v[106:109]
	v_mfma_f32_16x16x32_bf16 v[98:101], v[174:177], v[190:193], v[98:101]
	v_mfma_f32_16x16x32_bf16 v[90:93], v[166:169], v[198:201], v[90:93]
	v_mfma_f32_16x16x32_bf16 v[82:85], v[174:177], v[198:201], v[82:85]
	v_mfma_f32_16x16x32_bf16 v[74:77], v[166:169], v[206:209], v[74:77]
	v_mfma_f32_16x16x32_bf16 v[66:69], v[174:177], v[206:209], v[66:69]
	v_mfma_f32_16x16x32_bf16 v[122:125], v[170:173], v[186:189], v[122:125]
	v_mfma_f32_16x16x32_bf16 v[114:117], v[178:181], v[186:189], v[114:117]
	v_mfma_f32_16x16x32_bf16 v[106:109], v[170:173], v[194:197], v[106:109]
	v_mfma_f32_16x16x32_bf16 v[98:101], v[178:181], v[194:197], v[98:101]
	v_mfma_f32_16x16x32_bf16 v[90:93], v[170:173], v[202:205], v[90:93]
	v_mfma_f32_16x16x32_bf16 v[82:85], v[178:181], v[202:205], v[82:85]
	v_mfma_f32_16x16x32_bf16 v[74:77], v[170:173], v[210:213], v[74:77]
	v_mfma_f32_16x16x32_bf16 v[66:69], v[178:181], v[210:213], v[66:69]
	s_setprio 0
	s_barrier
	s_add_i32 s22, s26, s61
	v_lshl_add_u64 v[214:215], v[214:215], 0, s[4:5]
	s_mov_b32 m0, s22
	ds_read_b128 v[182:185], v148 offset:49152
	ds_read_b128 v[186:189], v148 offset:50176
	ds_read_b128 v[190:193], v148 offset:51200
	ds_read_b128 v[194:197], v148 offset:52224
	ds_read_b128 v[198:201], v148 offset:53248
	ds_read_b128 v[202:205], v148 offset:54272
	ds_read_b128 v[206:209], v148 offset:55296
	ds_read_b128 v[210:213], v148 offset:56320
	global_load_lds_dwordx4 v[214:215], off
	s_add_i32 m0, s22, 0x2000
	s_add_u32 s22, s42, 0x80080
	v_lshl_add_u64 v[214:215], v[216:217], 0, s[4:5]
	s_addc_u32 s23, s43, 0
	s_add_i32 s26, s27, s61
	global_load_lds_dwordx4 v[214:215], off
	v_lshl_add_u64 v[214:215], s[22:23], 0, v[132:133]
	s_mov_b32 m0, s26
	s_nop 0
	global_load_lds_dwordx4 v[214:215], off
	v_lshl_add_u64 v[214:215], s[22:23], 0, v[136:137]
	s_add_i32 m0, s26, 0x2000
	s_nop 0
	global_load_lds_dwordx4 v[214:215], off
	v_lshl_add_u64 v[214:215], v[218:219], 0, s[4:5]
	s_mov_b32 m0, s68
	s_nop 0
	global_load_lds_dwordx4 v[214:215], off
	v_lshl_add_u64 v[214:215], v[220:221], 0, s[4:5]
	s_mov_b32 m0, s69
	s_nop 0
	global_load_lds_dwordx4 v[214:215], off
	s_waitcnt vmcnt(8)
	s_waitcnt lgkmcnt(0)
	s_barrier
	s_setprio 1
	s_waitcnt lgkmcnt(0)
	v_mfma_f32_16x16x32_bf16 v[62:65], v[150:153], v[182:185], v[62:65]
	v_mfma_f32_16x16x32_bf16 v[54:57], v[158:161], v[182:185], v[54:57]
	v_mfma_f32_16x16x32_bf16 v[46:49], v[150:153], v[190:193], v[46:49]
	v_mfma_f32_16x16x32_bf16 v[38:41], v[158:161], v[190:193], v[38:41]
	v_mfma_f32_16x16x32_bf16 v[30:33], v[150:153], v[198:201], v[30:33]
	v_mfma_f32_16x16x32_bf16 v[22:25], v[158:161], v[198:201], v[22:25]
	v_mfma_f32_16x16x32_bf16 v[14:17], v[150:153], v[206:209], v[14:17]
	v_mfma_f32_16x16x32_bf16 v[6:9], v[158:161], v[206:209], v[6:9]
	v_mfma_f32_16x16x32_bf16 v[62:65], v[154:157], v[186:189], v[62:65]
	v_mfma_f32_16x16x32_bf16 v[54:57], v[162:165], v[186:189], v[54:57]
	v_mfma_f32_16x16x32_bf16 v[46:49], v[154:157], v[194:197], v[46:49]
	v_mfma_f32_16x16x32_bf16 v[38:41], v[162:165], v[194:197], v[38:41]
	v_mfma_f32_16x16x32_bf16 v[30:33], v[154:157], v[202:205], v[30:33]
	v_mfma_f32_16x16x32_bf16 v[22:25], v[162:165], v[202:205], v[22:25]
	v_mfma_f32_16x16x32_bf16 v[14:17], v[154:157], v[210:213], v[14:17]
	v_mfma_f32_16x16x32_bf16 v[6:9], v[162:165], v[210:213], v[6:9]
	s_setprio 0
	s_setprio 1
	v_mfma_f32_16x16x32_bf16 v[58:61], v[166:169], v[182:185], v[58:61]
	v_mfma_f32_16x16x32_bf16 v[50:53], v[174:177], v[182:185], v[50:53]
	v_mfma_f32_16x16x32_bf16 v[42:45], v[166:169], v[190:193], v[42:45]
	v_mfma_f32_16x16x32_bf16 v[34:37], v[174:177], v[190:193], v[34:37]
	v_mfma_f32_16x16x32_bf16 v[26:29], v[166:169], v[198:201], v[26:29]
	v_mfma_f32_16x16x32_bf16 v[18:21], v[174:177], v[198:201], v[18:21]
	v_mfma_f32_16x16x32_bf16 v[10:13], v[166:169], v[206:209], v[10:13]
	v_mfma_f32_16x16x32_bf16 v[2:5], v[174:177], v[206:209], v[2:5]
	v_mfma_f32_16x16x32_bf16 v[58:61], v[170:173], v[186:189], v[58:61]
	v_mfma_f32_16x16x32_bf16 v[50:53], v[178:181], v[186:189], v[50:53]
	v_mfma_f32_16x16x32_bf16 v[42:45], v[170:173], v[194:197], v[42:45]
	v_mfma_f32_16x16x32_bf16 v[34:37], v[178:181], v[194:197], v[34:37]
	v_mfma_f32_16x16x32_bf16 v[26:29], v[170:173], v[202:205], v[26:29]
	v_mfma_f32_16x16x32_bf16 v[18:21], v[178:181], v[202:205], v[18:21]
	v_mfma_f32_16x16x32_bf16 v[10:13], v[170:173], v[210:213], v[10:13]
	v_mfma_f32_16x16x32_bf16 v[2:5], v[178:181], v[210:213], v[2:5]
	s_setprio 0
	s_add_i32 s85, s85, 2
	s_cmp_gt_u32 s85, 29
	s_mov_b64 s[22:23], s[40:41]
	s_barrier
	s_cbranch_scc0 .LBB0_295
	s_and_b64 vcc, exec, s[6:7]
	s_cbranch_vccz .LBB0_298
	s_barrier

.LBB0_369:
	s_add_u32 s26, s8, s12
	s_addc_u32 s27, s9, s13
	s_add_u32 s12, s12, 0x100
	ds_read_b128 v[138:141], v88
	ds_read_b128 v[142:145], v88 offset:1024
	ds_read_b128 v[154:157], v88 offset:2048
	ds_read_b128 v[158:161], v88 offset:3072
	ds_read_b128 v[162:165], v89
	ds_read_b128 v[166:169], v89 offset:1024
	ds_read_b128 v[170:173], v89 offset:2048
	ds_read_b128 v[174:177], v89 offset:3072
	s_addc_u32 s13, s13, 0
	v_cmp_lt_u64_e32 vcc, s[12:13], v[86:87]
	s_and_b64 s[14:15], vcc, exec
	s_cselect_b32 s15, 0, 0xffffd500
	s_cselect_b32 s14, 0, -1
	s_add_u32 s12, s15, s12
	s_addc_u32 s13, s14, s13
	s_cmpk_lg_i32 s68, 0x52
	s_cselect_b32 s14, s12, 0
	s_cselect_b32 s15, s13, 0
	s_add_u32 s16, s8, s14
	s_addc_u32 s17, s9, s15
	s_add_u32 s14, s0, s14
	s_addc_u32 s15, s1, s15
	s_add_u32 s26, s26, 0x158080
	s_addc_u32 s27, s27, 0
	s_mov_b32 m0, s69
	v_lshl_add_u64 v[178:179], s[26:27], 0, v[146:147]
	ds_read_b128 v[188:191], v134
	ds_read_b128 v[192:195], v134 offset:1024
	ds_read_b128 v[196:199], v134 offset:2048
	ds_read_b128 v[200:203], v134 offset:3072
	ds_read_b128 v[204:207], v134 offset:4096
	ds_read_b128 v[208:211], v134 offset:5120
	ds_read_b128 v[212:215], v134 offset:6144
	ds_read_b128 v[216:219], v134 offset:7168
	global_load_lds_dwordx4 v[178:179], off
	v_lshl_add_u64 v[178:179], s[26:27], 0, v[150:151]
	s_mov_b32 m0, s70
	s_nop 0
	global_load_lds_dwordx4 v[178:179], off
	s_waitcnt vmcnt(8)
	s_waitcnt lgkmcnt(0)
	s_barrier
	s_setprio 1
	s_waitcnt lgkmcnt(0)
	v_mfma_f32_16x16x32_bf16 v[30:33], v[138:141], v[188:191], v[30:33]
	v_mfma_f32_16x16x32_bf16 v[58:61], v[154:157], v[188:191], v[58:61]
	v_mfma_f32_16x16x32_bf16 v[110:113], v[138:141], v[196:199], v[110:113]
	v_mfma_f32_16x16x32_bf16 v[130:133], v[154:157], v[196:199], v[130:133]
	v_mfma_f32_16x16x32_bf16 v[74:77], v[138:141], v[204:207], v[74:77]
	v_mfma_f32_16x16x32_bf16 v[66:69], v[154:157], v[204:207], v[66:69]
	v_mfma_f32_16x16x32_bf16 v[126:129], v[138:141], v[212:215], v[126:129]
	v_mfma_f32_16x16x32_bf16 v[50:53], v[154:157], v[212:215], v[50:53]
	v_mfma_f32_16x16x32_bf16 v[30:33], v[142:145], v[192:195], v[30:33]
	v_mfma_f32_16x16x32_bf16 v[58:61], v[158:161], v[192:195], v[58:61]
	v_mfma_f32_16x16x32_bf16 v[110:113], v[142:145], v[200:203], v[110:113]
	v_mfma_f32_16x16x32_bf16 v[130:133], v[158:161], v[200:203], v[130:133]
	v_mfma_f32_16x16x32_bf16 v[74:77], v[142:145], v[208:211], v[74:77]
	v_mfma_f32_16x16x32_bf16 v[66:69], v[158:161], v[208:211], v[66:69]
	v_mfma_f32_16x16x32_bf16 v[126:129], v[142:145], v[216:219], v[126:129]
	v_mfma_f32_16x16x32_bf16 v[50:53], v[158:161], v[216:219], v[50:53]
	s_setprio 0
	s_setprio 1
	v_mfma_f32_16x16x32_bf16 v[82:85], v[162:165], v[188:191], v[82:85]
	v_mfma_f32_16x16x32_bf16 v[62:65], v[170:173], v[188:191], v[62:65]
	v_mfma_f32_16x16x32_bf16 v[38:41], v[162:165], v[196:199], v[38:41]
	v_mfma_f32_16x16x32_bf16 v[26:29], v[170:173], v[196:199], v[26:29]
	v_mfma_f32_16x16x32_bf16 v[46:49], v[162:165], v[204:207], v[46:49]
	v_mfma_f32_16x16x32_bf16 v[34:37], v[170:173], v[204:207], v[34:37]
	v_mfma_f32_16x16x32_bf16 v[42:45], v[162:165], v[212:215], v[42:45]
	v_mfma_f32_16x16x32_bf16 v[70:73], v[170:173], v[212:215], v[70:73]
	v_mfma_f32_16x16x32_bf16 v[82:85], v[166:169], v[192:195], v[82:85]
	v_mfma_f32_16x16x32_bf16 v[62:65], v[174:177], v[192:195], v[62:65]
	v_mfma_f32_16x16x32_bf16 v[38:41], v[166:169], v[200:203], v[38:41]
	v_mfma_f32_16x16x32_bf16 v[26:29], v[174:177], v[200:203], v[26:29]
	v_mfma_f32_16x16x32_bf16 v[46:49], v[166:169], v[208:211], v[46:49]
	v_mfma_f32_16x16x32_bf16 v[34:37], v[174:177], v[208:211], v[34:37]
	v_mfma_f32_16x16x32_bf16 v[42:45], v[166:169], v[216:219], v[42:45]
	v_mfma_f32_16x16x32_bf16 v[70:73], v[174:177], v[216:219], v[70:73]
	s_setprio 0
	s_barrier
	s_mov_b32 m0, s71
	v_lshl_add_u64 v[178:179], s[14:15], 0, v[148:149]
	s_add_u32 s26, s14, 0x158000
	ds_read_b128 v[188:191], v134 offset:16384
	ds_read_b128 v[192:195], v134 offset:17408
	ds_read_b128 v[196:199], v134 offset:18432
	ds_read_b128 v[200:203], v134 offset:19456
	ds_read_b128 v[204:207], v134 offset:20480
	ds_read_b128 v[208:211], v134 offset:21504
	ds_read_b128 v[212:215], v134 offset:22528
	ds_read_b128 v[216:219], v134 offset:23552
	global_load_lds_dwordx4 v[178:179], off
	v_lshl_add_u64 v[220:221], s[14:15], 0, v[152:153]
	s_mov_b32 m0, s77
	s_addc_u32 s27, s15, 0
	global_load_lds_dwordx4 v[220:221], off
	v_lshl_add_u64 v[222:223], s[26:27], 0, v[148:149]
	s_mov_b32 m0, s80
	v_lshl_add_u64 v[224:225], s[16:17], 0, v[150:151]
	global_load_lds_dwordx4 v[222:223], off
	v_lshl_add_u64 v[222:223], s[26:27], 0, v[152:153]
	s_mov_b32 m0, s81
	s_nop 0
	global_load_lds_dwordx4 v[222:223], off
	v_lshl_add_u64 v[222:223], s[16:17], 0, v[146:147]
	s_mov_b32 m0, s61
	s_nop 0
	global_load_lds_dwordx4 v[222:223], off
	s_mov_b32 m0, s62
	s_nop 0
	global_load_lds_dwordx4 v[224:225], off
	s_waitcnt vmcnt(8)
	s_waitcnt lgkmcnt(0)
	s_barrier
	s_setprio 1
	s_waitcnt lgkmcnt(0)
	v_mfma_f32_16x16x32_bf16 v[102:105], v[138:141], v[188:191], v[102:105]
	v_mfma_f32_16x16x32_bf16 v[118:121], v[154:157], v[188:191], v[118:121]
	v_mfma_f32_16x16x32_bf16 v[122:125], v[138:141], v[196:199], v[122:125]
	v_mfma_f32_16x16x32_bf16 v[114:117], v[154:157], v[196:199], v[114:117]
	v_mfma_f32_16x16x32_bf16 v[98:101], v[138:141], v[204:207], v[98:101]
	v_mfma_f32_16x16x32_bf16 v[54:57], v[154:157], v[204:207], v[54:57]
	v_mfma_f32_16x16x32_bf16 v[22:25], v[138:141], v[212:215], v[22:25]
	v_mfma_f32_16x16x32_bf16 v[14:17], v[154:157], v[212:215], v[14:17]
	v_mfma_f32_16x16x32_bf16 v[102:105], v[142:145], v[192:195], v[102:105]
	v_mfma_f32_16x16x32_bf16 v[118:121], v[158:161], v[192:195], v[118:121]
	v_mfma_f32_16x16x32_bf16 v[122:125], v[142:145], v[200:203], v[122:125]
	v_mfma_f32_16x16x32_bf16 v[114:117], v[158:161], v[200:203], v[114:117]
	v_mfma_f32_16x16x32_bf16 v[98:101], v[142:145], v[208:211], v[98:101]
	v_mfma_f32_16x16x32_bf16 v[54:57], v[158:161], v[208:211], v[54:57]
	v_mfma_f32_16x16x32_bf16 v[22:25], v[142:145], v[216:219], v[22:25]
	v_mfma_f32_16x16x32_bf16 v[14:17], v[158:161], v[216:219], v[14:17]
	s_setprio 0
	s_setprio 1
	v_mfma_f32_16x16x32_bf16 v[106:109], v[162:165], v[188:191], v[106:109]
	v_mfma_f32_16x16x32_bf16 v[90:93], v[170:173], v[188:191], v[90:93]
	v_mfma_f32_16x16x32_bf16 v[94:97], v[162:165], v[196:199], v[94:97]
	v_mfma_f32_16x16x32_bf16 v[78:81], v[170:173], v[196:199], v[78:81]
	v_mfma_f32_16x16x32_bf16 v[18:21], v[162:165], v[204:207], v[18:21]
	v_mfma_f32_16x16x32_bf16 v[10:13], v[170:173], v[204:207], v[10:13]
	v_mfma_f32_16x16x32_bf16 v[6:9], v[162:165], v[212:215], v[6:9]
	v_mfma_f32_16x16x32_bf16 v[2:5], v[170:173], v[212:215], v[2:5]
	v_mfma_f32_16x16x32_bf16 v[106:109], v[166:169], v[192:195], v[106:109]
	v_mfma_f32_16x16x32_bf16 v[90:93], v[174:177], v[192:195], v[90:93]
	v_mfma_f32_16x16x32_bf16 v[94:97], v[166:169], v[200:203], v[94:97]
	v_mfma_f32_16x16x32_bf16 v[78:81], v[174:177], v[200:203], v[78:81]
	v_mfma_f32_16x16x32_bf16 v[18:21], v[166:169], v[208:211], v[18:21]
	v_mfma_f32_16x16x32_bf16 v[10:13], v[174:177], v[208:211], v[10:13]
	v_mfma_f32_16x16x32_bf16 v[6:9], v[166:169], v[216:219], v[6:9]
	v_mfma_f32_16x16x32_bf16 v[2:5], v[174:177], v[216:219], v[2:5]
	s_setprio 0
	s_barrier
	ds_read_b128 v[138:141], v135
	ds_read_b128 v[142:145], v135 offset:1024
	ds_read_b128 v[154:157], v135 offset:2048
	ds_read_b128 v[158:161], v135 offset:3072
	ds_read_b128 v[162:165], v136
	ds_read_b128 v[166:169], v136 offset:1024
	ds_read_b128 v[170:173], v136 offset:2048
	ds_read_b128 v[174:177], v136 offset:3072
	s_add_u32 s16, s16, 0x158000
	s_addc_u32 s17, s17, 0
	s_mov_b32 m0, s63
	v_lshl_add_u64 v[226:227], s[16:17], 0, v[146:147]
	ds_read_b128 v[188:191], v134 offset:32768
	ds_read_b128 v[192:195], v134 offset:33792
	ds_read_b128 v[196:199], v134 offset:34816
	ds_read_b128 v[200:203], v134 offset:35840
	ds_read_b128 v[204:207], v134 offset:36864
	ds_read_b128 v[208:211], v134 offset:37888
	ds_read_b128 v[212:215], v134 offset:38912
	ds_read_b128 v[216:219], v134 offset:39936
	global_load_lds_dwordx4 v[226:227], off
	v_lshl_add_u64 v[226:227], s[16:17], 0, v[150:151]
	s_mov_b32 m0, s66
	s_nop 0
	global_load_lds_dwordx4 v[226:227], off
	s_waitcnt vmcnt(8)
	s_waitcnt lgkmcnt(0)
	s_barrier
	s_setprio 1
	s_waitcnt lgkmcnt(0)
	v_mfma_f32_16x16x32_bf16 v[30:33], v[138:141], v[188:191], v[30:33]
	v_mfma_f32_16x16x32_bf16 v[58:61], v[154:157], v[188:191], v[58:61]
	v_mfma_f32_16x16x32_bf16 v[110:113], v[138:141], v[196:199], v[110:113]
	v_mfma_f32_16x16x32_bf16 v[130:133], v[154:157], v[196:199], v[130:133]
	v_mfma_f32_16x16x32_bf16 v[74:77], v[138:141], v[204:207], v[74:77]
	v_mfma_f32_16x16x32_bf16 v[66:69], v[154:157], v[204:207], v[66:69]
	v_mfma_f32_16x16x32_bf16 v[126:129], v[138:141], v[212:215], v[126:129]
	v_mfma_f32_16x16x32_bf16 v[50:53], v[154:157], v[212:215], v[50:53]
	v_mfma_f32_16x16x32_bf16 v[30:33], v[142:145], v[192:195], v[30:33]
	v_mfma_f32_16x16x32_bf16 v[58:61], v[158:161], v[192:195], v[58:61]
	v_mfma_f32_16x16x32_bf16 v[110:113], v[142:145], v[200:203], v[110:113]
	v_mfma_f32_16x16x32_bf16 v[130:133], v[158:161], v[200:203], v[130:133]
	v_mfma_f32_16x16x32_bf16 v[74:77], v[142:145], v[208:211], v[74:77]
	v_mfma_f32_16x16x32_bf16 v[66:69], v[158:161], v[208:211], v[66:69]
	v_mfma_f32_16x16x32_bf16 v[126:129], v[142:145], v[216:219], v[126:129]
	v_mfma_f32_16x16x32_bf16 v[50:53], v[158:161], v[216:219], v[50:53]
	s_setprio 0
	s_setprio 1
	v_mfma_f32_16x16x32_bf16 v[82:85], v[162:165], v[188:191], v[82:85]
	v_mfma_f32_16x16x32_bf16 v[62:65], v[170:173], v[188:191], v[62:65]
	v_mfma_f32_16x16x32_bf16 v[38:41], v[162:165], v[196:199], v[38:41]
	v_mfma_f32_16x16x32_bf16 v[26:29], v[170:173], v[196:199], v[26:29]
	v_mfma_f32_16x16x32_bf16 v[46:49], v[162:165], v[204:207], v[46:49]
	v_mfma_f32_16x16x32_bf16 v[34:37], v[170:173], v[204:207], v[34:37]
	v_mfma_f32_16x16x32_bf16 v[42:45], v[162:165], v[212:215], v[42:45]
	v_mfma_f32_16x16x32_bf16 v[70:73], v[170:173], v[212:215], v[70:73]
	v_mfma_f32_16x16x32_bf16 v[82:85], v[166:169], v[192:195], v[82:85]
	v_mfma_f32_16x16x32_bf16 v[62:65], v[174:177], v[192:195], v[62:65]
	v_mfma_f32_16x16x32_bf16 v[38:41], v[166:169], v[200:203], v[38:41]
	v_mfma_f32_16x16x32_bf16 v[26:29], v[174:177], v[200:203], v[26:29]
	v_mfma_f32_16x16x32_bf16 v[46:49], v[166:169], v[208:211], v[46:49]
	v_mfma_f32_16x16x32_bf16 v[34:37], v[174:177], v[208:211], v[34:37]
	v_mfma_f32_16x16x32_bf16 v[42:45], v[166:169], v[216:219], v[42:45]
	v_mfma_f32_16x16x32_bf16 v[70:73], v[174:177], v[216:219], v[70:73]
	s_setprio 0
	s_barrier
	s_mov_b32 m0, s85
	v_lshl_add_u64 v[178:179], v[178:179], 0, s[10:11]
	s_add_u32 s14, s14, 0x158080
	ds_read_b128 v[188:191], v134 offset:49152
	ds_read_b128 v[192:195], v134 offset:50176
	ds_read_b128 v[196:199], v134 offset:51200
	ds_read_b128 v[200:203], v134 offset:52224
	ds_read_b128 v[204:207], v134 offset:53248
	ds_read_b128 v[208:211], v134 offset:54272
	ds_read_b128 v[212:215], v134 offset:55296
	ds_read_b128 v[216:219], v134 offset:56320
	global_load_lds_dwordx4 v[178:179], off
	v_lshl_add_u64 v[178:179], v[220:221], 0, s[10:11]
	s_mov_b32 m0, s88
	s_addc_u32 s15, s15, 0
	global_load_lds_dwordx4 v[178:179], off
	v_lshl_add_u64 v[178:179], s[14:15], 0, v[148:149]
	s_mov_b32 m0, s89
	s_nop 0
	global_load_lds_dwordx4 v[178:179], off
	v_lshl_add_u64 v[178:179], s[14:15], 0, v[152:153]
	s_mov_b32 m0, s90
	s_nop 0
	global_load_lds_dwordx4 v[178:179], off
	v_lshl_add_u64 v[178:179], v[222:223], 0, s[10:11]
	s_mov_b32 m0, s34
	s_nop 0
	global_load_lds_dwordx4 v[178:179], off
	v_lshl_add_u64 v[178:179], v[224:225], 0, s[10:11]
	s_mov_b32 m0, s35
	s_nop 0
	global_load_lds_dwordx4 v[178:179], off
	s_waitcnt vmcnt(8)
	s_waitcnt lgkmcnt(0)
	s_barrier
	s_setprio 1
	s_waitcnt lgkmcnt(0)
	v_mfma_f32_16x16x32_bf16 v[102:105], v[138:141], v[188:191], v[102:105]
	v_mfma_f32_16x16x32_bf16 v[118:121], v[154:157], v[188:191], v[118:121]
	v_mfma_f32_16x16x32_bf16 v[122:125], v[138:141], v[196:199], v[122:125]
	v_mfma_f32_16x16x32_bf16 v[114:117], v[154:157], v[196:199], v[114:117]
	v_mfma_f32_16x16x32_bf16 v[98:101], v[138:141], v[204:207], v[98:101]
	v_mfma_f32_16x16x32_bf16 v[54:57], v[154:157], v[204:207], v[54:57]
	v_mfma_f32_16x16x32_bf16 v[22:25], v[138:141], v[212:215], v[22:25]
	v_mfma_f32_16x16x32_bf16 v[14:17], v[154:157], v[212:215], v[14:17]
	v_mfma_f32_16x16x32_bf16 v[102:105], v[142:145], v[192:195], v[102:105]
	v_mfma_f32_16x16x32_bf16 v[118:121], v[158:161], v[192:195], v[118:121]
	v_mfma_f32_16x16x32_bf16 v[122:125], v[142:145], v[200:203], v[122:125]
	v_mfma_f32_16x16x32_bf16 v[114:117], v[158:161], v[200:203], v[114:117]
	v_mfma_f32_16x16x32_bf16 v[98:101], v[142:145], v[208:211], v[98:101]
	v_mfma_f32_16x16x32_bf16 v[54:57], v[158:161], v[208:211], v[54:57]
	v_mfma_f32_16x16x32_bf16 v[22:25], v[142:145], v[216:219], v[22:25]
	v_mfma_f32_16x16x32_bf16 v[14:17], v[158:161], v[216:219], v[14:17]
	s_setprio 0
	s_setprio 1
	v_mfma_f32_16x16x32_bf16 v[106:109], v[162:165], v[188:191], v[106:109]
	v_mfma_f32_16x16x32_bf16 v[90:93], v[170:173], v[188:191], v[90:93]
	v_mfma_f32_16x16x32_bf16 v[94:97], v[162:165], v[196:199], v[94:97]
	v_mfma_f32_16x16x32_bf16 v[78:81], v[170:173], v[196:199], v[78:81]
	v_mfma_f32_16x16x32_bf16 v[18:21], v[162:165], v[204:207], v[18:21]
	v_mfma_f32_16x16x32_bf16 v[10:13], v[170:173], v[204:207], v[10:13]
	v_mfma_f32_16x16x32_bf16 v[6:9], v[162:165], v[212:215], v[6:9]
	v_mfma_f32_16x16x32_bf16 v[2:5], v[170:173], v[212:215], v[2:5]
	v_mfma_f32_16x16x32_bf16 v[106:109], v[166:169], v[192:195], v[106:109]
	v_mfma_f32_16x16x32_bf16 v[90:93], v[174:177], v[192:195], v[90:93]
	v_mfma_f32_16x16x32_bf16 v[94:97], v[166:169], v[200:203], v[94:97]
	v_mfma_f32_16x16x32_bf16 v[78:81], v[174:177], v[200:203], v[78:81]
	v_mfma_f32_16x16x32_bf16 v[18:21], v[166:169], v[208:211], v[18:21]
	v_mfma_f32_16x16x32_bf16 v[10:13], v[174:177], v[208:211], v[10:13]
	v_mfma_f32_16x16x32_bf16 v[6:9], v[166:169], v[216:219], v[6:9]
	v_mfma_f32_16x16x32_bf16 v[2:5], v[174:177], v[216:219], v[2:5]
	s_setprio 0
	s_add_i32 s68, s68, 2
	s_cmpk_gt_u32 s68, 0x53
	s_barrier
	s_cbranch_scc0 .LBB0_369
	s_cmpk_lt_u32 s58, 0x100
	s_cbranch_scc0 .LBB0_372
	s_barrier

.LBB0_421:
	s_add_u32 s26, s8, s12
	s_addc_u32 s27, s9, s13
	s_add_u32 s12, s12, 0x100
	ds_read_b128 v[138:141], v88
	ds_read_b128 v[142:145], v88 offset:1024
	ds_read_b128 v[154:157], v88 offset:2048
	ds_read_b128 v[158:161], v88 offset:3072
	ds_read_b128 v[162:165], v89
	ds_read_b128 v[166:169], v89 offset:1024
	ds_read_b128 v[170:173], v89 offset:2048
	ds_read_b128 v[174:177], v89 offset:3072
	s_addc_u32 s13, s13, 0
	v_cmp_lt_u64_e32 vcc, s[12:13], v[86:87]
	s_and_b64 s[14:15], vcc, exec
	s_cselect_b32 s15, 0, 0xffffd500
	s_cselect_b32 s14, 0, -1
	s_add_u32 s12, s15, s12
	s_addc_u32 s13, s14, s13
	s_cmpk_lg_i32 s68, 0x52
	s_cselect_b32 s14, s12, 0
	s_cselect_b32 s15, s13, 0
	s_add_u32 s16, s8, s14
	s_addc_u32 s17, s9, s15
	s_add_u32 s14, s0, s14
	s_addc_u32 s15, s1, s15
	s_add_u32 s26, s26, 0x158080
	s_addc_u32 s27, s27, 0
	s_mov_b32 m0, s69
	v_lshl_add_u64 v[178:179], s[26:27], 0, v[146:147]
	ds_read_b128 v[188:191], v134
	ds_read_b128 v[192:195], v134 offset:1024
	ds_read_b128 v[196:199], v134 offset:2048
	ds_read_b128 v[200:203], v134 offset:3072
	ds_read_b128 v[204:207], v134 offset:4096
	ds_read_b128 v[208:211], v134 offset:5120
	ds_read_b128 v[212:215], v134 offset:6144
	ds_read_b128 v[216:219], v134 offset:7168
	global_load_lds_dwordx4 v[178:179], off
	v_lshl_add_u64 v[178:179], s[26:27], 0, v[150:151]
	s_mov_b32 m0, s70
	s_nop 0
	global_load_lds_dwordx4 v[178:179], off
	s_waitcnt vmcnt(8)
	s_waitcnt lgkmcnt(0)
	s_barrier
	s_setprio 1
	s_waitcnt lgkmcnt(0)
	v_mfma_f32_16x16x32_bf16 v[30:33], v[138:141], v[188:191], v[30:33]
	v_mfma_f32_16x16x32_bf16 v[58:61], v[154:157], v[188:191], v[58:61]
	v_mfma_f32_16x16x32_bf16 v[110:113], v[138:141], v[196:199], v[110:113]
	v_mfma_f32_16x16x32_bf16 v[130:133], v[154:157], v[196:199], v[130:133]
	v_mfma_f32_16x16x32_bf16 v[74:77], v[138:141], v[204:207], v[74:77]
	v_mfma_f32_16x16x32_bf16 v[66:69], v[154:157], v[204:207], v[66:69]
	v_mfma_f32_16x16x32_bf16 v[126:129], v[138:141], v[212:215], v[126:129]
	v_mfma_f32_16x16x32_bf16 v[50:53], v[154:157], v[212:215], v[50:53]
	v_mfma_f32_16x16x32_bf16 v[30:33], v[142:145], v[192:195], v[30:33]
	v_mfma_f32_16x16x32_bf16 v[58:61], v[158:161], v[192:195], v[58:61]
	v_mfma_f32_16x16x32_bf16 v[110:113], v[142:145], v[200:203], v[110:113]
	v_mfma_f32_16x16x32_bf16 v[130:133], v[158:161], v[200:203], v[130:133]
	v_mfma_f32_16x16x32_bf16 v[74:77], v[142:145], v[208:211], v[74:77]
	v_mfma_f32_16x16x32_bf16 v[66:69], v[158:161], v[208:211], v[66:69]
	v_mfma_f32_16x16x32_bf16 v[126:129], v[142:145], v[216:219], v[126:129]
	v_mfma_f32_16x16x32_bf16 v[50:53], v[158:161], v[216:219], v[50:53]
	s_setprio 0
	s_setprio 1
	v_mfma_f32_16x16x32_bf16 v[82:85], v[162:165], v[188:191], v[82:85]
	v_mfma_f32_16x16x32_bf16 v[62:65], v[170:173], v[188:191], v[62:65]
	v_mfma_f32_16x16x32_bf16 v[38:41], v[162:165], v[196:199], v[38:41]
	v_mfma_f32_16x16x32_bf16 v[26:29], v[170:173], v[196:199], v[26:29]
	v_mfma_f32_16x16x32_bf16 v[46:49], v[162:165], v[204:207], v[46:49]
	v_mfma_f32_16x16x32_bf16 v[34:37], v[170:173], v[204:207], v[34:37]
	v_mfma_f32_16x16x32_bf16 v[42:45], v[162:165], v[212:215], v[42:45]
	v_mfma_f32_16x16x32_bf16 v[70:73], v[170:173], v[212:215], v[70:73]
	v_mfma_f32_16x16x32_bf16 v[82:85], v[166:169], v[192:195], v[82:85]
	v_mfma_f32_16x16x32_bf16 v[62:65], v[174:177], v[192:195], v[62:65]
	v_mfma_f32_16x16x32_bf16 v[38:41], v[166:169], v[200:203], v[38:41]
	v_mfma_f32_16x16x32_bf16 v[26:29], v[174:177], v[200:203], v[26:29]
	v_mfma_f32_16x16x32_bf16 v[46:49], v[166:169], v[208:211], v[46:49]
	v_mfma_f32_16x16x32_bf16 v[34:37], v[174:177], v[208:211], v[34:37]
	v_mfma_f32_16x16x32_bf16 v[42:45], v[166:169], v[216:219], v[42:45]
	v_mfma_f32_16x16x32_bf16 v[70:73], v[174:177], v[216:219], v[70:73]
	s_setprio 0
	s_barrier
	s_mov_b32 m0, s71
	v_lshl_add_u64 v[178:179], s[14:15], 0, v[148:149]
	s_add_u32 s26, s14, 0x158000
	ds_read_b128 v[188:191], v134 offset:16384
	ds_read_b128 v[192:195], v134 offset:17408
	ds_read_b128 v[196:199], v134 offset:18432
	ds_read_b128 v[200:203], v134 offset:19456
	ds_read_b128 v[204:207], v134 offset:20480
	ds_read_b128 v[208:211], v134 offset:21504
	ds_read_b128 v[212:215], v134 offset:22528
	ds_read_b128 v[216:219], v134 offset:23552
	global_load_lds_dwordx4 v[178:179], off
	v_lshl_add_u64 v[184:185], s[14:15], 0, v[152:153]
	s_mov_b32 m0, s77
	s_addc_u32 s27, s15, 0
	global_load_lds_dwordx4 v[184:185], off
	v_lshl_add_u64 v[220:221], s[26:27], 0, v[148:149]
	s_mov_b32 m0, s80
	v_lshl_add_u64 v[222:223], s[16:17], 0, v[150:151]
	global_load_lds_dwordx4 v[220:221], off
	v_lshl_add_u64 v[220:221], s[26:27], 0, v[152:153]
	s_mov_b32 m0, s81
	s_nop 0
	global_load_lds_dwordx4 v[220:221], off
	v_lshl_add_u64 v[220:221], s[16:17], 0, v[146:147]
	s_mov_b32 m0, s61
	s_nop 0
	global_load_lds_dwordx4 v[220:221], off
	s_mov_b32 m0, s62
	s_nop 0
	global_load_lds_dwordx4 v[222:223], off
	s_waitcnt vmcnt(8)
	s_waitcnt lgkmcnt(0)
	s_barrier
	s_setprio 1
	s_waitcnt lgkmcnt(0)
	v_mfma_f32_16x16x32_bf16 v[102:105], v[138:141], v[188:191], v[102:105]
	v_mfma_f32_16x16x32_bf16 v[118:121], v[154:157], v[188:191], v[118:121]
	v_mfma_f32_16x16x32_bf16 v[122:125], v[138:141], v[196:199], v[122:125]
	v_mfma_f32_16x16x32_bf16 v[114:117], v[154:157], v[196:199], v[114:117]
	v_mfma_f32_16x16x32_bf16 v[98:101], v[138:141], v[204:207], v[98:101]
	v_mfma_f32_16x16x32_bf16 v[54:57], v[154:157], v[204:207], v[54:57]
	v_mfma_f32_16x16x32_bf16 v[22:25], v[138:141], v[212:215], v[22:25]
	v_mfma_f32_16x16x32_bf16 v[14:17], v[154:157], v[212:215], v[14:17]
	v_mfma_f32_16x16x32_bf16 v[102:105], v[142:145], v[192:195], v[102:105]
	v_mfma_f32_16x16x32_bf16 v[118:121], v[158:161], v[192:195], v[118:121]
	v_mfma_f32_16x16x32_bf16 v[122:125], v[142:145], v[200:203], v[122:125]
	v_mfma_f32_16x16x32_bf16 v[114:117], v[158:161], v[200:203], v[114:117]
	v_mfma_f32_16x16x32_bf16 v[98:101], v[142:145], v[208:211], v[98:101]
	v_mfma_f32_16x16x32_bf16 v[54:57], v[158:161], v[208:211], v[54:57]
	v_mfma_f32_16x16x32_bf16 v[22:25], v[142:145], v[216:219], v[22:25]
	v_mfma_f32_16x16x32_bf16 v[14:17], v[158:161], v[216:219], v[14:17]
	s_setprio 0
	s_setprio 1
	v_mfma_f32_16x16x32_bf16 v[106:109], v[162:165], v[188:191], v[106:109]
	v_mfma_f32_16x16x32_bf16 v[90:93], v[170:173], v[188:191], v[90:93]
	v_mfma_f32_16x16x32_bf16 v[94:97], v[162:165], v[196:199], v[94:97]
	v_mfma_f32_16x16x32_bf16 v[78:81], v[170:173], v[196:199], v[78:81]
	v_mfma_f32_16x16x32_bf16 v[18:21], v[162:165], v[204:207], v[18:21]
	v_mfma_f32_16x16x32_bf16 v[10:13], v[170:173], v[204:207], v[10:13]
	v_mfma_f32_16x16x32_bf16 v[6:9], v[162:165], v[212:215], v[6:9]
	v_mfma_f32_16x16x32_bf16 v[2:5], v[170:173], v[212:215], v[2:5]
	v_mfma_f32_16x16x32_bf16 v[106:109], v[166:169], v[192:195], v[106:109]
	v_mfma_f32_16x16x32_bf16 v[90:93], v[174:177], v[192:195], v[90:93]
	v_mfma_f32_16x16x32_bf16 v[94:97], v[166:169], v[200:203], v[94:97]
	v_mfma_f32_16x16x32_bf16 v[78:81], v[174:177], v[200:203], v[78:81]
	v_mfma_f32_16x16x32_bf16 v[18:21], v[166:169], v[208:211], v[18:21]
	v_mfma_f32_16x16x32_bf16 v[10:13], v[174:177], v[208:211], v[10:13]
	v_mfma_f32_16x16x32_bf16 v[6:9], v[166:169], v[216:219], v[6:9]
	v_mfma_f32_16x16x32_bf16 v[2:5], v[174:177], v[216:219], v[2:5]
	s_setprio 0
	s_barrier
	ds_read_b128 v[138:141], v135
	ds_read_b128 v[142:145], v135 offset:1024
	ds_read_b128 v[154:157], v135 offset:2048
	ds_read_b128 v[158:161], v135 offset:3072
	ds_read_b128 v[162:165], v136
	ds_read_b128 v[166:169], v136 offset:1024
	ds_read_b128 v[170:173], v136 offset:2048
	ds_read_b128 v[174:177], v136 offset:3072
	s_add_u32 s16, s16, 0x158000
	s_addc_u32 s17, s17, 0
	s_mov_b32 m0, s63
	v_lshl_add_u64 v[224:225], s[16:17], 0, v[146:147]
	ds_read_b128 v[188:191], v134 offset:32768
	ds_read_b128 v[192:195], v134 offset:33792
	ds_read_b128 v[196:199], v134 offset:34816
	ds_read_b128 v[200:203], v134 offset:35840
	ds_read_b128 v[204:207], v134 offset:36864
	ds_read_b128 v[208:211], v134 offset:37888
	ds_read_b128 v[212:215], v134 offset:38912
	ds_read_b128 v[216:219], v134 offset:39936
	global_load_lds_dwordx4 v[224:225], off
	v_lshl_add_u64 v[224:225], s[16:17], 0, v[150:151]
	s_mov_b32 m0, s66
	s_nop 0
	global_load_lds_dwordx4 v[224:225], off
	s_waitcnt vmcnt(8)
	s_waitcnt lgkmcnt(0)
	s_barrier
	s_setprio 1
	s_waitcnt lgkmcnt(0)
	v_mfma_f32_16x16x32_bf16 v[30:33], v[138:141], v[188:191], v[30:33]
	v_mfma_f32_16x16x32_bf16 v[58:61], v[154:157], v[188:191], v[58:61]
	v_mfma_f32_16x16x32_bf16 v[110:113], v[138:141], v[196:199], v[110:113]
	v_mfma_f32_16x16x32_bf16 v[130:133], v[154:157], v[196:199], v[130:133]
	v_mfma_f32_16x16x32_bf16 v[74:77], v[138:141], v[204:207], v[74:77]
	v_mfma_f32_16x16x32_bf16 v[66:69], v[154:157], v[204:207], v[66:69]
	v_mfma_f32_16x16x32_bf16 v[126:129], v[138:141], v[212:215], v[126:129]
	v_mfma_f32_16x16x32_bf16 v[50:53], v[154:157], v[212:215], v[50:53]
	v_mfma_f32_16x16x32_bf16 v[30:33], v[142:145], v[192:195], v[30:33]
	v_mfma_f32_16x16x32_bf16 v[58:61], v[158:161], v[192:195], v[58:61]
	v_mfma_f32_16x16x32_bf16 v[110:113], v[142:145], v[200:203], v[110:113]
	v_mfma_f32_16x16x32_bf16 v[130:133], v[158:161], v[200:203], v[130:133]
	v_mfma_f32_16x16x32_bf16 v[74:77], v[142:145], v[208:211], v[74:77]
	v_mfma_f32_16x16x32_bf16 v[66:69], v[158:161], v[208:211], v[66:69]
	v_mfma_f32_16x16x32_bf16 v[126:129], v[142:145], v[216:219], v[126:129]
	v_mfma_f32_16x16x32_bf16 v[50:53], v[158:161], v[216:219], v[50:53]
	s_setprio 0
	s_setprio 1
	v_mfma_f32_16x16x32_bf16 v[82:85], v[162:165], v[188:191], v[82:85]
	v_mfma_f32_16x16x32_bf16 v[62:65], v[170:173], v[188:191], v[62:65]
	v_mfma_f32_16x16x32_bf16 v[38:41], v[162:165], v[196:199], v[38:41]
	v_mfma_f32_16x16x32_bf16 v[26:29], v[170:173], v[196:199], v[26:29]
	v_mfma_f32_16x16x32_bf16 v[46:49], v[162:165], v[204:207], v[46:49]
	v_mfma_f32_16x16x32_bf16 v[34:37], v[170:173], v[204:207], v[34:37]
	v_mfma_f32_16x16x32_bf16 v[42:45], v[162:165], v[212:215], v[42:45]
	v_mfma_f32_16x16x32_bf16 v[70:73], v[170:173], v[212:215], v[70:73]
	v_mfma_f32_16x16x32_bf16 v[82:85], v[166:169], v[192:195], v[82:85]
	v_mfma_f32_16x16x32_bf16 v[62:65], v[174:177], v[192:195], v[62:65]
	v_mfma_f32_16x16x32_bf16 v[38:41], v[166:169], v[200:203], v[38:41]
	v_mfma_f32_16x16x32_bf16 v[26:29], v[174:177], v[200:203], v[26:29]
	v_mfma_f32_16x16x32_bf16 v[46:49], v[166:169], v[208:211], v[46:49]
	v_mfma_f32_16x16x32_bf16 v[34:37], v[174:177], v[208:211], v[34:37]
	v_mfma_f32_16x16x32_bf16 v[42:45], v[166:169], v[216:219], v[42:45]
	v_mfma_f32_16x16x32_bf16 v[70:73], v[174:177], v[216:219], v[70:73]
	s_setprio 0
	s_barrier
	s_mov_b32 m0, s85
	v_lshl_add_u64 v[178:179], v[178:179], 0, s[10:11]
	s_add_u32 s14, s14, 0x158080
	ds_read_b128 v[188:191], v134 offset:49152
	ds_read_b128 v[192:195], v134 offset:50176
	ds_read_b128 v[196:199], v134 offset:51200
	ds_read_b128 v[200:203], v134 offset:52224
	ds_read_b128 v[204:207], v134 offset:53248
	ds_read_b128 v[208:211], v134 offset:54272
	ds_read_b128 v[212:215], v134 offset:55296
	ds_read_b128 v[216:219], v134 offset:56320
	global_load_lds_dwordx4 v[178:179], off
	v_lshl_add_u64 v[178:179], v[184:185], 0, s[10:11]
	s_mov_b32 m0, s88
	s_addc_u32 s15, s15, 0
	global_load_lds_dwordx4 v[178:179], off
	v_lshl_add_u64 v[178:179], s[14:15], 0, v[148:149]
	s_mov_b32 m0, s89
	s_nop 0
	global_load_lds_dwordx4 v[178:179], off
	v_lshl_add_u64 v[178:179], s[14:15], 0, v[152:153]
	s_mov_b32 m0, s90
	s_nop 0
	global_load_lds_dwordx4 v[178:179], off
	v_lshl_add_u64 v[178:179], v[220:221], 0, s[10:11]
	s_mov_b32 m0, s34
	s_nop 0
	global_load_lds_dwordx4 v[178:179], off
	v_lshl_add_u64 v[178:179], v[222:223], 0, s[10:11]
	s_mov_b32 m0, s35
	s_nop 0
	global_load_lds_dwordx4 v[178:179], off
	s_waitcnt vmcnt(8)
	s_waitcnt lgkmcnt(0)
	s_barrier
	s_setprio 1
	s_waitcnt lgkmcnt(0)
	v_mfma_f32_16x16x32_bf16 v[102:105], v[138:141], v[188:191], v[102:105]
	v_mfma_f32_16x16x32_bf16 v[118:121], v[154:157], v[188:191], v[118:121]
	v_mfma_f32_16x16x32_bf16 v[122:125], v[138:141], v[196:199], v[122:125]
	v_mfma_f32_16x16x32_bf16 v[114:117], v[154:157], v[196:199], v[114:117]
	v_mfma_f32_16x16x32_bf16 v[98:101], v[138:141], v[204:207], v[98:101]
	v_mfma_f32_16x16x32_bf16 v[54:57], v[154:157], v[204:207], v[54:57]
	v_mfma_f32_16x16x32_bf16 v[22:25], v[138:141], v[212:215], v[22:25]
	v_mfma_f32_16x16x32_bf16 v[14:17], v[154:157], v[212:215], v[14:17]
	v_mfma_f32_16x16x32_bf16 v[102:105], v[142:145], v[192:195], v[102:105]
	v_mfma_f32_16x16x32_bf16 v[118:121], v[158:161], v[192:195], v[118:121]
	v_mfma_f32_16x16x32_bf16 v[122:125], v[142:145], v[200:203], v[122:125]
	v_mfma_f32_16x16x32_bf16 v[114:117], v[158:161], v[200:203], v[114:117]
	v_mfma_f32_16x16x32_bf16 v[98:101], v[142:145], v[208:211], v[98:101]
	v_mfma_f32_16x16x32_bf16 v[54:57], v[158:161], v[208:211], v[54:57]
	v_mfma_f32_16x16x32_bf16 v[22:25], v[142:145], v[216:219], v[22:25]
	v_mfma_f32_16x16x32_bf16 v[14:17], v[158:161], v[216:219], v[14:17]
	s_setprio 0
	s_setprio 1
	v_mfma_f32_16x16x32_bf16 v[106:109], v[162:165], v[188:191], v[106:109]
	v_mfma_f32_16x16x32_bf16 v[90:93], v[170:173], v[188:191], v[90:93]
	v_mfma_f32_16x16x32_bf16 v[94:97], v[162:165], v[196:199], v[94:97]
	v_mfma_f32_16x16x32_bf16 v[78:81], v[170:173], v[196:199], v[78:81]
	v_mfma_f32_16x16x32_bf16 v[18:21], v[162:165], v[204:207], v[18:21]
	v_mfma_f32_16x16x32_bf16 v[10:13], v[170:173], v[204:207], v[10:13]
	v_mfma_f32_16x16x32_bf16 v[6:9], v[162:165], v[212:215], v[6:9]
	v_mfma_f32_16x16x32_bf16 v[2:5], v[170:173], v[212:215], v[2:5]
	v_mfma_f32_16x16x32_bf16 v[106:109], v[166:169], v[192:195], v[106:109]
	v_mfma_f32_16x16x32_bf16 v[90:93], v[174:177], v[192:195], v[90:93]
	v_mfma_f32_16x16x32_bf16 v[94:97], v[166:169], v[200:203], v[94:97]
	v_mfma_f32_16x16x32_bf16 v[78:81], v[174:177], v[200:203], v[78:81]
	v_mfma_f32_16x16x32_bf16 v[18:21], v[166:169], v[208:211], v[18:21]
	v_mfma_f32_16x16x32_bf16 v[10:13], v[174:177], v[208:211], v[10:13]
	v_mfma_f32_16x16x32_bf16 v[6:9], v[166:169], v[216:219], v[6:9]
	v_mfma_f32_16x16x32_bf16 v[2:5], v[174:177], v[216:219], v[2:5]
	s_setprio 0
	s_add_i32 s68, s68, 2
	s_cmpk_gt_u32 s68, 0x53
	s_barrier
	s_cbranch_scc0 .LBB0_421
	s_cmpk_lt_u32 s58, 0x100
	s_cbranch_scc0 .LBB0_424
	s_barrier

.LBB0_471:
	s_add_u32 s26, s4, s10
	s_addc_u32 s27, s5, s11
	s_add_u32 s10, s10, 0x100
	ds_read_b128 v[138:141], v133
	ds_read_b128 v[142:145], v133 offset:1024
	ds_read_b128 v[154:157], v133 offset:2048
	ds_read_b128 v[158:161], v133 offset:3072
	ds_read_b128 v[162:165], v134
	ds_read_b128 v[166:169], v134 offset:1024
	ds_read_b128 v[170:173], v134 offset:2048
	ds_read_b128 v[174:177], v134 offset:3072
	s_addc_u32 s11, s11, 0
	v_cmp_ge_u64_e32 vcc, s[10:11], v[130:131]
	s_and_b64 s[12:13], vcc, exec
	s_cselect_b32 s13, s6, 0
	s_cselect_b32 s12, 0, 0
	s_sub_u32 s10, s10, s13
	s_subb_u32 s11, s11, s12
	s_cmp_lg_u32 s40, s7
	s_cselect_b32 s12, s10, 0
	s_cselect_b32 s13, s11, 0
	s_add_u32 s14, s4, s12
	s_addc_u32 s15, s5, s13
	s_add_u32 s12, s2, s12
	s_addc_u32 s13, s3, s13
	s_add_u32 s26, s26, 0x158080
	s_addc_u32 s27, s27, 0
	s_mov_b32 m0, s41
	v_lshl_add_u64 v[210:211], s[26:27], 0, v[146:147]
	ds_read_b128 v[178:181], v135
	ds_read_b128 v[182:185], v135 offset:1024
	ds_read_b128 v[186:189], v135 offset:2048
	ds_read_b128 v[190:193], v135 offset:3072
	ds_read_b128 v[194:197], v135 offset:4096
	ds_read_b128 v[198:201], v135 offset:5120
	ds_read_b128 v[202:205], v135 offset:6144
	ds_read_b128 v[206:209], v135 offset:7168
	global_load_lds_dwordx4 v[210:211], off
	v_lshl_add_u64 v[210:211], s[26:27], 0, v[150:151]
	s_mov_b32 m0, s52
	s_nop 0
	global_load_lds_dwordx4 v[210:211], off
	s_waitcnt vmcnt(8)
	s_waitcnt lgkmcnt(0)
	s_barrier
	s_setprio 1
	s_waitcnt lgkmcnt(0)
	v_mfma_f32_16x16x32_bf16 v[126:129], v[138:141], v[178:181], v[126:129]
	v_mfma_f32_16x16x32_bf16 v[122:125], v[154:157], v[178:181], v[122:125]
	v_mfma_f32_16x16x32_bf16 v[118:121], v[138:141], v[186:189], v[118:121]
	v_mfma_f32_16x16x32_bf16 v[114:117], v[154:157], v[186:189], v[114:117]
	v_mfma_f32_16x16x32_bf16 v[102:105], v[138:141], v[194:197], v[102:105]
	v_mfma_f32_16x16x32_bf16 v[98:101], v[154:157], v[194:197], v[98:101]
	v_mfma_f32_16x16x32_bf16 v[86:89], v[138:141], v[202:205], v[86:89]
	v_mfma_f32_16x16x32_bf16 v[82:85], v[154:157], v[202:205], v[82:85]
	v_mfma_f32_16x16x32_bf16 v[126:129], v[142:145], v[182:185], v[126:129]
	v_mfma_f32_16x16x32_bf16 v[122:125], v[158:161], v[182:185], v[122:125]
	v_mfma_f32_16x16x32_bf16 v[118:121], v[142:145], v[190:193], v[118:121]
	v_mfma_f32_16x16x32_bf16 v[114:117], v[158:161], v[190:193], v[114:117]
	v_mfma_f32_16x16x32_bf16 v[102:105], v[142:145], v[198:201], v[102:105]
	v_mfma_f32_16x16x32_bf16 v[98:101], v[158:161], v[198:201], v[98:101]
	v_mfma_f32_16x16x32_bf16 v[86:89], v[142:145], v[206:209], v[86:89]
	v_mfma_f32_16x16x32_bf16 v[82:85], v[158:161], v[206:209], v[82:85]
	s_setprio 0
	s_setprio 1
	v_mfma_f32_16x16x32_bf16 v[110:113], v[162:165], v[178:181], v[110:113]
	v_mfma_f32_16x16x32_bf16 v[106:109], v[170:173], v[178:181], v[106:109]
	v_mfma_f32_16x16x32_bf16 v[94:97], v[162:165], v[186:189], v[94:97]
	v_mfma_f32_16x16x32_bf16 v[90:93], v[170:173], v[186:189], v[90:93]
	v_mfma_f32_16x16x32_bf16 v[78:81], v[162:165], v[194:197], v[78:81]
	v_mfma_f32_16x16x32_bf16 v[74:77], v[170:173], v[194:197], v[74:77]
	v_mfma_f32_16x16x32_bf16 v[70:73], v[162:165], v[202:205], v[70:73]
	v_mfma_f32_16x16x32_bf16 v[66:69], v[170:173], v[202:205], v[66:69]
	v_mfma_f32_16x16x32_bf16 v[110:113], v[166:169], v[182:185], v[110:113]
	v_mfma_f32_16x16x32_bf16 v[106:109], v[174:177], v[182:185], v[106:109]
	v_mfma_f32_16x16x32_bf16 v[94:97], v[166:169], v[190:193], v[94:97]
	v_mfma_f32_16x16x32_bf16 v[90:93], v[174:177], v[190:193], v[90:93]
	v_mfma_f32_16x16x32_bf16 v[78:81], v[166:169], v[198:201], v[78:81]
	v_mfma_f32_16x16x32_bf16 v[74:77], v[174:177], v[198:201], v[74:77]
	v_mfma_f32_16x16x32_bf16 v[70:73], v[166:169], v[206:209], v[70:73]
	v_mfma_f32_16x16x32_bf16 v[66:69], v[174:177], v[206:209], v[66:69]
	s_setprio 0
	s_barrier
	s_mov_b32 m0, s53
	v_lshl_add_u64 v[210:211], s[12:13], 0, v[148:149]
	s_add_u32 s26, s12, 0x158000
	ds_read_b128 v[178:181], v135 offset:16384
	ds_read_b128 v[182:185], v135 offset:17408
	ds_read_b128 v[186:189], v135 offset:18432
	ds_read_b128 v[190:193], v135 offset:19456
	ds_read_b128 v[194:197], v135 offset:20480
	ds_read_b128 v[198:201], v135 offset:21504
	ds_read_b128 v[202:205], v135 offset:22528
	ds_read_b128 v[206:209], v135 offset:23552
	global_load_lds_dwordx4 v[210:211], off
	v_lshl_add_u64 v[212:213], s[12:13], 0, v[152:153]
	s_mov_b32 m0, s54
	s_addc_u32 s27, s13, 0
	global_load_lds_dwordx4 v[212:213], off
	v_lshl_add_u64 v[214:215], s[26:27], 0, v[148:149]
	s_mov_b32 m0, s55
	v_lshl_add_u64 v[216:217], s[14:15], 0, v[150:151]
	global_load_lds_dwordx4 v[214:215], off
	v_lshl_add_u64 v[214:215], s[26:27], 0, v[152:153]
	s_mov_b32 m0, s58
	s_nop 0
	global_load_lds_dwordx4 v[214:215], off
	v_lshl_add_u64 v[214:215], s[14:15], 0, v[146:147]
	s_mov_b32 m0, s18
	s_nop 0
	global_load_lds_dwordx4 v[214:215], off
	s_mov_b32 m0, s19
	s_nop 0
	global_load_lds_dwordx4 v[216:217], off
	s_waitcnt vmcnt(8)
	s_waitcnt lgkmcnt(0)
	s_barrier
	s_setprio 1
	s_waitcnt lgkmcnt(0)
	v_mfma_f32_16x16x32_bf16 v[62:65], v[138:141], v[178:181], v[62:65]
	v_mfma_f32_16x16x32_bf16 v[58:61], v[154:157], v[178:181], v[58:61]
	v_mfma_f32_16x16x32_bf16 v[54:57], v[138:141], v[186:189], v[54:57]
	v_mfma_f32_16x16x32_bf16 v[50:53], v[154:157], v[186:189], v[50:53]
	v_mfma_f32_16x16x32_bf16 v[38:41], v[138:141], v[194:197], v[38:41]
	v_mfma_f32_16x16x32_bf16 v[34:37], v[154:157], v[194:197], v[34:37]
	v_mfma_f32_16x16x32_bf16 v[22:25], v[138:141], v[202:205], v[22:25]
	v_mfma_f32_16x16x32_bf16 v[18:21], v[154:157], v[202:205], v[18:21]
	v_mfma_f32_16x16x32_bf16 v[62:65], v[142:145], v[182:185], v[62:65]
	v_mfma_f32_16x16x32_bf16 v[58:61], v[158:161], v[182:185], v[58:61]
	v_mfma_f32_16x16x32_bf16 v[54:57], v[142:145], v[190:193], v[54:57]
	v_mfma_f32_16x16x32_bf16 v[50:53], v[158:161], v[190:193], v[50:53]
	v_mfma_f32_16x16x32_bf16 v[38:41], v[142:145], v[198:201], v[38:41]
	v_mfma_f32_16x16x32_bf16 v[34:37], v[158:161], v[198:201], v[34:37]
	v_mfma_f32_16x16x32_bf16 v[22:25], v[142:145], v[206:209], v[22:25]
	v_mfma_f32_16x16x32_bf16 v[18:21], v[158:161], v[206:209], v[18:21]
	s_setprio 0
	s_setprio 1
	v_mfma_f32_16x16x32_bf16 v[46:49], v[162:165], v[178:181], v[46:49]
	v_mfma_f32_16x16x32_bf16 v[42:45], v[170:173], v[178:181], v[42:45]
	v_mfma_f32_16x16x32_bf16 v[30:33], v[162:165], v[186:189], v[30:33]
	v_mfma_f32_16x16x32_bf16 v[26:29], v[170:173], v[186:189], v[26:29]
	v_mfma_f32_16x16x32_bf16 v[14:17], v[162:165], v[194:197], v[14:17]
	v_mfma_f32_16x16x32_bf16 v[10:13], v[170:173], v[194:197], v[10:13]
	v_mfma_f32_16x16x32_bf16 v[6:9], v[162:165], v[202:205], v[6:9]
	v_mfma_f32_16x16x32_bf16 v[2:5], v[170:173], v[202:205], v[2:5]
	v_mfma_f32_16x16x32_bf16 v[46:49], v[166:169], v[182:185], v[46:49]
	v_mfma_f32_16x16x32_bf16 v[42:45], v[174:177], v[182:185], v[42:45]
	v_mfma_f32_16x16x32_bf16 v[30:33], v[166:169], v[190:193], v[30:33]
	v_mfma_f32_16x16x32_bf16 v[26:29], v[174:177], v[190:193], v[26:29]
	v_mfma_f32_16x16x32_bf16 v[14:17], v[166:169], v[198:201], v[14:17]
	v_mfma_f32_16x16x32_bf16 v[10:13], v[174:177], v[198:201], v[10:13]
	v_mfma_f32_16x16x32_bf16 v[6:9], v[166:169], v[206:209], v[6:9]
	v_mfma_f32_16x16x32_bf16 v[2:5], v[174:177], v[206:209], v[2:5]
	s_setprio 0
	s_barrier
	ds_read_b128 v[138:141], v136
	ds_read_b128 v[142:145], v136 offset:1024
	ds_read_b128 v[154:157], v136 offset:2048
	ds_read_b128 v[158:161], v136 offset:3072
	ds_read_b128 v[162:165], v137
	ds_read_b128 v[166:169], v137 offset:1024
	ds_read_b128 v[170:173], v137 offset:2048
	ds_read_b128 v[174:177], v137 offset:3072
	s_add_u32 s14, s14, 0x158000
	s_addc_u32 s15, s15, 0
	s_mov_b32 m0, s21
	v_lshl_add_u64 v[218:219], s[14:15], 0, v[146:147]
	ds_read_b128 v[178:181], v135 offset:32768
	ds_read_b128 v[182:185], v135 offset:33792
	ds_read_b128 v[186:189], v135 offset:34816
	ds_read_b128 v[190:193], v135 offset:35840
	ds_read_b128 v[194:197], v135 offset:36864
	ds_read_b128 v[198:201], v135 offset:37888
	ds_read_b128 v[202:205], v135 offset:38912
	ds_read_b128 v[206:209], v135 offset:39936
	global_load_lds_dwordx4 v[218:219], off
	v_lshl_add_u64 v[218:219], s[14:15], 0, v[150:151]
	s_mov_b32 m0, s22
	s_nop 0
	global_load_lds_dwordx4 v[218:219], off
	s_waitcnt vmcnt(8)
	s_waitcnt lgkmcnt(0)
	s_barrier
	s_setprio 1
	s_waitcnt lgkmcnt(0)
	v_mfma_f32_16x16x32_bf16 v[126:129], v[138:141], v[178:181], v[126:129]
	v_mfma_f32_16x16x32_bf16 v[122:125], v[154:157], v[178:181], v[122:125]
	v_mfma_f32_16x16x32_bf16 v[118:121], v[138:141], v[186:189], v[118:121]
	v_mfma_f32_16x16x32_bf16 v[114:117], v[154:157], v[186:189], v[114:117]
	v_mfma_f32_16x16x32_bf16 v[102:105], v[138:141], v[194:197], v[102:105]
	v_mfma_f32_16x16x32_bf16 v[98:101], v[154:157], v[194:197], v[98:101]
	v_mfma_f32_16x16x32_bf16 v[86:89], v[138:141], v[202:205], v[86:89]
	v_mfma_f32_16x16x32_bf16 v[82:85], v[154:157], v[202:205], v[82:85]
	v_mfma_f32_16x16x32_bf16 v[126:129], v[142:145], v[182:185], v[126:129]
	v_mfma_f32_16x16x32_bf16 v[122:125], v[158:161], v[182:185], v[122:125]
	v_mfma_f32_16x16x32_bf16 v[118:121], v[142:145], v[190:193], v[118:121]
	v_mfma_f32_16x16x32_bf16 v[114:117], v[158:161], v[190:193], v[114:117]
	v_mfma_f32_16x16x32_bf16 v[102:105], v[142:145], v[198:201], v[102:105]
	v_mfma_f32_16x16x32_bf16 v[98:101], v[158:161], v[198:201], v[98:101]
	v_mfma_f32_16x16x32_bf16 v[86:89], v[142:145], v[206:209], v[86:89]
	v_mfma_f32_16x16x32_bf16 v[82:85], v[158:161], v[206:209], v[82:85]
	s_setprio 0
	s_setprio 1
	v_mfma_f32_16x16x32_bf16 v[110:113], v[162:165], v[178:181], v[110:113]
	v_mfma_f32_16x16x32_bf16 v[106:109], v[170:173], v[178:181], v[106:109]
	v_mfma_f32_16x16x32_bf16 v[94:97], v[162:165], v[186:189], v[94:97]
	v_mfma_f32_16x16x32_bf16 v[90:93], v[170:173], v[186:189], v[90:93]
	v_mfma_f32_16x16x32_bf16 v[78:81], v[162:165], v[194:197], v[78:81]
	v_mfma_f32_16x16x32_bf16 v[74:77], v[170:173], v[194:197], v[74:77]
	v_mfma_f32_16x16x32_bf16 v[70:73], v[162:165], v[202:205], v[70:73]
	v_mfma_f32_16x16x32_bf16 v[66:69], v[170:173], v[202:205], v[66:69]
	v_mfma_f32_16x16x32_bf16 v[110:113], v[166:169], v[182:185], v[110:113]
	v_mfma_f32_16x16x32_bf16 v[106:109], v[174:177], v[182:185], v[106:109]
	v_mfma_f32_16x16x32_bf16 v[94:97], v[166:169], v[190:193], v[94:97]
	v_mfma_f32_16x16x32_bf16 v[90:93], v[174:177], v[190:193], v[90:93]
	v_mfma_f32_16x16x32_bf16 v[78:81], v[166:169], v[198:201], v[78:81]
	v_mfma_f32_16x16x32_bf16 v[74:77], v[174:177], v[198:201], v[74:77]
	v_mfma_f32_16x16x32_bf16 v[70:73], v[166:169], v[206:209], v[70:73]
	v_mfma_f32_16x16x32_bf16 v[66:69], v[174:177], v[206:209], v[66:69]
	s_setprio 0
	s_barrier
	s_mov_b32 m0, s59
	v_lshl_add_u64 v[210:211], v[210:211], 0, s[8:9]
	s_add_u32 s12, s12, 0x158080
	ds_read_b128 v[178:181], v135 offset:49152
	ds_read_b128 v[182:185], v135 offset:50176
	ds_read_b128 v[186:189], v135 offset:51200
	ds_read_b128 v[190:193], v135 offset:52224
	ds_read_b128 v[194:197], v135 offset:53248
	ds_read_b128 v[198:201], v135 offset:54272
	ds_read_b128 v[202:205], v135 offset:55296
	ds_read_b128 v[206:209], v135 offset:56320
	global_load_lds_dwordx4 v[210:211], off
	v_lshl_add_u64 v[210:211], v[212:213], 0, s[8:9]
	s_mov_b32 m0, s60
	s_addc_u32 s13, s13, 0
	global_load_lds_dwordx4 v[210:211], off
	v_lshl_add_u64 v[210:211], s[12:13], 0, v[148:149]
	s_mov_b32 m0, s61
	s_nop 0
	global_load_lds_dwordx4 v[210:211], off
	v_lshl_add_u64 v[210:211], s[12:13], 0, v[152:153]
	s_mov_b32 m0, s62
	s_nop 0
	global_load_lds_dwordx4 v[210:211], off
	v_lshl_add_u64 v[210:211], v[214:215], 0, s[8:9]
	s_mov_b32 m0, s34
	s_nop 0
	global_load_lds_dwordx4 v[210:211], off
	v_lshl_add_u64 v[210:211], v[216:217], 0, s[8:9]
	s_mov_b32 m0, s35
	s_nop 0
	global_load_lds_dwordx4 v[210:211], off
	s_waitcnt vmcnt(8)
	s_waitcnt lgkmcnt(0)
	s_barrier
	s_setprio 1
	s_waitcnt lgkmcnt(0)
	v_mfma_f32_16x16x32_bf16 v[62:65], v[138:141], v[178:181], v[62:65]
	v_mfma_f32_16x16x32_bf16 v[58:61], v[154:157], v[178:181], v[58:61]
	v_mfma_f32_16x16x32_bf16 v[54:57], v[138:141], v[186:189], v[54:57]
	v_mfma_f32_16x16x32_bf16 v[50:53], v[154:157], v[186:189], v[50:53]
	v_mfma_f32_16x16x32_bf16 v[38:41], v[138:141], v[194:197], v[38:41]
	v_mfma_f32_16x16x32_bf16 v[34:37], v[154:157], v[194:197], v[34:37]
	v_mfma_f32_16x16x32_bf16 v[22:25], v[138:141], v[202:205], v[22:25]
	v_mfma_f32_16x16x32_bf16 v[18:21], v[154:157], v[202:205], v[18:21]
	v_mfma_f32_16x16x32_bf16 v[62:65], v[142:145], v[182:185], v[62:65]
	v_mfma_f32_16x16x32_bf16 v[58:61], v[158:161], v[182:185], v[58:61]
	v_mfma_f32_16x16x32_bf16 v[54:57], v[142:145], v[190:193], v[54:57]
	v_mfma_f32_16x16x32_bf16 v[50:53], v[158:161], v[190:193], v[50:53]
	v_mfma_f32_16x16x32_bf16 v[38:41], v[142:145], v[198:201], v[38:41]
	v_mfma_f32_16x16x32_bf16 v[34:37], v[158:161], v[198:201], v[34:37]
	v_mfma_f32_16x16x32_bf16 v[22:25], v[142:145], v[206:209], v[22:25]
	v_mfma_f32_16x16x32_bf16 v[18:21], v[158:161], v[206:209], v[18:21]
	s_setprio 0
	s_setprio 1
	v_mfma_f32_16x16x32_bf16 v[46:49], v[162:165], v[178:181], v[46:49]
	v_mfma_f32_16x16x32_bf16 v[42:45], v[170:173], v[178:181], v[42:45]
	v_mfma_f32_16x16x32_bf16 v[30:33], v[162:165], v[186:189], v[30:33]
	v_mfma_f32_16x16x32_bf16 v[26:29], v[170:173], v[186:189], v[26:29]
	v_mfma_f32_16x16x32_bf16 v[14:17], v[162:165], v[194:197], v[14:17]
	v_mfma_f32_16x16x32_bf16 v[10:13], v[170:173], v[194:197], v[10:13]
	v_mfma_f32_16x16x32_bf16 v[6:9], v[162:165], v[202:205], v[6:9]
	v_mfma_f32_16x16x32_bf16 v[2:5], v[170:173], v[202:205], v[2:5]
	v_mfma_f32_16x16x32_bf16 v[46:49], v[166:169], v[182:185], v[46:49]
	v_mfma_f32_16x16x32_bf16 v[42:45], v[174:177], v[182:185], v[42:45]
	v_mfma_f32_16x16x32_bf16 v[30:33], v[166:169], v[190:193], v[30:33]
	v_mfma_f32_16x16x32_bf16 v[26:29], v[174:177], v[190:193], v[26:29]
	v_mfma_f32_16x16x32_bf16 v[14:17], v[166:169], v[198:201], v[14:17]
	v_mfma_f32_16x16x32_bf16 v[10:13], v[174:177], v[198:201], v[10:13]
	v_mfma_f32_16x16x32_bf16 v[6:9], v[166:169], v[206:209], v[6:9]
	v_mfma_f32_16x16x32_bf16 v[2:5], v[174:177], v[206:209], v[2:5]
	s_setprio 0
	s_add_i32 s7, s7, 2
	s_cmp_ge_u32 s7, s1
	s_barrier
	s_cbranch_scc0 .LBB0_471
	s_cmpk_lt_u32 s20, 0x100
	s_cbranch_scc0 .LBB0_474
	s_barrier

.LBB0_618:
	s_add_u32 s26, s54, 0x100
	s_addc_u32 s27, s55, 0
	ds_read_b128 v[90:93], v234
	ds_read_b128 v[94:97], v234 offset:1024
	ds_read_b128 v[106:109], v234 offset:2048
	ds_read_b128 v[110:113], v234 offset:3072
	ds_read_b128 v[122:125], v235
	ds_read_b128 v[126:129], v235 offset:1024
	ds_read_b128 v[138:141], v235 offset:2048
	ds_read_b128 v[142:145], v235 offset:3072
	s_add_u32 s35, s54, 0xfffff100
	v_cmp_gt_u64_e32 vcc, s[26:27], v[216:217]
	s_addc_u32 s58, s55, -1
	s_and_b64 s[56:57], vcc, exec
	s_cselect_b32 s56, s35, s26
	s_cselect_b32 s57, s58, s27
	s_add_u32 s26, s52, s56
	s_addc_u32 s27, s53, s57
	s_add_u32 s35, s4, s56
	s_addc_u32 s58, s5, s57
	s_cmp_eq_u32 s34, 28
	s_cselect_b32 s61, s3, s27
	s_cselect_b32 s60, s7, s26
	s_cselect_b32 s59, s19, s58
	s_cselect_b32 s58, s21, s35
	s_add_u32 s26, s52, s54
	s_addc_u32 s27, s53, s55
	s_add_u32 s26, s26, 0x80080
	s_addc_u32 s27, s27, 0
	v_lshl_add_u64 v[218:219], s[26:27], 0, v[194:195]
	s_add_i32 m0, s67, 0xc000
	ds_read_b128 v[154:157], v236
	ds_read_b128 v[158:161], v236 offset:1024
	ds_read_b128 v[170:173], v236 offset:2048
	ds_read_b128 v[174:177], v236 offset:3072
	ds_read_b128 v[178:181], v236 offset:4096
	ds_read_b128 v[182:185], v236 offset:5120
	ds_read_b128 v[186:189], v236 offset:6144
	ds_read_b128 v[190:193], v236 offset:7168
	global_load_lds_dwordx4 v[218:219], off
	v_lshl_add_u64 v[218:219], s[26:27], 0, v[198:199]
	s_add_i32 m0, s67, 0xe000
	s_nop 0
	global_load_lds_dwordx4 v[218:219], off
	s_waitcnt vmcnt(8)
	s_waitcnt lgkmcnt(0)
	s_barrier
	s_setprio 1
	s_waitcnt lgkmcnt(0)
	v_mfma_f32_16x16x32_bf16 v[62:65], v[90:93], v[154:157], v[62:65]
	v_mfma_f32_16x16x32_bf16 v[58:61], v[106:109], v[154:157], v[58:61]
	v_mfma_f32_16x16x32_bf16 v[54:57], v[90:93], v[170:173], v[54:57]
	v_mfma_f32_16x16x32_bf16 v[50:53], v[106:109], v[170:173], v[50:53]
	v_mfma_f32_16x16x32_bf16 v[46:49], v[90:93], v[178:181], v[46:49]
	v_mfma_f32_16x16x32_bf16 v[42:45], v[106:109], v[178:181], v[42:45]
	v_mfma_f32_16x16x32_bf16 v[38:41], v[90:93], v[186:189], v[38:41]
	v_mfma_f32_16x16x32_bf16 v[34:37], v[106:109], v[186:189], v[34:37]
	v_mfma_f32_16x16x32_bf16 v[62:65], v[94:97], v[158:161], v[62:65]
	v_mfma_f32_16x16x32_bf16 v[58:61], v[110:113], v[158:161], v[58:61]
	v_mfma_f32_16x16x32_bf16 v[54:57], v[94:97], v[174:177], v[54:57]
	v_mfma_f32_16x16x32_bf16 v[50:53], v[110:113], v[174:177], v[50:53]
	v_mfma_f32_16x16x32_bf16 v[46:49], v[94:97], v[182:185], v[46:49]
	v_mfma_f32_16x16x32_bf16 v[42:45], v[110:113], v[182:185], v[42:45]
	v_mfma_f32_16x16x32_bf16 v[38:41], v[94:97], v[190:193], v[38:41]
	v_mfma_f32_16x16x32_bf16 v[34:37], v[110:113], v[190:193], v[34:37]
	s_setprio 0
	s_setprio 1
	v_mfma_f32_16x16x32_bf16 v[166:169], v[122:125], v[154:157], v[166:169]
	v_mfma_f32_16x16x32_bf16 v[150:153], v[122:125], v[170:173], v[150:153]
	v_mfma_f32_16x16x32_bf16 v[146:149], v[138:141], v[170:173], v[146:149]
	v_mfma_f32_16x16x32_bf16 v[134:137], v[122:125], v[178:181], v[134:137]
	v_mfma_f32_16x16x32_bf16 v[130:133], v[138:141], v[178:181], v[130:133]
	v_mfma_f32_16x16x32_bf16 v[118:121], v[122:125], v[186:189], v[118:121]
	v_mfma_f32_16x16x32_bf16 v[114:117], v[138:141], v[186:189], v[114:117]
	v_mfma_f32_16x16x32_bf16 v[166:169], v[126:129], v[158:161], v[166:169]
	v_mfma_f32_16x16x32_bf16 v[154:157], v[138:141], v[154:157], v[162:165]
	v_mfma_f32_16x16x32_bf16 v[150:153], v[126:129], v[174:177], v[150:153]
	v_mfma_f32_16x16x32_bf16 v[146:149], v[142:145], v[174:177], v[146:149]
	v_mfma_f32_16x16x32_bf16 v[134:137], v[126:129], v[182:185], v[134:137]
	v_mfma_f32_16x16x32_bf16 v[130:133], v[142:145], v[182:185], v[130:133]
	v_mfma_f32_16x16x32_bf16 v[118:121], v[126:129], v[190:193], v[118:121]
	v_mfma_f32_16x16x32_bf16 v[114:117], v[142:145], v[190:193], v[114:117]
	v_mfma_f32_16x16x32_bf16 v[154:157], v[142:145], v[158:161], v[154:157]
	s_setprio 0
	s_barrier
	s_add_i32 s26, s8, s66
	v_lshl_add_u64 v[218:219], s[58:59], 0, v[196:197]
	s_mov_b32 m0, s26
	ds_read_b128 v[158:161], v236 offset:16384
	ds_read_b128 v[162:165], v236 offset:17408
	ds_read_b128 v[170:173], v236 offset:18432
	ds_read_b128 v[174:177], v236 offset:19456
	ds_read_b128 v[178:181], v236 offset:20480
	ds_read_b128 v[182:185], v236 offset:21504
	ds_read_b128 v[186:189], v236 offset:22528
	ds_read_b128 v[190:193], v236 offset:23552
	global_load_lds_dwordx4 v[218:219], off
	s_add_i32 m0, s26, 0x2000
	s_add_u32 s26, s58, 0x80000
	v_lshl_add_u64 v[220:221], s[58:59], 0, v[200:201]
	s_addc_u32 s27, s59, 0
	s_add_i32 s35, s88, s66
	global_load_lds_dwordx4 v[220:221], off
	v_lshl_add_u64 v[222:223], s[26:27], 0, v[196:197]
	s_mov_b32 m0, s35
	v_lshl_add_u64 v[224:225], s[60:61], 0, v[198:199]
	global_load_lds_dwordx4 v[222:223], off
	v_lshl_add_u64 v[222:223], s[26:27], 0, v[200:201]
	s_add_i32 m0, s35, 0x2000
	s_nop 0
	global_load_lds_dwordx4 v[222:223], off
	v_lshl_add_u64 v[222:223], s[60:61], 0, v[194:195]
	s_mov_b32 m0, s67
	s_nop 0
	global_load_lds_dwordx4 v[222:223], off
	s_mov_b32 m0, s68
	s_nop 0
	global_load_lds_dwordx4 v[224:225], off
	s_waitcnt vmcnt(8)
	s_waitcnt lgkmcnt(0)
	s_barrier
	s_setprio 1
	s_waitcnt lgkmcnt(0)
	v_mfma_f32_16x16x32_bf16 v[30:33], v[90:93], v[158:161], v[30:33]
	v_mfma_f32_16x16x32_bf16 v[26:29], v[106:109], v[158:161], v[26:29]
	v_mfma_f32_16x16x32_bf16 v[22:25], v[90:93], v[170:173], v[22:25]
	v_mfma_f32_16x16x32_bf16 v[18:21], v[106:109], v[170:173], v[18:21]
	v_mfma_f32_16x16x32_bf16 v[14:17], v[90:93], v[178:181], v[14:17]
	v_mfma_f32_16x16x32_bf16 v[10:13], v[106:109], v[178:181], v[10:13]
	v_mfma_f32_16x16x32_bf16 v[6:9], v[90:93], v[186:189], v[6:9]
	v_mfma_f32_16x16x32_bf16 v[2:5], v[106:109], v[186:189], v[2:5]
	v_mfma_f32_16x16x32_bf16 v[30:33], v[94:97], v[162:165], v[30:33]
	v_mfma_f32_16x16x32_bf16 v[26:29], v[110:113], v[162:165], v[26:29]
	v_mfma_f32_16x16x32_bf16 v[22:25], v[94:97], v[174:177], v[22:25]
	v_mfma_f32_16x16x32_bf16 v[18:21], v[110:113], v[174:177], v[18:21]
	v_mfma_f32_16x16x32_bf16 v[14:17], v[94:97], v[182:185], v[14:17]
	v_mfma_f32_16x16x32_bf16 v[10:13], v[110:113], v[182:185], v[10:13]
	v_mfma_f32_16x16x32_bf16 v[6:9], v[94:97], v[190:193], v[6:9]
	v_mfma_f32_16x16x32_bf16 v[2:5], v[110:113], v[190:193], v[2:5]
	s_setprio 0
	s_setprio 1
	v_mfma_f32_16x16x32_bf16 v[86:89], v[122:125], v[170:173], v[86:89]
	v_mfma_f32_16x16x32_bf16 v[82:85], v[138:141], v[170:173], v[82:85]
	v_mfma_f32_16x16x32_bf16 v[78:81], v[122:125], v[178:181], v[78:81]
	v_mfma_f32_16x16x32_bf16 v[74:77], v[138:141], v[178:181], v[74:77]
	v_mfma_f32_16x16x32_bf16 v[70:73], v[122:125], v[186:189], v[70:73]
	v_mfma_f32_16x16x32_bf16 v[66:69], v[138:141], v[186:189], v[66:69]
	v_mfma_f32_16x16x32_bf16 v[90:93], v[122:125], v[158:161], v[102:105]
	v_mfma_f32_16x16x32_bf16 v[94:97], v[138:141], v[158:161], v[98:101]
	v_mfma_f32_16x16x32_bf16 v[86:89], v[126:129], v[174:177], v[86:89]
	v_mfma_f32_16x16x32_bf16 v[82:85], v[142:145], v[174:177], v[82:85]
	v_mfma_f32_16x16x32_bf16 v[78:81], v[126:129], v[182:185], v[78:81]
	v_mfma_f32_16x16x32_bf16 v[74:77], v[142:145], v[182:185], v[74:77]
	v_mfma_f32_16x16x32_bf16 v[70:73], v[126:129], v[190:193], v[70:73]
	v_mfma_f32_16x16x32_bf16 v[66:69], v[142:145], v[190:193], v[66:69]
	v_mfma_f32_16x16x32_bf16 v[90:93], v[126:129], v[162:165], v[90:93]
	v_mfma_f32_16x16x32_bf16 v[94:97], v[142:145], v[162:165], v[94:97]
	s_setprio 0
	s_barrier
	s_add_i32 s35, 0, 0x18000
	s_add_i32 s54, 0, 0x1c000
	v_add_u32_e32 v110, s35, v232
	v_add_u32_e32 v142, s54, v232
	ds_read_b128 v[98:101], v110
	ds_read_b128 v[102:105], v110 offset:1024
	ds_read_b128 v[106:109], v110 offset:2048
	ds_read_b128 v[110:113], v110 offset:3072
	ds_read_b128 v[122:125], v142
	ds_read_b128 v[126:129], v142 offset:1024
	ds_read_b128 v[138:141], v142 offset:2048
	ds_read_b128 v[142:145], v142 offset:3072
	s_add_u32 s26, s60, 0x80000
	s_addc_u32 s27, s61, 0
	s_mov_b32 m0, s69
	v_lshl_add_u64 v[226:227], s[26:27], 0, v[194:195]
	ds_read_b128 v[158:161], v236 offset:32768
	ds_read_b128 v[162:165], v236 offset:33792
	ds_read_b128 v[170:173], v236 offset:34816
	ds_read_b128 v[174:177], v236 offset:35840
	ds_read_b128 v[178:181], v236 offset:36864
	ds_read_b128 v[182:185], v236 offset:37888
	ds_read_b128 v[186:189], v236 offset:38912
	ds_read_b128 v[190:193], v236 offset:39936
	global_load_lds_dwordx4 v[226:227], off
	v_lshl_add_u64 v[226:227], s[26:27], 0, v[198:199]
	s_mov_b32 m0, s70
	s_nop 0
	global_load_lds_dwordx4 v[226:227], off
	s_waitcnt vmcnt(8)
	s_waitcnt lgkmcnt(0)
	s_barrier
	s_setprio 1
	s_waitcnt lgkmcnt(0)
	v_mfma_f32_16x16x32_bf16 v[62:65], v[98:101], v[158:161], v[62:65]
	v_mfma_f32_16x16x32_bf16 v[58:61], v[106:109], v[158:161], v[58:61]
	v_mfma_f32_16x16x32_bf16 v[54:57], v[98:101], v[170:173], v[54:57]
	v_mfma_f32_16x16x32_bf16 v[50:53], v[106:109], v[170:173], v[50:53]
	v_mfma_f32_16x16x32_bf16 v[46:49], v[98:101], v[178:181], v[46:49]
	v_mfma_f32_16x16x32_bf16 v[42:45], v[106:109], v[178:181], v[42:45]
	v_mfma_f32_16x16x32_bf16 v[38:41], v[98:101], v[186:189], v[38:41]
	v_mfma_f32_16x16x32_bf16 v[34:37], v[106:109], v[186:189], v[34:37]
	v_mfma_f32_16x16x32_bf16 v[62:65], v[102:105], v[162:165], v[62:65]
	v_mfma_f32_16x16x32_bf16 v[58:61], v[110:113], v[162:165], v[58:61]
	v_mfma_f32_16x16x32_bf16 v[54:57], v[102:105], v[174:177], v[54:57]
	v_mfma_f32_16x16x32_bf16 v[50:53], v[110:113], v[174:177], v[50:53]
	v_mfma_f32_16x16x32_bf16 v[46:49], v[102:105], v[182:185], v[46:49]
	v_mfma_f32_16x16x32_bf16 v[42:45], v[110:113], v[182:185], v[42:45]
	v_mfma_f32_16x16x32_bf16 v[38:41], v[102:105], v[190:193], v[38:41]
	v_mfma_f32_16x16x32_bf16 v[34:37], v[110:113], v[190:193], v[34:37]
	s_setprio 0
	s_setprio 1
	v_mfma_f32_16x16x32_bf16 v[166:169], v[122:125], v[158:161], v[166:169]
	v_mfma_f32_16x16x32_bf16 v[154:157], v[138:141], v[158:161], v[154:157]
	v_mfma_f32_16x16x32_bf16 v[150:153], v[122:125], v[170:173], v[150:153]
	v_mfma_f32_16x16x32_bf16 v[146:149], v[138:141], v[170:173], v[146:149]
	v_mfma_f32_16x16x32_bf16 v[134:137], v[122:125], v[178:181], v[134:137]
	v_mfma_f32_16x16x32_bf16 v[130:133], v[138:141], v[178:181], v[130:133]
	v_mfma_f32_16x16x32_bf16 v[118:121], v[122:125], v[186:189], v[118:121]
	v_mfma_f32_16x16x32_bf16 v[114:117], v[138:141], v[186:189], v[114:117]
	v_mfma_f32_16x16x32_bf16 v[166:169], v[126:129], v[162:165], v[166:169]
	v_mfma_f32_16x16x32_bf16 v[162:165], v[142:145], v[162:165], v[154:157]
	v_mfma_f32_16x16x32_bf16 v[150:153], v[126:129], v[174:177], v[150:153]
	v_mfma_f32_16x16x32_bf16 v[146:149], v[142:145], v[174:177], v[146:149]
	v_mfma_f32_16x16x32_bf16 v[134:137], v[126:129], v[182:185], v[134:137]
	v_mfma_f32_16x16x32_bf16 v[130:133], v[142:145], v[182:185], v[130:133]
	v_mfma_f32_16x16x32_bf16 v[118:121], v[126:129], v[190:193], v[118:121]
	v_mfma_f32_16x16x32_bf16 v[114:117], v[142:145], v[190:193], v[114:117]
	s_setprio 0
	s_barrier
	s_add_i32 s26, s35, s66
	v_lshl_add_u64 v[218:219], v[218:219], 0, s[12:13]
	s_mov_b32 m0, s26
	ds_read_b128 v[154:157], v236 offset:49152
	ds_read_b128 v[158:161], v236 offset:50176
	ds_read_b128 v[170:173], v236 offset:51200
	ds_read_b128 v[174:177], v236 offset:52224
	ds_read_b128 v[178:181], v236 offset:53248
	ds_read_b128 v[182:185], v236 offset:54272
	ds_read_b128 v[186:189], v236 offset:55296
	ds_read_b128 v[190:193], v236 offset:56320
	global_load_lds_dwordx4 v[218:219], off
	s_add_i32 m0, s26, 0x2000
	s_add_u32 s26, s58, 0x80080
	v_lshl_add_u64 v[218:219], v[220:221], 0, s[12:13]
	s_addc_u32 s27, s59, 0
	s_add_i32 s35, s54, s66
	global_load_lds_dwordx4 v[218:219], off
	v_lshl_add_u64 v[218:219], s[26:27], 0, v[196:197]
	s_mov_b32 m0, s35
	s_nop 0
	global_load_lds_dwordx4 v[218:219], off
	v_lshl_add_u64 v[218:219], s[26:27], 0, v[200:201]
	s_add_i32 m0, s35, 0x2000
	s_nop 0
	global_load_lds_dwordx4 v[218:219], off
	v_lshl_add_u64 v[218:219], v[222:223], 0, s[12:13]
	s_mov_b32 m0, s80
	s_nop 0
	global_load_lds_dwordx4 v[218:219], off
	v_lshl_add_u64 v[218:219], v[224:225], 0, s[12:13]
	s_mov_b32 m0, s81
	s_nop 0
	global_load_lds_dwordx4 v[218:219], off
	s_waitcnt vmcnt(8)
	s_waitcnt lgkmcnt(0)
	s_barrier
	s_setprio 1
	s_waitcnt lgkmcnt(0)
	v_mfma_f32_16x16x32_bf16 v[30:33], v[98:101], v[154:157], v[30:33]
	v_mfma_f32_16x16x32_bf16 v[26:29], v[106:109], v[154:157], v[26:29]
	v_mfma_f32_16x16x32_bf16 v[22:25], v[98:101], v[170:173], v[22:25]
	v_mfma_f32_16x16x32_bf16 v[18:21], v[106:109], v[170:173], v[18:21]
	v_mfma_f32_16x16x32_bf16 v[14:17], v[98:101], v[178:181], v[14:17]
	v_mfma_f32_16x16x32_bf16 v[10:13], v[106:109], v[178:181], v[10:13]
	v_mfma_f32_16x16x32_bf16 v[6:9], v[98:101], v[186:189], v[6:9]
	v_mfma_f32_16x16x32_bf16 v[2:5], v[106:109], v[186:189], v[2:5]
	v_mfma_f32_16x16x32_bf16 v[30:33], v[102:105], v[158:161], v[30:33]
	v_mfma_f32_16x16x32_bf16 v[26:29], v[110:113], v[158:161], v[26:29]
	v_mfma_f32_16x16x32_bf16 v[22:25], v[102:105], v[174:177], v[22:25]
	v_mfma_f32_16x16x32_bf16 v[18:21], v[110:113], v[174:177], v[18:21]
	v_mfma_f32_16x16x32_bf16 v[14:17], v[102:105], v[182:185], v[14:17]
	v_mfma_f32_16x16x32_bf16 v[10:13], v[110:113], v[182:185], v[10:13]
	v_mfma_f32_16x16x32_bf16 v[6:9], v[102:105], v[190:193], v[6:9]
	v_mfma_f32_16x16x32_bf16 v[2:5], v[110:113], v[190:193], v[2:5]
	s_setprio 0
	s_setprio 1
	v_mfma_f32_16x16x32_bf16 v[90:93], v[122:125], v[154:157], v[90:93]
	v_mfma_f32_16x16x32_bf16 v[102:105], v[126:129], v[158:161], v[90:93]
	v_mfma_f32_16x16x32_bf16 v[90:93], v[138:141], v[154:157], v[94:97]
	v_mfma_f32_16x16x32_bf16 v[86:89], v[122:125], v[170:173], v[86:89]
	v_mfma_f32_16x16x32_bf16 v[82:85], v[138:141], v[170:173], v[82:85]
	v_mfma_f32_16x16x32_bf16 v[78:81], v[122:125], v[178:181], v[78:81]
	v_mfma_f32_16x16x32_bf16 v[74:77], v[138:141], v[178:181], v[74:77]
	v_mfma_f32_16x16x32_bf16 v[70:73], v[122:125], v[186:189], v[70:73]
	v_mfma_f32_16x16x32_bf16 v[66:69], v[138:141], v[186:189], v[66:69]
	v_mfma_f32_16x16x32_bf16 v[98:101], v[142:145], v[158:161], v[90:93]
	v_mfma_f32_16x16x32_bf16 v[86:89], v[126:129], v[174:177], v[86:89]
	v_mfma_f32_16x16x32_bf16 v[82:85], v[142:145], v[174:177], v[82:85]
	v_mfma_f32_16x16x32_bf16 v[78:81], v[126:129], v[182:185], v[78:81]
	v_mfma_f32_16x16x32_bf16 v[74:77], v[142:145], v[182:185], v[74:77]
	v_mfma_f32_16x16x32_bf16 v[70:73], v[126:129], v[190:193], v[70:73]
	v_mfma_f32_16x16x32_bf16 v[66:69], v[142:145], v[190:193], v[66:69]
	s_setprio 0
	s_add_i32 s34, s34, 2
	s_cmp_gt_u32 s34, 29
	s_mov_b64 s[54:55], s[56:57]
	s_barrier
	s_cbranch_scc0 .LBB0_618
	s_and_b64 vcc, exec, s[14:15]
	s_cbranch_vccz .LBB0_625
	s_barrier
	v_lshl_add_u32 v218, s2, 8, v1
	s_cmp_lg_u32 s6, 24
	s_mov_b64 s[4:5], -1
	s_cbranch_scc1 .LBB0_626

.LBB0_788:
	v_cndmask_b32_e64 v117, 0, 1, s[16:17]
	s_and_b64 s[16:17], s[16:17], exec
	s_cselect_b32 s16, s52, s53
	v_add_u32_e32 v220, s16, v68
	v_add_u32_e32 v128, v70, v67
	v_add_u32_e32 v20, v220, v66
	ds_read_b64_tr_b16 v[6:7], v104
	ds_read_b64_tr_b16 v[10:11], v104 offset:32
	ds_read_b64_tr_b16 v[14:15], v104 offset:64
	ds_read_b64_tr_b16 v[18:19], v104 offset:96
	ds_read_b64_tr_b16 v[22:23], v104 offset:128
	ds_read_b64_tr_b16 v[26:27], v104 offset:160
	ds_read_b64_tr_b16 v[30:31], v104 offset:192
	ds_read_b64_tr_b16 v[34:35], v104 offset:224
	ds_read_b64_tr_b16 v[38:39], v104 offset:256
	ds_read_b64_tr_b16 v[42:43], v104 offset:288
	ds_read_b64_tr_b16 v[46:47], v104 offset:320
	ds_read_b64_tr_b16 v[120:121], v104 offset:352
	ds_read_b64_tr_b16 v[48:49], v104 offset:384
	ds_read_b64_tr_b16 v[122:123], v104 offset:416
	ds_read_b64_tr_b16 v[126:127], v104 offset:448
	ds_read_b64_tr_b16 v[130:131], v104 offset:480
	ds_read_b64_tr_b16 v[134:135], v104 offset:512
	ds_read_b64_tr_b16 v[2:3], v105
	ds_read_b64_tr_b16 v[4:5], v128
	ds_read_b64_tr_b16 v[8:9], v128 offset:32
	ds_read_b64_tr_b16 v[12:13], v128 offset:64
	ds_read_b64_tr_b16 v[16:17], v128 offset:96
	ds_read_b64_tr_b16 v[132:133], v128 offset:512
	v_add_u32_e32 v21, v220, v69
	ds_read_b64_tr_b16 v[136:137], v20
	ds_read_b64_tr_b16 v[138:139], v21
	s_waitcnt lgkmcnt(0)
	v_mfma_f32_16x16x32_bf16 v[140:143], v[136:139], v[4:7], 0
	ds_read_b64_tr_b16 v[4:5], v106
	ds_read_b64_tr_b16 v[146:147], v106 offset:32
	ds_read_b64_tr_b16 v[150:151], v106 offset:64
	s_or_b32 s35, s34, s20
	s_mov_b32 s34, 1
	v_mfma_f32_16x16x32_bf16 v[6:9], v[136:139], v[8:11], 0
	ds_read_b64_tr_b16 v[144:145], v105 offset:32
	ds_read_b64_tr_b16 v[148:149], v105 offset:64
	ds_read_b64_tr_b16 v[10:11], v105 offset:96
	v_cmp_ne_u32_e64 s[16:17], 1, v117
	v_mfma_f32_16x16x32_bf16 v[152:155], v[136:139], v[12:15], 0
	ds_read_b64_tr_b16 v[12:13], v106 offset:96
	ds_read_b64_tr_b16 v[14:15], v105 offset:128
	ds_read_b64_tr_b16 v[20:21], v128 offset:128
	ds_read_b64_tr_b16 v[24:25], v128 offset:160
	ds_read_b64_tr_b16 v[28:29], v128 offset:192
	ds_read_b64_tr_b16 v[32:33], v128 offset:224
	v_mfma_f32_16x16x32_bf16 v[156:159], v[136:139], v[16:19], 0
	ds_read_b64_tr_b16 v[16:17], v106 offset:128
	ds_read_b64_tr_b16 v[162:163], v106 offset:160
	ds_read_b64_tr_b16 v[166:167], v106 offset:192
	s_waitcnt lgkmcnt(6)
	v_mfma_f32_16x16x32_bf16 v[18:21], v[136:139], v[20:23], 0
	s_waitcnt lgkmcnt(5)
	v_mfma_f32_16x16x32_bf16 v[22:25], v[136:139], v[24:27], 0
	ds_read_b64_tr_b16 v[160:161], v105 offset:160
	ds_read_b64_tr_b16 v[164:165], v105 offset:192
	ds_read_b64_tr_b16 v[26:27], v105 offset:224
	s_waitcnt lgkmcnt(7)
	v_mfma_f32_16x16x32_bf16 v[168:171], v[136:139], v[28:31], 0
	ds_read_b64_tr_b16 v[28:29], v106 offset:224
	ds_read_b64_tr_b16 v[30:31], v105 offset:256
	ds_read_b64_tr_b16 v[36:37], v128 offset:256
	ds_read_b64_tr_b16 v[40:41], v128 offset:288
	ds_read_b64_tr_b16 v[44:45], v128 offset:320
	ds_read_b64_tr_b16 v[118:119], v128 offset:352
	s_waitcnt lgkmcnt(12)
	v_mfma_f32_16x16x32_bf16 v[172:175], v[136:139], v[32:35], 0
	ds_read_b64_tr_b16 v[32:33], v106 offset:256
	ds_read_b64_tr_b16 v[178:179], v106 offset:288
	ds_read_b64_tr_b16 v[182:183], v106 offset:320
	s_waitcnt lgkmcnt(6)
	v_mfma_f32_16x16x32_bf16 v[34:37], v[136:139], v[36:39], 0
	s_waitcnt lgkmcnt(5)
	v_mfma_f32_16x16x32_bf16 v[38:41], v[136:139], v[40:43], 0
	ds_read_b64_tr_b16 v[176:177], v105 offset:288
	ds_read_b64_tr_b16 v[180:181], v105 offset:320
	ds_read_b64_tr_b16 v[42:43], v105 offset:352
	s_waitcnt lgkmcnt(7)
	v_mfma_f32_16x16x32_bf16 v[184:187], v[136:139], v[44:47], 0
	ds_read_b64_tr_b16 v[44:45], v106 offset:352
	ds_read_b64_tr_b16 v[188:189], v105 offset:384
	ds_read_b64_tr_b16 v[46:47], v128 offset:384
	s_waitcnt lgkmcnt(9)
	v_mfma_f32_16x16x32_bf16 v[192:195], v[136:139], v[118:121], 0
	ds_read_b64_tr_b16 v[120:121], v128 offset:416
	ds_read_b64_tr_b16 v[124:125], v128 offset:448
	ds_read_b64_tr_b16 v[128:129], v128 offset:480
	ds_read_b64_tr_b16 v[190:191], v106 offset:384
	ds_read_b64_tr_b16 v[198:199], v106 offset:416
	ds_read_b64_tr_b16 v[202:203], v106 offset:448
	s_waitcnt lgkmcnt(5)
	v_mfma_f32_16x16x32_bf16 v[118:121], v[136:139], v[120:123], 0
	ds_read_b64_tr_b16 v[196:197], v105 offset:416
	ds_read_b64_tr_b16 v[200:201], v105 offset:448
	ds_read_b64_tr_b16 v[122:123], v105 offset:480
	s_waitcnt lgkmcnt(7)
	v_mfma_f32_16x16x32_bf16 v[204:207], v[136:139], v[124:127], 0
	ds_read_b64_tr_b16 v[208:209], v105 offset:512
	ds_read_b64_tr_b16 v[124:125], v106 offset:480
	ds_read_b64_tr_b16 v[210:211], v106 offset:512
	s_waitcnt lgkmcnt(9)
	v_mfma_f32_16x16x32_bf16 v[126:129], v[136:139], v[128:131], 0
	v_add_u32_e32 v130, v220, v91
	ds_read_b64_tr_b16 v[212:213], v130
	ds_read_b64_tr_b16 v[214:215], v130 offset:1152
	v_mfma_f32_16x16x32_bf16 v[46:49], v[136:139], v[46:49], 0
	v_mfma_f32_16x16x32_bf16 v[130:133], v[136:139], v[132:135], 0
	v_add_u32_e32 v117, v220, v92
	s_waitcnt lgkmcnt(0)
	v_mfma_f32_16x16x32_bf16 v[2:5], v[212:215], v[2:5], v[140:143]
	ds_read_b64_tr_b16 v[138:139], v117
	s_nop 1
	ds_read_b64_tr_b16 v[140:141], v117 offset:1152
	v_mfma_f32_16x16x32_bf16 v[6:9], v[212:215], v[144:147], v[6:9]
	v_mfma_f32_16x16x32_bf16 v[134:137], v[212:215], v[148:151], v[152:155]
	v_mfma_f32_16x16x32_bf16 v[10:13], v[212:215], v[10:13], v[156:159]
	v_mfma_f32_16x16x32_bf16 v[14:17], v[212:215], v[14:17], v[18:21]
	v_mfma_f32_16x16x32_bf16 v[18:21], v[212:215], v[160:163], v[22:25]
	v_mfma_f32_16x16x32_bf16 v[22:25], v[212:215], v[164:167], v[168:171]
	v_mfma_f32_16x16x32_bf16 v[26:29], v[212:215], v[26:29], v[172:175]
	v_mfma_f32_16x16x32_bf16 v[30:33], v[212:215], v[30:33], v[34:37]
	s_nop 2
	ds_read_b64_tr_b16 v[34:35], v107
	ds_read_b64_tr_b16 v[142:143], v107 offset:32
	ds_read_b64_tr_b16 v[146:147], v107 offset:64
	ds_read_b64_tr_b16 v[150:151], v107 offset:96
	ds_read_b64_tr_b16 v[152:153], v108 offset:96
	ds_read_b64_tr_b16 v[156:157], v108 offset:128
	ds_read_b64_tr_b16 v[160:161], v108 offset:160
	ds_read_b64_tr_b16 v[164:165], v108 offset:192
	ds_read_b64_tr_b16 v[154:155], v107 offset:128
	ds_read_b64_tr_b16 v[158:159], v107 offset:160
	ds_read_b64_tr_b16 v[162:163], v107 offset:192
	ds_read_b64_tr_b16 v[170:171], v107 offset:224
	v_mfma_f32_16x16x32_bf16 v[38:41], v[212:215], v[176:179], v[38:41]
	v_mfma_f32_16x16x32_bf16 v[166:169], v[212:215], v[180:183], v[184:187]
	ds_read_b64_tr_b16 v[172:173], v108 offset:224
	ds_read_b64_tr_b16 v[176:177], v108 offset:256
	ds_read_b64_tr_b16 v[180:181], v108 offset:288
	ds_read_b64_tr_b16 v[184:185], v108 offset:320
	ds_read_b64_tr_b16 v[174:175], v107 offset:256
	ds_read_b64_tr_b16 v[178:179], v107 offset:288
	ds_read_b64_tr_b16 v[182:183], v107 offset:320
	ds_read_b64_tr_b16 v[186:187], v107 offset:352
	v_mfma_f32_16x16x32_bf16 v[42:45], v[212:215], v[42:45], v[192:195]
	v_mfma_f32_16x16x32_bf16 v[46:49], v[212:215], v[188:191], v[46:49]
	v_mfma_f32_16x16x32_bf16 v[118:121], v[212:215], v[196:199], v[118:121]
	ds_read_b64_tr_b16 v[188:189], v108 offset:352
	ds_read_b64_tr_b16 v[192:193], v108 offset:384
	ds_read_b64_tr_b16 v[196:197], v108 offset:416
	ds_read_b64_tr_b16 v[218:219], v108 offset:448
	v_mfma_f32_16x16x32_bf16 v[198:201], v[212:215], v[200:203], v[204:207]
	ds_read_b64_tr_b16 v[190:191], v107 offset:384
	ds_read_b64_tr_b16 v[194:195], v107 offset:416
	ds_read_b64_tr_b16 v[216:217], v107 offset:448
	ds_read_b64_tr_b16 v[202:203], v107 offset:480
	v_mfma_f32_16x16x32_bf16 v[122:125], v[212:215], v[122:125], v[126:129]
	ds_read_b64_tr_b16 v[36:37], v108
	ds_read_b64_tr_b16 v[144:145], v108 offset:32
	ds_read_b64_tr_b16 v[148:149], v108 offset:64
	ds_read_b64_tr_b16 v[126:127], v107 offset:512
	ds_read_b64_tr_b16 v[204:205], v108 offset:480
	ds_read_b64_tr_b16 v[128:129], v108 offset:512
	v_mfma_f32_16x16x32_bf16 v[130:133], v[212:215], v[208:211], v[130:133]
	v_add_u32_e32 v117, v220, v93
	s_waitcnt lgkmcnt(5)
	v_mfma_f32_16x16x32_bf16 v[2:5], v[138:141], v[34:37], v[2:5]
	s_waitcnt lgkmcnt(4)
	v_mfma_f32_16x16x32_bf16 v[6:9], v[138:141], v[142:145], v[6:9]
	s_waitcnt lgkmcnt(3)
	v_mfma_f32_16x16x32_bf16 v[34:37], v[138:141], v[146:149], v[134:137]
	s_nop 2
	ds_read_b64_tr_b16 v[134:135], v117
	ds_read_b64_tr_b16 v[136:137], v117 offset:1152
	v_mfma_f32_16x16x32_bf16 v[10:13], v[138:141], v[150:153], v[10:13]
	v_mfma_f32_16x16x32_bf16 v[14:17], v[138:141], v[154:157], v[14:17]
	ds_read_b64_tr_b16 v[142:143], v109
	ds_read_b64_tr_b16 v[146:147], v109 offset:32
	ds_read_b64_tr_b16 v[150:151], v109 offset:64
	ds_read_b64_tr_b16 v[154:155], v109 offset:96
	v_mfma_f32_16x16x32_bf16 v[18:21], v[138:141], v[158:161], v[18:21]
	v_mfma_f32_16x16x32_bf16 v[22:25], v[138:141], v[162:165], v[22:25]
	v_mfma_f32_16x16x32_bf16 v[26:29], v[138:141], v[170:173], v[26:29]
	ds_read_b64_tr_b16 v[156:157], v110 offset:96
	ds_read_b64_tr_b16 v[160:161], v110 offset:128
	ds_read_b64_tr_b16 v[164:165], v110 offset:160
	ds_read_b64_tr_b16 v[170:171], v110 offset:192
	v_mfma_f32_16x16x32_bf16 v[30:33], v[138:141], v[174:177], v[30:33]
	v_mfma_f32_16x16x32_bf16 v[38:41], v[138:141], v[178:181], v[38:41]
	v_mfma_f32_16x16x32_bf16 v[172:175], v[138:141], v[182:185], v[166:169]
	ds_read_b64_tr_b16 v[158:159], v109 offset:128
	ds_read_b64_tr_b16 v[162:163], v109 offset:160
	s_nop 0
	ds_read_b64_tr_b16 v[168:169], v109 offset:192
	ds_read_b64_tr_b16 v[176:177], v109 offset:224
	v_mfma_f32_16x16x32_bf16 v[42:45], v[138:141], v[186:189], v[42:45]
	ds_read_b64_tr_b16 v[178:179], v110 offset:224
	ds_read_b64_tr_b16 v[182:183], v110 offset:256
	ds_read_b64_tr_b16 v[186:187], v110 offset:288
	ds_read_b64_tr_b16 v[208:209], v110 offset:320
	ds_read_b64_tr_b16 v[180:181], v109 offset:256
	ds_read_b64_tr_b16 v[184:185], v109 offset:288
	ds_read_b64_tr_b16 v[206:207], v109 offset:320
	ds_read_b64_tr_b16 v[188:189], v109 offset:352
	v_mfma_f32_16x16x32_bf16 v[46:49], v[138:141], v[190:193], v[46:49]
	v_mfma_f32_16x16x32_bf16 v[118:121], v[138:141], v[194:197], v[118:121]
	ds_read_b64_tr_b16 v[190:191], v110 offset:352
	ds_read_b64_tr_b16 v[194:195], v110 offset:384
	ds_read_b64_tr_b16 v[212:213], v110 offset:416
	ds_read_b64_tr_b16 v[220:221], v110 offset:448
	v_mfma_f32_16x16x32_bf16 v[196:199], v[138:141], v[216:219], v[198:201]
	ds_read_b64_tr_b16 v[192:193], v109 offset:384
	ds_read_b64_tr_b16 v[210:211], v109 offset:416
	ds_read_b64_tr_b16 v[218:219], v109 offset:448
	ds_read_b64_tr_b16 v[200:201], v109 offset:480
	s_waitcnt lgkmcnt(14)
	v_mfma_f32_16x16x32_bf16 v[122:125], v[138:141], v[202:205], v[122:125]
	ds_read_b64_tr_b16 v[144:145], v110
	ds_read_b64_tr_b16 v[148:149], v110 offset:32
	ds_read_b64_tr_b16 v[152:153], v110 offset:64
	ds_read_b64_tr_b16 v[214:215], v109 offset:512
	ds_read_b64_tr_b16 v[202:203], v110 offset:480
	ds_read_b64_tr_b16 v[216:217], v110 offset:512
	v_mfma_f32_16x16x32_bf16 v[126:129], v[138:141], v[126:129], v[130:133]
	s_waitcnt lgkmcnt(5)
	v_mfma_f32_16x16x32_bf16 v[2:5], v[134:137], v[142:145], v[2:5]
	s_waitcnt lgkmcnt(4)
	v_mfma_f32_16x16x32_bf16 v[6:9], v[134:137], v[146:149], v[6:9]
	s_waitcnt lgkmcnt(3)
	v_mfma_f32_16x16x32_bf16 v[34:37], v[134:137], v[150:153], v[34:37]
	v_mfma_f32_16x16x32_bf16 v[10:13], v[134:137], v[154:157], v[10:13]
	v_mfma_f32_16x16x32_bf16 v[14:17], v[134:137], v[158:161], v[14:17]
	v_mfma_f32_16x16x32_bf16 v[18:21], v[134:137], v[162:165], v[18:21]
	v_mfma_f32_16x16x32_bf16 v[22:25], v[134:137], v[168:171], v[22:25]
	v_mfma_f32_16x16x32_bf16 v[26:29], v[134:137], v[176:179], v[26:29]
	v_mfma_f32_16x16x32_bf16 v[30:33], v[134:137], v[180:183], v[30:33]
	v_mfma_f32_16x16x32_bf16 v[38:41], v[134:137], v[184:187], v[38:41]
	v_mfma_f32_16x16x32_bf16 v[130:133], v[134:137], v[206:209], v[172:175]
	v_mfma_f32_16x16x32_bf16 v[42:45], v[134:137], v[188:191], v[42:45]
	v_mfma_f32_16x16x32_bf16 v[46:49], v[134:137], v[192:195], v[46:49]
	v_mfma_f32_16x16x32_bf16 v[118:121], v[134:137], v[210:213], v[118:121]
	v_mfma_f32_16x16x32_bf16 v[138:141], v[134:137], v[218:221], v[196:199]
	s_waitcnt lgkmcnt(1)
	v_mfma_f32_16x16x32_bf16 v[122:125], v[134:137], v[200:203], v[122:125]
	s_waitcnt lgkmcnt(0)
	v_mfma_f32_16x16x32_bf16 v[126:129], v[134:137], v[214:217], v[126:129]
	v_mad_i64_i32 v[142:143], s[26:27], s35, v116, v[56:57]
	v_mbcnt_lo_u32_b32 v150, -1, 0
	v_mbcnt_hi_u32_b32 v150, -1, v150
	v_bfe_u32 v150, v150, 4, 1
	v_mul_u32_u24_e32 v150, 0xff8, v150
	v_mov_b32_e32 v151, 0
	v_lshl_add_u64 v[152:153], v[142:143], 0, v[150:151]
	v_cvt_pk_bf16_f32 v144, v2, v3
	v_cvt_pk_bf16_f32 v145, v4, v5
	v_cvt_pk_bf16_f32 v146, v6, v7
	v_cvt_pk_bf16_f32 v147, v8, v9
	s_nop 0
	s_nop 0
	v_permlane16_swap_b32_e32 v144, v146
	v_permlane16_swap_b32_e32 v145, v147
	global_store_dwordx4 v[152:153], v[144:147], off
	v_cvt_pk_bf16_f32 v148, v34, v35
	v_cvt_pk_bf16_f32 v149, v36, v37
	v_add_co_u32_e32 v154, vcc, s62, v152
	v_cvt_pk_bf16_f32 v150, v10, v11
	v_cvt_pk_bf16_f32 v151, v12, v13
	v_addc_co_u32_e32 v155, vcc, 0, v153, vcc
	s_nop 0
	v_permlane16_swap_b32_e32 v148, v150
	v_permlane16_swap_b32_e32 v149, v151
	global_store_dwordx4 v[154:155], v[148:151], off
	v_cvt_pk_bf16_f32 v144, v14, v15
	v_cvt_pk_bf16_f32 v145, v16, v17
	v_add_co_u32_e32 v154, vcc, s54, v152
	v_cvt_pk_bf16_f32 v146, v18, v19
	v_cvt_pk_bf16_f32 v147, v20, v21
	v_addc_co_u32_e32 v155, vcc, 0, v153, vcc
	s_nop 0
	v_permlane16_swap_b32_e32 v144, v146
	v_permlane16_swap_b32_e32 v145, v147
	global_store_dwordx4 v[154:155], v[144:147], off
	v_cvt_pk_bf16_f32 v148, v22, v23
	v_cvt_pk_bf16_f32 v149, v24, v25
	v_add_co_u32_e32 v154, vcc, s63, v152
	v_cvt_pk_bf16_f32 v150, v26, v27
	v_cvt_pk_bf16_f32 v151, v28, v29
	v_addc_co_u32_e32 v155, vcc, 0, v153, vcc
	s_nop 0
	v_permlane16_swap_b32_e32 v148, v150
	v_permlane16_swap_b32_e32 v149, v151
	global_store_dwordx4 v[154:155], v[148:151], off
	v_cvt_pk_bf16_f32 v144, v30, v31
	v_cvt_pk_bf16_f32 v145, v32, v33
	v_add_co_u32_e32 v154, vcc, s66, v152
	v_cvt_pk_bf16_f32 v146, v38, v39
	v_cvt_pk_bf16_f32 v147, v40, v41
	v_addc_co_u32_e32 v155, vcc, 0, v153, vcc
	s_nop 0
	v_permlane16_swap_b32_e32 v144, v146
	v_permlane16_swap_b32_e32 v145, v147
	global_store_dwordx4 v[154:155], v[144:147], off
	v_cvt_pk_bf16_f32 v148, v130, v131
	v_cvt_pk_bf16_f32 v149, v132, v133
	v_add_co_u32_e32 v154, vcc, s67, v152
	v_cvt_pk_bf16_f32 v150, v42, v43
	v_cvt_pk_bf16_f32 v151, v44, v45
	v_addc_co_u32_e32 v155, vcc, 0, v153, vcc
	s_nop 0
	v_permlane16_swap_b32_e32 v148, v150
	v_permlane16_swap_b32_e32 v149, v151
	global_store_dwordx4 v[154:155], v[148:151], off
	v_cvt_pk_bf16_f32 v144, v46, v47
	v_cvt_pk_bf16_f32 v145, v48, v49
	v_add_co_u32_e32 v154, vcc, s68, v152
	v_cvt_pk_bf16_f32 v146, v118, v119
	v_cvt_pk_bf16_f32 v147, v120, v121
	v_addc_co_u32_e32 v155, vcc, 0, v153, vcc
	s_nop 0
	v_permlane16_swap_b32_e32 v144, v146
	v_permlane16_swap_b32_e32 v145, v147
	global_store_dwordx4 v[154:155], v[144:147], off
	v_cvt_pk_bf16_f32 v148, v138, v139
	v_cvt_pk_bf16_f32 v149, v140, v141
	v_add_co_u32_e32 v154, vcc, s69, v152
	v_cvt_pk_bf16_f32 v150, v122, v123
	v_cvt_pk_bf16_f32 v151, v124, v125
	v_addc_co_u32_e32 v155, vcc, 0, v153, vcc
	s_nop 0
	v_permlane16_swap_b32_e32 v148, v150
	v_permlane16_swap_b32_e32 v149, v151
	global_store_dwordx4 v[154:155], v[148:151], off
	v_add_co_u32_e32 v142, vcc, 0x10000, v142
	v_cvt_pk_bf16_f32 v2, v126, v127
	v_cvt_pk_bf16_f32 v3, v128, v129
	v_addc_co_u32_e32 v143, vcc, 0, v143, vcc
	s_and_b64 vcc, exec, s[16:17]
	s_mov_b64 s[16:17], 0
	global_store_dwordx2 v[142:143], v[2:3], off
	s_cbranch_vccz .LBB0_788
	s_add_i32 s71, s71, s33
	s_cmpk_gt_i32 s71, 0x43f
	s_barrier
	s_cbranch_scc0 .LBB0_775

.LBB0_1322:
	s_add_u32 s26, s8, s12
	s_addc_u32 s27, s9, s13
	s_add_u32 s12, s12, 0x100
	ds_read_b128 v[138:141], v84
	ds_read_b128 v[142:145], v84 offset:1024
	ds_read_b128 v[146:149], v84 offset:2048
	ds_read_b128 v[158:161], v84 offset:3072
	ds_read_b128 v[162:165], v85
	ds_read_b128 v[166:169], v85 offset:1024
	ds_read_b128 v[170:173], v85 offset:2048
	ds_read_b128 v[174:177], v85 offset:3072
	s_addc_u32 s13, s13, 0
	v_cmp_lt_u64_e32 vcc, s[12:13], v[82:83]
	s_and_b64 s[14:15], vcc, exec
	s_cselect_b32 s15, 0, 0xfffff000
	s_cselect_b32 s14, 0, -1
	s_add_u32 s12, s15, s12
	s_addc_u32 s13, s14, s13
	s_cmp_lg_u32 s56, 28
	s_cselect_b32 s14, s12, 0
	s_cselect_b32 s15, s13, 0
	s_add_u32 s16, s8, s14
	s_addc_u32 s17, s9, s15
	s_add_u32 s14, s0, s14
	s_addc_u32 s15, s1, s15
	s_add_u32 s26, s26, 0x80080
	s_addc_u32 s27, s27, 0
	s_mov_b32 m0, s57
	v_lshl_add_u64 v[178:179], s[26:27], 0, v[150:151]
	ds_read_b128 v[188:191], v134
	ds_read_b128 v[192:195], v134 offset:1024
	ds_read_b128 v[196:199], v134 offset:2048
	ds_read_b128 v[200:203], v134 offset:3072
	ds_read_b128 v[204:207], v134 offset:4096
	ds_read_b128 v[208:211], v134 offset:5120
	ds_read_b128 v[212:215], v134 offset:6144
	ds_read_b128 v[216:219], v134 offset:7168
	global_load_lds_dwordx4 v[178:179], off
	v_lshl_add_u64 v[178:179], s[26:27], 0, v[154:155]
	s_mov_b32 m0, s58
	s_nop 0
	global_load_lds_dwordx4 v[178:179], off
	s_waitcnt vmcnt(8)
	s_waitcnt lgkmcnt(0)
	s_barrier
	s_setprio 1
	s_waitcnt lgkmcnt(0)
	v_mfma_f32_16x16x32_bf16 v[26:29], v[138:141], v[188:191], v[26:29]
	v_mfma_f32_16x16x32_bf16 v[54:57], v[146:149], v[188:191], v[54:57]
	v_mfma_f32_16x16x32_bf16 v[98:101], v[138:141], v[196:199], v[98:101]
	v_mfma_f32_16x16x32_bf16 v[118:121], v[146:149], v[196:199], v[118:121]
	v_mfma_f32_16x16x32_bf16 v[126:129], v[138:141], v[204:207], v[126:129]
	v_mfma_f32_16x16x32_bf16 v[38:41], v[146:149], v[204:207], v[38:41]
	v_mfma_f32_16x16x32_bf16 v[50:53], v[138:141], v[212:215], v[50:53]
	v_mfma_f32_16x16x32_bf16 v[66:69], v[146:149], v[212:215], v[66:69]
	v_mfma_f32_16x16x32_bf16 v[26:29], v[142:145], v[192:195], v[26:29]
	v_mfma_f32_16x16x32_bf16 v[54:57], v[158:161], v[192:195], v[54:57]
	v_mfma_f32_16x16x32_bf16 v[98:101], v[142:145], v[200:203], v[98:101]
	v_mfma_f32_16x16x32_bf16 v[118:121], v[158:161], v[200:203], v[118:121]
	v_mfma_f32_16x16x32_bf16 v[126:129], v[142:145], v[208:211], v[126:129]
	v_mfma_f32_16x16x32_bf16 v[38:41], v[158:161], v[208:211], v[38:41]
	v_mfma_f32_16x16x32_bf16 v[50:53], v[142:145], v[216:219], v[50:53]
	v_mfma_f32_16x16x32_bf16 v[66:69], v[158:161], v[216:219], v[66:69]
	s_setprio 0
	s_setprio 1
	v_mfma_f32_16x16x32_bf16 v[74:77], v[162:165], v[188:191], v[74:77]
	v_mfma_f32_16x16x32_bf16 v[62:65], v[170:173], v[188:191], v[62:65]
	v_mfma_f32_16x16x32_bf16 v[42:45], v[162:165], v[196:199], v[42:45]
	v_mfma_f32_16x16x32_bf16 v[30:33], v[170:173], v[196:199], v[30:33]
	v_mfma_f32_16x16x32_bf16 v[34:37], v[162:165], v[204:207], v[34:37]
	v_mfma_f32_16x16x32_bf16 v[46:49], v[170:173], v[204:207], v[46:49]
	v_mfma_f32_16x16x32_bf16 v[58:61], v[162:165], v[212:215], v[58:61]
	v_mfma_f32_16x16x32_bf16 v[70:73], v[170:173], v[212:215], v[70:73]
	v_mfma_f32_16x16x32_bf16 v[74:77], v[166:169], v[192:195], v[74:77]
	v_mfma_f32_16x16x32_bf16 v[62:65], v[174:177], v[192:195], v[62:65]
	v_mfma_f32_16x16x32_bf16 v[42:45], v[166:169], v[200:203], v[42:45]
	v_mfma_f32_16x16x32_bf16 v[30:33], v[174:177], v[200:203], v[30:33]
	v_mfma_f32_16x16x32_bf16 v[34:37], v[166:169], v[208:211], v[34:37]
	v_mfma_f32_16x16x32_bf16 v[46:49], v[174:177], v[208:211], v[46:49]
	v_mfma_f32_16x16x32_bf16 v[58:61], v[166:169], v[216:219], v[58:61]
	v_mfma_f32_16x16x32_bf16 v[70:73], v[174:177], v[216:219], v[70:73]
	s_setprio 0
	s_barrier
	s_mov_b32 m0, s59
	v_lshl_add_u64 v[178:179], s[14:15], 0, v[152:153]
	s_add_u32 s26, s14, 0x80000
	ds_read_b128 v[188:191], v134 offset:16384
	ds_read_b128 v[192:195], v134 offset:17408
	ds_read_b128 v[196:199], v134 offset:18432
	ds_read_b128 v[200:203], v134 offset:19456
	ds_read_b128 v[204:207], v134 offset:20480
	ds_read_b128 v[208:211], v134 offset:21504
	ds_read_b128 v[212:215], v134 offset:22528
	ds_read_b128 v[216:219], v134 offset:23552
	global_load_lds_dwordx4 v[178:179], off
	v_lshl_add_u64 v[220:221], s[14:15], 0, v[156:157]
	s_mov_b32 m0, s60
	s_addc_u32 s27, s15, 0
	global_load_lds_dwordx4 v[220:221], off
	v_lshl_add_u64 v[222:223], s[26:27], 0, v[152:153]
	s_mov_b32 m0, s61
	v_lshl_add_u64 v[224:225], s[16:17], 0, v[154:155]
	global_load_lds_dwordx4 v[222:223], off
	v_lshl_add_u64 v[222:223], s[26:27], 0, v[156:157]
	s_mov_b32 m0, s62
	s_nop 0
	global_load_lds_dwordx4 v[222:223], off
	v_lshl_add_u64 v[222:223], s[16:17], 0, v[150:151]
	s_mov_b32 m0, s51
	s_nop 0
	global_load_lds_dwordx4 v[222:223], off
	s_mov_b32 m0, s52
	s_nop 0
	global_load_lds_dwordx4 v[224:225], off
	s_waitcnt vmcnt(8)
	s_waitcnt lgkmcnt(0)
	s_barrier
	s_setprio 1
	s_waitcnt lgkmcnt(0)
	v_mfma_f32_16x16x32_bf16 v[94:97], v[138:141], v[188:191], v[94:97]
	v_mfma_f32_16x16x32_bf16 v[114:117], v[146:149], v[188:191], v[114:117]
	v_mfma_f32_16x16x32_bf16 v[122:125], v[138:141], v[196:199], v[122:125]
	v_mfma_f32_16x16x32_bf16 v[110:113], v[146:149], v[196:199], v[110:113]
	v_mfma_f32_16x16x32_bf16 v[130:133], v[138:141], v[204:207], v[130:133]
	v_mfma_f32_16x16x32_bf16 v[86:89], v[146:149], v[204:207], v[86:89]
	v_mfma_f32_16x16x32_bf16 v[18:21], v[138:141], v[212:215], v[18:21]
	v_mfma_f32_16x16x32_bf16 v[10:13], v[146:149], v[212:215], v[10:13]
	v_mfma_f32_16x16x32_bf16 v[94:97], v[142:145], v[192:195], v[94:97]
	v_mfma_f32_16x16x32_bf16 v[114:117], v[158:161], v[192:195], v[114:117]
	v_mfma_f32_16x16x32_bf16 v[122:125], v[142:145], v[200:203], v[122:125]
	v_mfma_f32_16x16x32_bf16 v[110:113], v[158:161], v[200:203], v[110:113]
	v_mfma_f32_16x16x32_bf16 v[130:133], v[142:145], v[208:211], v[130:133]
	v_mfma_f32_16x16x32_bf16 v[86:89], v[158:161], v[208:211], v[86:89]
	v_mfma_f32_16x16x32_bf16 v[18:21], v[142:145], v[216:219], v[18:21]
	v_mfma_f32_16x16x32_bf16 v[10:13], v[158:161], v[216:219], v[10:13]
	s_setprio 0
	s_setprio 1
	v_mfma_f32_16x16x32_bf16 v[106:109], v[162:165], v[188:191], v[106:109]
	v_mfma_f32_16x16x32_bf16 v[90:93], v[170:173], v[188:191], v[90:93]
	v_mfma_f32_16x16x32_bf16 v[102:105], v[162:165], v[196:199], v[102:105]
	v_mfma_f32_16x16x32_bf16 v[78:81], v[170:173], v[196:199], v[78:81]
	v_mfma_f32_16x16x32_bf16 v[22:25], v[162:165], v[204:207], v[22:25]
	v_mfma_f32_16x16x32_bf16 v[14:17], v[170:173], v[204:207], v[14:17]
	v_mfma_f32_16x16x32_bf16 v[6:9], v[162:165], v[212:215], v[6:9]
	v_mfma_f32_16x16x32_bf16 v[2:5], v[170:173], v[212:215], v[2:5]
	v_mfma_f32_16x16x32_bf16 v[106:109], v[166:169], v[192:195], v[106:109]
	v_mfma_f32_16x16x32_bf16 v[90:93], v[174:177], v[192:195], v[90:93]
	v_mfma_f32_16x16x32_bf16 v[102:105], v[166:169], v[200:203], v[102:105]
	v_mfma_f32_16x16x32_bf16 v[78:81], v[174:177], v[200:203], v[78:81]
	v_mfma_f32_16x16x32_bf16 v[22:25], v[166:169], v[208:211], v[22:25]
	v_mfma_f32_16x16x32_bf16 v[14:17], v[174:177], v[208:211], v[14:17]
	v_mfma_f32_16x16x32_bf16 v[6:9], v[166:169], v[216:219], v[6:9]
	v_mfma_f32_16x16x32_bf16 v[2:5], v[174:177], v[216:219], v[2:5]
	s_setprio 0
	s_barrier
	ds_read_b128 v[138:141], v135
	ds_read_b128 v[142:145], v135 offset:1024
	ds_read_b128 v[146:149], v135 offset:2048
	ds_read_b128 v[158:161], v135 offset:3072
	ds_read_b128 v[162:165], v136
	ds_read_b128 v[166:169], v136 offset:1024
	ds_read_b128 v[170:173], v136 offset:2048
	ds_read_b128 v[174:177], v136 offset:3072
	s_add_u32 s16, s16, 0x80000
	s_addc_u32 s17, s17, 0
	s_mov_b32 m0, s53
	v_lshl_add_u64 v[226:227], s[16:17], 0, v[150:151]
	ds_read_b128 v[188:191], v134 offset:32768
	ds_read_b128 v[192:195], v134 offset:33792
	ds_read_b128 v[196:199], v134 offset:34816
	ds_read_b128 v[200:203], v134 offset:35840
	ds_read_b128 v[204:207], v134 offset:36864
	ds_read_b128 v[208:211], v134 offset:37888
	ds_read_b128 v[212:215], v134 offset:38912
	ds_read_b128 v[216:219], v134 offset:39936
	global_load_lds_dwordx4 v[226:227], off
	v_lshl_add_u64 v[226:227], s[16:17], 0, v[154:155]
	s_mov_b32 m0, s54
	s_nop 0
	global_load_lds_dwordx4 v[226:227], off
	s_waitcnt vmcnt(8)
	s_waitcnt lgkmcnt(0)
	s_barrier
	s_setprio 1
	s_waitcnt lgkmcnt(0)
	v_mfma_f32_16x16x32_bf16 v[26:29], v[138:141], v[188:191], v[26:29]
	v_mfma_f32_16x16x32_bf16 v[54:57], v[146:149], v[188:191], v[54:57]
	v_mfma_f32_16x16x32_bf16 v[98:101], v[138:141], v[196:199], v[98:101]
	v_mfma_f32_16x16x32_bf16 v[118:121], v[146:149], v[196:199], v[118:121]
	v_mfma_f32_16x16x32_bf16 v[126:129], v[138:141], v[204:207], v[126:129]
	v_mfma_f32_16x16x32_bf16 v[38:41], v[146:149], v[204:207], v[38:41]
	v_mfma_f32_16x16x32_bf16 v[50:53], v[138:141], v[212:215], v[50:53]
	v_mfma_f32_16x16x32_bf16 v[66:69], v[146:149], v[212:215], v[66:69]
	v_mfma_f32_16x16x32_bf16 v[26:29], v[142:145], v[192:195], v[26:29]
	v_mfma_f32_16x16x32_bf16 v[54:57], v[158:161], v[192:195], v[54:57]
	v_mfma_f32_16x16x32_bf16 v[98:101], v[142:145], v[200:203], v[98:101]
	v_mfma_f32_16x16x32_bf16 v[118:121], v[158:161], v[200:203], v[118:121]
	v_mfma_f32_16x16x32_bf16 v[126:129], v[142:145], v[208:211], v[126:129]
	v_mfma_f32_16x16x32_bf16 v[38:41], v[158:161], v[208:211], v[38:41]
	v_mfma_f32_16x16x32_bf16 v[50:53], v[142:145], v[216:219], v[50:53]
	v_mfma_f32_16x16x32_bf16 v[66:69], v[158:161], v[216:219], v[66:69]
	s_setprio 0
	s_setprio 1
	v_mfma_f32_16x16x32_bf16 v[74:77], v[162:165], v[188:191], v[74:77]
	v_mfma_f32_16x16x32_bf16 v[62:65], v[170:173], v[188:191], v[62:65]
	v_mfma_f32_16x16x32_bf16 v[42:45], v[162:165], v[196:199], v[42:45]
	v_mfma_f32_16x16x32_bf16 v[30:33], v[170:173], v[196:199], v[30:33]
	v_mfma_f32_16x16x32_bf16 v[34:37], v[162:165], v[204:207], v[34:37]
	v_mfma_f32_16x16x32_bf16 v[46:49], v[170:173], v[204:207], v[46:49]
	v_mfma_f32_16x16x32_bf16 v[58:61], v[162:165], v[212:215], v[58:61]
	v_mfma_f32_16x16x32_bf16 v[70:73], v[170:173], v[212:215], v[70:73]
	v_mfma_f32_16x16x32_bf16 v[74:77], v[166:169], v[192:195], v[74:77]
	v_mfma_f32_16x16x32_bf16 v[62:65], v[174:177], v[192:195], v[62:65]
	v_mfma_f32_16x16x32_bf16 v[42:45], v[166:169], v[200:203], v[42:45]
	v_mfma_f32_16x16x32_bf16 v[30:33], v[174:177], v[200:203], v[30:33]
	v_mfma_f32_16x16x32_bf16 v[34:37], v[166:169], v[208:211], v[34:37]
	v_mfma_f32_16x16x32_bf16 v[46:49], v[174:177], v[208:211], v[46:49]
	v_mfma_f32_16x16x32_bf16 v[58:61], v[166:169], v[216:219], v[58:61]
	v_mfma_f32_16x16x32_bf16 v[70:73], v[174:177], v[216:219], v[70:73]
	s_setprio 0
	s_barrier
	s_mov_b32 m0, s63
	v_lshl_add_u64 v[178:179], v[178:179], 0, s[10:11]
	s_add_u32 s14, s14, 0x80080
	ds_read_b128 v[188:191], v134 offset:49152
	ds_read_b128 v[192:195], v134 offset:50176
	ds_read_b128 v[196:199], v134 offset:51200
	ds_read_b128 v[200:203], v134 offset:52224
	ds_read_b128 v[204:207], v134 offset:53248
	ds_read_b128 v[208:211], v134 offset:54272
	ds_read_b128 v[212:215], v134 offset:55296
	ds_read_b128 v[216:219], v134 offset:56320
	global_load_lds_dwordx4 v[178:179], off
	v_lshl_add_u64 v[178:179], v[220:221], 0, s[10:11]
	s_mov_b32 m0, s66
	s_addc_u32 s15, s15, 0
	global_load_lds_dwordx4 v[178:179], off
	v_lshl_add_u64 v[178:179], s[14:15], 0, v[152:153]
	s_mov_b32 m0, s67
	s_nop 0
	global_load_lds_dwordx4 v[178:179], off
	v_lshl_add_u64 v[178:179], s[14:15], 0, v[156:157]
	s_mov_b32 m0, s68
	s_nop 0
	global_load_lds_dwordx4 v[178:179], off
	v_lshl_add_u64 v[178:179], v[222:223], 0, s[10:11]
	s_mov_b32 m0, s34
	s_nop 0
	global_load_lds_dwordx4 v[178:179], off
	v_lshl_add_u64 v[178:179], v[224:225], 0, s[10:11]
	s_mov_b32 m0, s35
	s_nop 0
	global_load_lds_dwordx4 v[178:179], off
	s_waitcnt vmcnt(8)
	s_waitcnt lgkmcnt(0)
	s_barrier
	s_setprio 1
	s_waitcnt lgkmcnt(0)
	v_mfma_f32_16x16x32_bf16 v[94:97], v[138:141], v[188:191], v[94:97]
	v_mfma_f32_16x16x32_bf16 v[114:117], v[146:149], v[188:191], v[114:117]
	v_mfma_f32_16x16x32_bf16 v[122:125], v[138:141], v[196:199], v[122:125]
	v_mfma_f32_16x16x32_bf16 v[110:113], v[146:149], v[196:199], v[110:113]
	v_mfma_f32_16x16x32_bf16 v[130:133], v[138:141], v[204:207], v[130:133]
	v_mfma_f32_16x16x32_bf16 v[86:89], v[146:149], v[204:207], v[86:89]
	v_mfma_f32_16x16x32_bf16 v[18:21], v[138:141], v[212:215], v[18:21]
	v_mfma_f32_16x16x32_bf16 v[10:13], v[146:149], v[212:215], v[10:13]
	v_mfma_f32_16x16x32_bf16 v[94:97], v[142:145], v[192:195], v[94:97]
	v_mfma_f32_16x16x32_bf16 v[114:117], v[158:161], v[192:195], v[114:117]
	v_mfma_f32_16x16x32_bf16 v[122:125], v[142:145], v[200:203], v[122:125]
	v_mfma_f32_16x16x32_bf16 v[110:113], v[158:161], v[200:203], v[110:113]
	v_mfma_f32_16x16x32_bf16 v[130:133], v[142:145], v[208:211], v[130:133]
	v_mfma_f32_16x16x32_bf16 v[86:89], v[158:161], v[208:211], v[86:89]
	v_mfma_f32_16x16x32_bf16 v[18:21], v[142:145], v[216:219], v[18:21]
	v_mfma_f32_16x16x32_bf16 v[10:13], v[158:161], v[216:219], v[10:13]
	s_setprio 0
	s_setprio 1
	v_mfma_f32_16x16x32_bf16 v[106:109], v[162:165], v[188:191], v[106:109]
	v_mfma_f32_16x16x32_bf16 v[90:93], v[170:173], v[188:191], v[90:93]
	v_mfma_f32_16x16x32_bf16 v[102:105], v[162:165], v[196:199], v[102:105]
	v_mfma_f32_16x16x32_bf16 v[78:81], v[170:173], v[196:199], v[78:81]
	v_mfma_f32_16x16x32_bf16 v[22:25], v[162:165], v[204:207], v[22:25]
	v_mfma_f32_16x16x32_bf16 v[14:17], v[170:173], v[204:207], v[14:17]
	v_mfma_f32_16x16x32_bf16 v[6:9], v[162:165], v[212:215], v[6:9]
	v_mfma_f32_16x16x32_bf16 v[2:5], v[170:173], v[212:215], v[2:5]
	v_mfma_f32_16x16x32_bf16 v[106:109], v[166:169], v[192:195], v[106:109]
	v_mfma_f32_16x16x32_bf16 v[90:93], v[174:177], v[192:195], v[90:93]
	v_mfma_f32_16x16x32_bf16 v[102:105], v[166:169], v[200:203], v[102:105]
	v_mfma_f32_16x16x32_bf16 v[78:81], v[174:177], v[200:203], v[78:81]
	v_mfma_f32_16x16x32_bf16 v[22:25], v[166:169], v[208:211], v[22:25]
	v_mfma_f32_16x16x32_bf16 v[14:17], v[174:177], v[208:211], v[14:17]
	v_mfma_f32_16x16x32_bf16 v[6:9], v[166:169], v[216:219], v[6:9]
	v_mfma_f32_16x16x32_bf16 v[2:5], v[174:177], v[216:219], v[2:5]
	s_setprio 0
	s_add_i32 s56, s56, 2
	s_cmp_gt_u32 s56, 29
	s_barrier
	s_cbranch_scc0 .LBB0_1322
	s_cmpk_lt_u32 s48, 0x100
	s_cbranch_scc0 .LBB0_1325
	s_barrier

.LBB0_1374:
	s_add_u32 s26, s8, s12
	s_addc_u32 s27, s9, s13
	s_add_u32 s12, s12, 0x100
	ds_read_b128 v[138:141], v84
	ds_read_b128 v[142:145], v84 offset:1024
	ds_read_b128 v[146:149], v84 offset:2048
	ds_read_b128 v[158:161], v84 offset:3072
	ds_read_b128 v[162:165], v85
	ds_read_b128 v[166:169], v85 offset:1024
	ds_read_b128 v[170:173], v85 offset:2048
	ds_read_b128 v[174:177], v85 offset:3072
	s_addc_u32 s13, s13, 0
	v_cmp_lt_u64_e32 vcc, s[12:13], v[82:83]
	s_and_b64 s[14:15], vcc, exec
	s_cselect_b32 s15, 0, 0xfffff000
	s_cselect_b32 s14, 0, -1
	s_add_u32 s12, s15, s12
	s_addc_u32 s13, s14, s13
	s_cmp_lg_u32 s56, 28
	s_cselect_b32 s14, s12, 0
	s_cselect_b32 s15, s13, 0
	s_add_u32 s16, s8, s14
	s_addc_u32 s17, s9, s15
	s_add_u32 s14, s0, s14
	s_addc_u32 s15, s1, s15
	s_add_u32 s26, s26, 0x80080
	s_addc_u32 s27, s27, 0
	s_mov_b32 m0, s57
	v_lshl_add_u64 v[178:179], s[26:27], 0, v[150:151]
	ds_read_b128 v[188:191], v134
	ds_read_b128 v[192:195], v134 offset:1024
	ds_read_b128 v[196:199], v134 offset:2048
	ds_read_b128 v[200:203], v134 offset:3072
	ds_read_b128 v[204:207], v134 offset:4096
	ds_read_b128 v[208:211], v134 offset:5120
	ds_read_b128 v[212:215], v134 offset:6144
	ds_read_b128 v[216:219], v134 offset:7168
	global_load_lds_dwordx4 v[178:179], off
	v_lshl_add_u64 v[178:179], s[26:27], 0, v[154:155]
	s_mov_b32 m0, s58
	s_nop 0
	global_load_lds_dwordx4 v[178:179], off
	s_waitcnt vmcnt(8)
	s_waitcnt lgkmcnt(0)
	s_barrier
	s_setprio 1
	s_waitcnt lgkmcnt(0)
	v_mfma_f32_16x16x32_bf16 v[26:29], v[138:141], v[188:191], v[26:29]
	v_mfma_f32_16x16x32_bf16 v[54:57], v[146:149], v[188:191], v[54:57]
	v_mfma_f32_16x16x32_bf16 v[98:101], v[138:141], v[196:199], v[98:101]
	v_mfma_f32_16x16x32_bf16 v[118:121], v[146:149], v[196:199], v[118:121]
	v_mfma_f32_16x16x32_bf16 v[126:129], v[138:141], v[204:207], v[126:129]
	v_mfma_f32_16x16x32_bf16 v[38:41], v[146:149], v[204:207], v[38:41]
	v_mfma_f32_16x16x32_bf16 v[50:53], v[138:141], v[212:215], v[50:53]
	v_mfma_f32_16x16x32_bf16 v[66:69], v[146:149], v[212:215], v[66:69]
	v_mfma_f32_16x16x32_bf16 v[26:29], v[142:145], v[192:195], v[26:29]
	v_mfma_f32_16x16x32_bf16 v[54:57], v[158:161], v[192:195], v[54:57]
	v_mfma_f32_16x16x32_bf16 v[98:101], v[142:145], v[200:203], v[98:101]
	v_mfma_f32_16x16x32_bf16 v[118:121], v[158:161], v[200:203], v[118:121]
	v_mfma_f32_16x16x32_bf16 v[126:129], v[142:145], v[208:211], v[126:129]
	v_mfma_f32_16x16x32_bf16 v[38:41], v[158:161], v[208:211], v[38:41]
	v_mfma_f32_16x16x32_bf16 v[50:53], v[142:145], v[216:219], v[50:53]
	v_mfma_f32_16x16x32_bf16 v[66:69], v[158:161], v[216:219], v[66:69]
	s_setprio 0
	s_setprio 1
	v_mfma_f32_16x16x32_bf16 v[74:77], v[162:165], v[188:191], v[74:77]
	v_mfma_f32_16x16x32_bf16 v[62:65], v[170:173], v[188:191], v[62:65]
	v_mfma_f32_16x16x32_bf16 v[42:45], v[162:165], v[196:199], v[42:45]
	v_mfma_f32_16x16x32_bf16 v[30:33], v[170:173], v[196:199], v[30:33]
	v_mfma_f32_16x16x32_bf16 v[34:37], v[162:165], v[204:207], v[34:37]
	v_mfma_f32_16x16x32_bf16 v[46:49], v[170:173], v[204:207], v[46:49]
	v_mfma_f32_16x16x32_bf16 v[58:61], v[162:165], v[212:215], v[58:61]
	v_mfma_f32_16x16x32_bf16 v[70:73], v[170:173], v[212:215], v[70:73]
	v_mfma_f32_16x16x32_bf16 v[74:77], v[166:169], v[192:195], v[74:77]
	v_mfma_f32_16x16x32_bf16 v[62:65], v[174:177], v[192:195], v[62:65]
	v_mfma_f32_16x16x32_bf16 v[42:45], v[166:169], v[200:203], v[42:45]
	v_mfma_f32_16x16x32_bf16 v[30:33], v[174:177], v[200:203], v[30:33]
	v_mfma_f32_16x16x32_bf16 v[34:37], v[166:169], v[208:211], v[34:37]
	v_mfma_f32_16x16x32_bf16 v[46:49], v[174:177], v[208:211], v[46:49]
	v_mfma_f32_16x16x32_bf16 v[58:61], v[166:169], v[216:219], v[58:61]
	v_mfma_f32_16x16x32_bf16 v[70:73], v[174:177], v[216:219], v[70:73]
	s_setprio 0
	s_barrier
	s_mov_b32 m0, s59
	v_lshl_add_u64 v[178:179], s[14:15], 0, v[152:153]
	s_add_u32 s26, s14, 0x80000
	ds_read_b128 v[188:191], v134 offset:16384
	ds_read_b128 v[192:195], v134 offset:17408
	ds_read_b128 v[196:199], v134 offset:18432
	ds_read_b128 v[200:203], v134 offset:19456
	ds_read_b128 v[204:207], v134 offset:20480
	ds_read_b128 v[208:211], v134 offset:21504
	ds_read_b128 v[212:215], v134 offset:22528
	ds_read_b128 v[216:219], v134 offset:23552
	global_load_lds_dwordx4 v[178:179], off
	v_lshl_add_u64 v[184:185], s[14:15], 0, v[156:157]
	s_mov_b32 m0, s60
	s_addc_u32 s27, s15, 0
	global_load_lds_dwordx4 v[184:185], off
	v_lshl_add_u64 v[220:221], s[26:27], 0, v[152:153]
	s_mov_b32 m0, s61
	v_lshl_add_u64 v[222:223], s[16:17], 0, v[154:155]
	global_load_lds_dwordx4 v[220:221], off
	v_lshl_add_u64 v[220:221], s[26:27], 0, v[156:157]
	s_mov_b32 m0, s62
	s_nop 0
	global_load_lds_dwordx4 v[220:221], off
	v_lshl_add_u64 v[220:221], s[16:17], 0, v[150:151]
	s_mov_b32 m0, s51
	s_nop 0
	global_load_lds_dwordx4 v[220:221], off
	s_mov_b32 m0, s52
	s_nop 0
	global_load_lds_dwordx4 v[222:223], off
	s_waitcnt vmcnt(8)
	s_waitcnt lgkmcnt(0)
	s_barrier
	s_setprio 1
	s_waitcnt lgkmcnt(0)
	v_mfma_f32_16x16x32_bf16 v[94:97], v[138:141], v[188:191], v[94:97]
	v_mfma_f32_16x16x32_bf16 v[114:117], v[146:149], v[188:191], v[114:117]
	v_mfma_f32_16x16x32_bf16 v[122:125], v[138:141], v[196:199], v[122:125]
	v_mfma_f32_16x16x32_bf16 v[110:113], v[146:149], v[196:199], v[110:113]
	v_mfma_f32_16x16x32_bf16 v[130:133], v[138:141], v[204:207], v[130:133]
	v_mfma_f32_16x16x32_bf16 v[86:89], v[146:149], v[204:207], v[86:89]
	v_mfma_f32_16x16x32_bf16 v[18:21], v[138:141], v[212:215], v[18:21]
	v_mfma_f32_16x16x32_bf16 v[10:13], v[146:149], v[212:215], v[10:13]
	v_mfma_f32_16x16x32_bf16 v[94:97], v[142:145], v[192:195], v[94:97]
	v_mfma_f32_16x16x32_bf16 v[114:117], v[158:161], v[192:195], v[114:117]
	v_mfma_f32_16x16x32_bf16 v[122:125], v[142:145], v[200:203], v[122:125]
	v_mfma_f32_16x16x32_bf16 v[110:113], v[158:161], v[200:203], v[110:113]
	v_mfma_f32_16x16x32_bf16 v[130:133], v[142:145], v[208:211], v[130:133]
	v_mfma_f32_16x16x32_bf16 v[86:89], v[158:161], v[208:211], v[86:89]
	v_mfma_f32_16x16x32_bf16 v[18:21], v[142:145], v[216:219], v[18:21]
	v_mfma_f32_16x16x32_bf16 v[10:13], v[158:161], v[216:219], v[10:13]
	s_setprio 0
	s_setprio 1
	v_mfma_f32_16x16x32_bf16 v[106:109], v[162:165], v[188:191], v[106:109]
	v_mfma_f32_16x16x32_bf16 v[90:93], v[170:173], v[188:191], v[90:93]
	v_mfma_f32_16x16x32_bf16 v[102:105], v[162:165], v[196:199], v[102:105]
	v_mfma_f32_16x16x32_bf16 v[78:81], v[170:173], v[196:199], v[78:81]
	v_mfma_f32_16x16x32_bf16 v[22:25], v[162:165], v[204:207], v[22:25]
	v_mfma_f32_16x16x32_bf16 v[14:17], v[170:173], v[204:207], v[14:17]
	v_mfma_f32_16x16x32_bf16 v[6:9], v[162:165], v[212:215], v[6:9]
	v_mfma_f32_16x16x32_bf16 v[2:5], v[170:173], v[212:215], v[2:5]
	v_mfma_f32_16x16x32_bf16 v[106:109], v[166:169], v[192:195], v[106:109]
	v_mfma_f32_16x16x32_bf16 v[90:93], v[174:177], v[192:195], v[90:93]
	v_mfma_f32_16x16x32_bf16 v[102:105], v[166:169], v[200:203], v[102:105]
	v_mfma_f32_16x16x32_bf16 v[78:81], v[174:177], v[200:203], v[78:81]
	v_mfma_f32_16x16x32_bf16 v[22:25], v[166:169], v[208:211], v[22:25]
	v_mfma_f32_16x16x32_bf16 v[14:17], v[174:177], v[208:211], v[14:17]
	v_mfma_f32_16x16x32_bf16 v[6:9], v[166:169], v[216:219], v[6:9]
	v_mfma_f32_16x16x32_bf16 v[2:5], v[174:177], v[216:219], v[2:5]
	s_setprio 0
	s_barrier
	ds_read_b128 v[138:141], v135
	ds_read_b128 v[142:145], v135 offset:1024
	ds_read_b128 v[146:149], v135 offset:2048
	ds_read_b128 v[158:161], v135 offset:3072
	ds_read_b128 v[162:165], v136
	ds_read_b128 v[166:169], v136 offset:1024
	ds_read_b128 v[170:173], v136 offset:2048
	ds_read_b128 v[174:177], v136 offset:3072
	s_add_u32 s16, s16, 0x80000
	s_addc_u32 s17, s17, 0
	s_mov_b32 m0, s53
	v_lshl_add_u64 v[224:225], s[16:17], 0, v[150:151]
	ds_read_b128 v[188:191], v134 offset:32768
	ds_read_b128 v[192:195], v134 offset:33792
	ds_read_b128 v[196:199], v134 offset:34816
	ds_read_b128 v[200:203], v134 offset:35840
	ds_read_b128 v[204:207], v134 offset:36864
	ds_read_b128 v[208:211], v134 offset:37888
	ds_read_b128 v[212:215], v134 offset:38912
	ds_read_b128 v[216:219], v134 offset:39936
	global_load_lds_dwordx4 v[224:225], off
	v_lshl_add_u64 v[224:225], s[16:17], 0, v[154:155]
	s_mov_b32 m0, s54
	s_nop 0
	global_load_lds_dwordx4 v[224:225], off
	s_waitcnt vmcnt(8)
	s_waitcnt lgkmcnt(0)
	s_barrier
	s_setprio 1
	s_waitcnt lgkmcnt(0)
	v_mfma_f32_16x16x32_bf16 v[26:29], v[138:141], v[188:191], v[26:29]
	v_mfma_f32_16x16x32_bf16 v[54:57], v[146:149], v[188:191], v[54:57]
	v_mfma_f32_16x16x32_bf16 v[98:101], v[138:141], v[196:199], v[98:101]
	v_mfma_f32_16x16x32_bf16 v[118:121], v[146:149], v[196:199], v[118:121]
	v_mfma_f32_16x16x32_bf16 v[126:129], v[138:141], v[204:207], v[126:129]
	v_mfma_f32_16x16x32_bf16 v[38:41], v[146:149], v[204:207], v[38:41]
	v_mfma_f32_16x16x32_bf16 v[50:53], v[138:141], v[212:215], v[50:53]
	v_mfma_f32_16x16x32_bf16 v[66:69], v[146:149], v[212:215], v[66:69]
	v_mfma_f32_16x16x32_bf16 v[26:29], v[142:145], v[192:195], v[26:29]
	v_mfma_f32_16x16x32_bf16 v[54:57], v[158:161], v[192:195], v[54:57]
	v_mfma_f32_16x16x32_bf16 v[98:101], v[142:145], v[200:203], v[98:101]
	v_mfma_f32_16x16x32_bf16 v[118:121], v[158:161], v[200:203], v[118:121]
	v_mfma_f32_16x16x32_bf16 v[126:129], v[142:145], v[208:211], v[126:129]
	v_mfma_f32_16x16x32_bf16 v[38:41], v[158:161], v[208:211], v[38:41]
	v_mfma_f32_16x16x32_bf16 v[50:53], v[142:145], v[216:219], v[50:53]
	v_mfma_f32_16x16x32_bf16 v[66:69], v[158:161], v[216:219], v[66:69]
	s_setprio 0
	s_setprio 1
	v_mfma_f32_16x16x32_bf16 v[74:77], v[162:165], v[188:191], v[74:77]
	v_mfma_f32_16x16x32_bf16 v[62:65], v[170:173], v[188:191], v[62:65]
	v_mfma_f32_16x16x32_bf16 v[42:45], v[162:165], v[196:199], v[42:45]
	v_mfma_f32_16x16x32_bf16 v[30:33], v[170:173], v[196:199], v[30:33]
	v_mfma_f32_16x16x32_bf16 v[34:37], v[162:165], v[204:207], v[34:37]
	v_mfma_f32_16x16x32_bf16 v[46:49], v[170:173], v[204:207], v[46:49]
	v_mfma_f32_16x16x32_bf16 v[58:61], v[162:165], v[212:215], v[58:61]
	v_mfma_f32_16x16x32_bf16 v[70:73], v[170:173], v[212:215], v[70:73]
	v_mfma_f32_16x16x32_bf16 v[74:77], v[166:169], v[192:195], v[74:77]
	v_mfma_f32_16x16x32_bf16 v[62:65], v[174:177], v[192:195], v[62:65]
	v_mfma_f32_16x16x32_bf16 v[42:45], v[166:169], v[200:203], v[42:45]
	v_mfma_f32_16x16x32_bf16 v[30:33], v[174:177], v[200:203], v[30:33]
	v_mfma_f32_16x16x32_bf16 v[34:37], v[166:169], v[208:211], v[34:37]
	v_mfma_f32_16x16x32_bf16 v[46:49], v[174:177], v[208:211], v[46:49]
	v_mfma_f32_16x16x32_bf16 v[58:61], v[166:169], v[216:219], v[58:61]
	v_mfma_f32_16x16x32_bf16 v[70:73], v[174:177], v[216:219], v[70:73]
	s_setprio 0
	s_barrier
	s_mov_b32 m0, s63
	v_lshl_add_u64 v[178:179], v[178:179], 0, s[10:11]
	s_add_u32 s14, s14, 0x80080
	ds_read_b128 v[188:191], v134 offset:49152
	ds_read_b128 v[192:195], v134 offset:50176
	ds_read_b128 v[196:199], v134 offset:51200
	ds_read_b128 v[200:203], v134 offset:52224
	ds_read_b128 v[204:207], v134 offset:53248
	ds_read_b128 v[208:211], v134 offset:54272
	ds_read_b128 v[212:215], v134 offset:55296
	ds_read_b128 v[216:219], v134 offset:56320
	global_load_lds_dwordx4 v[178:179], off
	v_lshl_add_u64 v[178:179], v[184:185], 0, s[10:11]
	s_mov_b32 m0, s66
	s_addc_u32 s15, s15, 0
	global_load_lds_dwordx4 v[178:179], off
	v_lshl_add_u64 v[178:179], s[14:15], 0, v[152:153]
	s_mov_b32 m0, s67
	s_nop 0
	global_load_lds_dwordx4 v[178:179], off
	v_lshl_add_u64 v[178:179], s[14:15], 0, v[156:157]
	s_mov_b32 m0, s68
	s_nop 0
	global_load_lds_dwordx4 v[178:179], off
	v_lshl_add_u64 v[178:179], v[220:221], 0, s[10:11]
	s_mov_b32 m0, s34
	s_nop 0
	global_load_lds_dwordx4 v[178:179], off
	v_lshl_add_u64 v[178:179], v[222:223], 0, s[10:11]
	s_mov_b32 m0, s35
	s_nop 0
	global_load_lds_dwordx4 v[178:179], off
	s_waitcnt vmcnt(8)
	s_waitcnt lgkmcnt(0)
	s_barrier
	s_setprio 1
	s_waitcnt lgkmcnt(0)
	v_mfma_f32_16x16x32_bf16 v[94:97], v[138:141], v[188:191], v[94:97]
	v_mfma_f32_16x16x32_bf16 v[114:117], v[146:149], v[188:191], v[114:117]
	v_mfma_f32_16x16x32_bf16 v[122:125], v[138:141], v[196:199], v[122:125]
	v_mfma_f32_16x16x32_bf16 v[110:113], v[146:149], v[196:199], v[110:113]
	v_mfma_f32_16x16x32_bf16 v[130:133], v[138:141], v[204:207], v[130:133]
	v_mfma_f32_16x16x32_bf16 v[86:89], v[146:149], v[204:207], v[86:89]
	v_mfma_f32_16x16x32_bf16 v[18:21], v[138:141], v[212:215], v[18:21]
	v_mfma_f32_16x16x32_bf16 v[10:13], v[146:149], v[212:215], v[10:13]
	v_mfma_f32_16x16x32_bf16 v[94:97], v[142:145], v[192:195], v[94:97]
	v_mfma_f32_16x16x32_bf16 v[114:117], v[158:161], v[192:195], v[114:117]
	v_mfma_f32_16x16x32_bf16 v[122:125], v[142:145], v[200:203], v[122:125]
	v_mfma_f32_16x16x32_bf16 v[110:113], v[158:161], v[200:203], v[110:113]
	v_mfma_f32_16x16x32_bf16 v[130:133], v[142:145], v[208:211], v[130:133]
	v_mfma_f32_16x16x32_bf16 v[86:89], v[158:161], v[208:211], v[86:89]
	v_mfma_f32_16x16x32_bf16 v[18:21], v[142:145], v[216:219], v[18:21]
	v_mfma_f32_16x16x32_bf16 v[10:13], v[158:161], v[216:219], v[10:13]
	s_setprio 0
	s_setprio 1
	v_mfma_f32_16x16x32_bf16 v[106:109], v[162:165], v[188:191], v[106:109]
	v_mfma_f32_16x16x32_bf16 v[90:93], v[170:173], v[188:191], v[90:93]
	v_mfma_f32_16x16x32_bf16 v[102:105], v[162:165], v[196:199], v[102:105]
	v_mfma_f32_16x16x32_bf16 v[78:81], v[170:173], v[196:199], v[78:81]
	v_mfma_f32_16x16x32_bf16 v[22:25], v[162:165], v[204:207], v[22:25]
	v_mfma_f32_16x16x32_bf16 v[14:17], v[170:173], v[204:207], v[14:17]
	v_mfma_f32_16x16x32_bf16 v[6:9], v[162:165], v[212:215], v[6:9]
	v_mfma_f32_16x16x32_bf16 v[2:5], v[170:173], v[212:215], v[2:5]
	v_mfma_f32_16x16x32_bf16 v[106:109], v[166:169], v[192:195], v[106:109]
	v_mfma_f32_16x16x32_bf16 v[90:93], v[174:177], v[192:195], v[90:93]
	v_mfma_f32_16x16x32_bf16 v[102:105], v[166:169], v[200:203], v[102:105]
	v_mfma_f32_16x16x32_bf16 v[78:81], v[174:177], v[200:203], v[78:81]
	v_mfma_f32_16x16x32_bf16 v[22:25], v[166:169], v[208:211], v[22:25]
	v_mfma_f32_16x16x32_bf16 v[14:17], v[174:177], v[208:211], v[14:17]
	v_mfma_f32_16x16x32_bf16 v[6:9], v[166:169], v[216:219], v[6:9]
	v_mfma_f32_16x16x32_bf16 v[2:5], v[174:177], v[216:219], v[2:5]
	s_setprio 0
	s_add_i32 s56, s56, 2
	s_cmp_gt_u32 s56, 29
	s_barrier
	s_cbranch_scc0 .LBB0_1374
	s_cmpk_lt_u32 s48, 0x100
	s_cbranch_scc0 .LBB0_1377
	s_barrier

.LBB0_1564:
	s_add_u32 s26, s22, 0x100
	s_addc_u32 s27, s23, 0
	s_add_u32 s46, s22, 0xfffff100
	ds_read_b128 v[150:153], v146
	ds_read_b128 v[154:157], v146 offset:1024
	ds_read_b128 v[158:161], v146 offset:2048
	ds_read_b128 v[162:165], v146 offset:3072
	ds_read_b128 v[166:169], v147
	ds_read_b128 v[170:173], v147 offset:1024
	ds_read_b128 v[174:177], v147 offset:2048
	ds_read_b128 v[178:181], v147 offset:3072
	v_cmp_gt_u64_e32 vcc, s[26:27], v[142:143]
	s_addc_u32 s47, s23, -1
	s_and_b64 s[44:45], vcc, exec
	s_cselect_b32 s44, s46, s26
	s_cselect_b32 s45, s47, s27
	s_add_u32 s26, s20, s44
	s_addc_u32 s27, s21, s45
	s_add_u32 s46, s18, s44
	s_addc_u32 s47, s19, s45
	s_cmp_eq_u32 s67, 28
	s_cselect_b32 s49, s11, s27
	s_cselect_b32 s48, s34, s26
	s_cselect_b32 s47, s9, s47
	s_cselect_b32 s46, s35, s46
	s_add_u32 s22, s20, s22
	s_addc_u32 s23, s21, s23
	s_add_u32 s22, s22, 0x80080
	s_addc_u32 s23, s23, 0
	v_lshl_add_u64 v[214:215], s[22:23], 0, v[130:131]
	s_add_i32 m0, s17, 0xc000
	ds_read_b128 v[182:185], v148
	ds_read_b128 v[186:189], v148 offset:1024
	ds_read_b128 v[190:193], v148 offset:2048
	ds_read_b128 v[194:197], v148 offset:3072
	ds_read_b128 v[198:201], v148 offset:4096
	ds_read_b128 v[202:205], v148 offset:5120
	ds_read_b128 v[206:209], v148 offset:6144
	ds_read_b128 v[210:213], v148 offset:7168
	global_load_lds_dwordx4 v[214:215], off
	v_lshl_add_u64 v[214:215], s[22:23], 0, v[134:135]
	s_add_i32 m0, s17, 0xe000
	s_nop 0
	global_load_lds_dwordx4 v[214:215], off
	s_waitcnt vmcnt(8)
	s_waitcnt lgkmcnt(0)
	s_barrier
	s_setprio 1
	s_waitcnt lgkmcnt(0)
	v_mfma_f32_16x16x32_bf16 v[126:129], v[150:153], v[182:185], v[126:129]
	v_mfma_f32_16x16x32_bf16 v[118:121], v[158:161], v[182:185], v[118:121]
	v_mfma_f32_16x16x32_bf16 v[110:113], v[150:153], v[190:193], v[110:113]
	v_mfma_f32_16x16x32_bf16 v[102:105], v[158:161], v[190:193], v[102:105]
	v_mfma_f32_16x16x32_bf16 v[94:97], v[150:153], v[198:201], v[94:97]
	v_mfma_f32_16x16x32_bf16 v[86:89], v[158:161], v[198:201], v[86:89]
	v_mfma_f32_16x16x32_bf16 v[78:81], v[150:153], v[206:209], v[78:81]
	v_mfma_f32_16x16x32_bf16 v[70:73], v[158:161], v[206:209], v[70:73]
	v_mfma_f32_16x16x32_bf16 v[126:129], v[154:157], v[186:189], v[126:129]
	v_mfma_f32_16x16x32_bf16 v[118:121], v[162:165], v[186:189], v[118:121]
	v_mfma_f32_16x16x32_bf16 v[110:113], v[154:157], v[194:197], v[110:113]
	v_mfma_f32_16x16x32_bf16 v[102:105], v[162:165], v[194:197], v[102:105]
	v_mfma_f32_16x16x32_bf16 v[94:97], v[154:157], v[202:205], v[94:97]
	v_mfma_f32_16x16x32_bf16 v[86:89], v[162:165], v[202:205], v[86:89]
	v_mfma_f32_16x16x32_bf16 v[78:81], v[154:157], v[210:213], v[78:81]
	v_mfma_f32_16x16x32_bf16 v[70:73], v[162:165], v[210:213], v[70:73]
	s_setprio 0
	s_setprio 1
	v_mfma_f32_16x16x32_bf16 v[122:125], v[166:169], v[182:185], v[122:125]
	v_mfma_f32_16x16x32_bf16 v[114:117], v[174:177], v[182:185], v[114:117]
	v_mfma_f32_16x16x32_bf16 v[106:109], v[166:169], v[190:193], v[106:109]
	v_mfma_f32_16x16x32_bf16 v[98:101], v[174:177], v[190:193], v[98:101]
	v_mfma_f32_16x16x32_bf16 v[90:93], v[166:169], v[198:201], v[90:93]
	v_mfma_f32_16x16x32_bf16 v[82:85], v[174:177], v[198:201], v[82:85]
	v_mfma_f32_16x16x32_bf16 v[74:77], v[166:169], v[206:209], v[74:77]
	v_mfma_f32_16x16x32_bf16 v[66:69], v[174:177], v[206:209], v[66:69]
	v_mfma_f32_16x16x32_bf16 v[122:125], v[170:173], v[186:189], v[122:125]
	v_mfma_f32_16x16x32_bf16 v[114:117], v[178:181], v[186:189], v[114:117]
	v_mfma_f32_16x16x32_bf16 v[106:109], v[170:173], v[194:197], v[106:109]
	v_mfma_f32_16x16x32_bf16 v[98:101], v[178:181], v[194:197], v[98:101]
	v_mfma_f32_16x16x32_bf16 v[90:93], v[170:173], v[202:205], v[90:93]
	v_mfma_f32_16x16x32_bf16 v[82:85], v[178:181], v[202:205], v[82:85]
	v_mfma_f32_16x16x32_bf16 v[74:77], v[170:173], v[210:213], v[74:77]
	v_mfma_f32_16x16x32_bf16 v[66:69], v[178:181], v[210:213], v[66:69]
	s_setprio 0
	s_barrier
	s_add_i32 s22, s61, s52
	v_lshl_add_u64 v[214:215], s[46:47], 0, v[132:133]
	s_mov_b32 m0, s22
	ds_read_b128 v[182:185], v148 offset:16384
	ds_read_b128 v[186:189], v148 offset:17408
	ds_read_b128 v[190:193], v148 offset:18432
	ds_read_b128 v[194:197], v148 offset:19456
	ds_read_b128 v[198:201], v148 offset:20480
	ds_read_b128 v[202:205], v148 offset:21504
	ds_read_b128 v[206:209], v148 offset:22528
	ds_read_b128 v[210:213], v148 offset:23552
	global_load_lds_dwordx4 v[214:215], off
	s_add_i32 m0, s22, 0x2000
	s_add_u32 s22, s46, 0x80000
	v_lshl_add_u64 v[216:217], s[46:47], 0, v[136:137]
	s_addc_u32 s23, s47, 0
	s_add_i32 s26, s62, s52
	global_load_lds_dwordx4 v[216:217], off
	v_lshl_add_u64 v[218:219], s[22:23], 0, v[132:133]
	s_mov_b32 m0, s26
	v_lshl_add_u64 v[220:221], s[48:49], 0, v[134:135]
	global_load_lds_dwordx4 v[218:219], off
	v_lshl_add_u64 v[218:219], s[22:23], 0, v[136:137]
	s_add_i32 m0, s26, 0x2000
	s_nop 0
	global_load_lds_dwordx4 v[218:219], off
	v_lshl_add_u64 v[218:219], s[48:49], 0, v[130:131]
	s_mov_b32 m0, s17
	s_nop 0
	global_load_lds_dwordx4 v[218:219], off
	s_mov_b32 m0, s54
	s_nop 0
	global_load_lds_dwordx4 v[220:221], off
	s_waitcnt vmcnt(8)
	s_waitcnt lgkmcnt(0)
	s_barrier
	s_setprio 1
	s_waitcnt lgkmcnt(0)
	v_mfma_f32_16x16x32_bf16 v[62:65], v[150:153], v[182:185], v[62:65]
	v_mfma_f32_16x16x32_bf16 v[54:57], v[158:161], v[182:185], v[54:57]
	v_mfma_f32_16x16x32_bf16 v[46:49], v[150:153], v[190:193], v[46:49]
	v_mfma_f32_16x16x32_bf16 v[38:41], v[158:161], v[190:193], v[38:41]
	v_mfma_f32_16x16x32_bf16 v[30:33], v[150:153], v[198:201], v[30:33]
	v_mfma_f32_16x16x32_bf16 v[22:25], v[158:161], v[198:201], v[22:25]
	v_mfma_f32_16x16x32_bf16 v[14:17], v[150:153], v[206:209], v[14:17]
	v_mfma_f32_16x16x32_bf16 v[6:9], v[158:161], v[206:209], v[6:9]
	v_mfma_f32_16x16x32_bf16 v[62:65], v[154:157], v[186:189], v[62:65]
	v_mfma_f32_16x16x32_bf16 v[54:57], v[162:165], v[186:189], v[54:57]
	v_mfma_f32_16x16x32_bf16 v[46:49], v[154:157], v[194:197], v[46:49]
	v_mfma_f32_16x16x32_bf16 v[38:41], v[162:165], v[194:197], v[38:41]
	v_mfma_f32_16x16x32_bf16 v[30:33], v[154:157], v[202:205], v[30:33]
	v_mfma_f32_16x16x32_bf16 v[22:25], v[162:165], v[202:205], v[22:25]
	v_mfma_f32_16x16x32_bf16 v[14:17], v[154:157], v[210:213], v[14:17]
	v_mfma_f32_16x16x32_bf16 v[6:9], v[162:165], v[210:213], v[6:9]
	s_setprio 0
	s_setprio 1
	v_mfma_f32_16x16x32_bf16 v[58:61], v[166:169], v[182:185], v[58:61]
	v_mfma_f32_16x16x32_bf16 v[50:53], v[174:177], v[182:185], v[50:53]
	v_mfma_f32_16x16x32_bf16 v[42:45], v[166:169], v[190:193], v[42:45]
	v_mfma_f32_16x16x32_bf16 v[34:37], v[174:177], v[190:193], v[34:37]
	v_mfma_f32_16x16x32_bf16 v[26:29], v[166:169], v[198:201], v[26:29]
	v_mfma_f32_16x16x32_bf16 v[18:21], v[174:177], v[198:201], v[18:21]
	v_mfma_f32_16x16x32_bf16 v[10:13], v[166:169], v[206:209], v[10:13]
	v_mfma_f32_16x16x32_bf16 v[2:5], v[174:177], v[206:209], v[2:5]
	v_mfma_f32_16x16x32_bf16 v[58:61], v[170:173], v[186:189], v[58:61]
	v_mfma_f32_16x16x32_bf16 v[50:53], v[178:181], v[186:189], v[50:53]
	v_mfma_f32_16x16x32_bf16 v[42:45], v[170:173], v[194:197], v[42:45]
	v_mfma_f32_16x16x32_bf16 v[34:37], v[178:181], v[194:197], v[34:37]
	v_mfma_f32_16x16x32_bf16 v[26:29], v[170:173], v[202:205], v[26:29]
	v_mfma_f32_16x16x32_bf16 v[18:21], v[178:181], v[202:205], v[18:21]
	v_mfma_f32_16x16x32_bf16 v[10:13], v[170:173], v[210:213], v[10:13]
	v_mfma_f32_16x16x32_bf16 v[2:5], v[178:181], v[210:213], v[2:5]
	s_setprio 0
	s_barrier
	s_add_i32 s26, 0, 0x18000
	v_add_u32_e32 v149, s26, v144
	s_add_i32 s27, 0, 0x1c000
	ds_read_b128 v[150:153], v149
	ds_read_b128 v[154:157], v149 offset:1024
	ds_read_b128 v[158:161], v149 offset:2048
	ds_read_b128 v[162:165], v149 offset:3072
	v_add_u32_e32 v149, s27, v144
	ds_read_b128 v[166:169], v149
	ds_read_b128 v[170:173], v149 offset:1024
	ds_read_b128 v[174:177], v149 offset:2048
	ds_read_b128 v[178:181], v149 offset:3072
	s_add_u32 s22, s48, 0x80000
	s_addc_u32 s23, s49, 0
	s_mov_b32 m0, s55
	v_lshl_add_u64 v[222:223], s[22:23], 0, v[130:131]
	ds_read_b128 v[182:185], v148 offset:32768
	ds_read_b128 v[186:189], v148 offset:33792
	ds_read_b128 v[190:193], v148 offset:34816
	ds_read_b128 v[194:197], v148 offset:35840
	ds_read_b128 v[198:201], v148 offset:36864
	ds_read_b128 v[202:205], v148 offset:37888
	ds_read_b128 v[206:209], v148 offset:38912
	ds_read_b128 v[210:213], v148 offset:39936
	global_load_lds_dwordx4 v[222:223], off
	v_lshl_add_u64 v[222:223], s[22:23], 0, v[134:135]
	s_mov_b32 m0, s56
	s_nop 0
	global_load_lds_dwordx4 v[222:223], off
	s_waitcnt vmcnt(8)
	s_waitcnt lgkmcnt(0)
	s_barrier
	s_setprio 1
	s_waitcnt lgkmcnt(0)
	v_mfma_f32_16x16x32_bf16 v[126:129], v[150:153], v[182:185], v[126:129]
	v_mfma_f32_16x16x32_bf16 v[118:121], v[158:161], v[182:185], v[118:121]
	v_mfma_f32_16x16x32_bf16 v[110:113], v[150:153], v[190:193], v[110:113]
	v_mfma_f32_16x16x32_bf16 v[102:105], v[158:161], v[190:193], v[102:105]
	v_mfma_f32_16x16x32_bf16 v[94:97], v[150:153], v[198:201], v[94:97]
	v_mfma_f32_16x16x32_bf16 v[86:89], v[158:161], v[198:201], v[86:89]
	v_mfma_f32_16x16x32_bf16 v[78:81], v[150:153], v[206:209], v[78:81]
	v_mfma_f32_16x16x32_bf16 v[70:73], v[158:161], v[206:209], v[70:73]
	v_mfma_f32_16x16x32_bf16 v[126:129], v[154:157], v[186:189], v[126:129]
	v_mfma_f32_16x16x32_bf16 v[118:121], v[162:165], v[186:189], v[118:121]
	v_mfma_f32_16x16x32_bf16 v[110:113], v[154:157], v[194:197], v[110:113]
	v_mfma_f32_16x16x32_bf16 v[102:105], v[162:165], v[194:197], v[102:105]
	v_mfma_f32_16x16x32_bf16 v[94:97], v[154:157], v[202:205], v[94:97]
	v_mfma_f32_16x16x32_bf16 v[86:89], v[162:165], v[202:205], v[86:89]
	v_mfma_f32_16x16x32_bf16 v[78:81], v[154:157], v[210:213], v[78:81]
	v_mfma_f32_16x16x32_bf16 v[70:73], v[162:165], v[210:213], v[70:73]
	s_setprio 0
	s_setprio 1
	v_mfma_f32_16x16x32_bf16 v[122:125], v[166:169], v[182:185], v[122:125]
	v_mfma_f32_16x16x32_bf16 v[114:117], v[174:177], v[182:185], v[114:117]
	v_mfma_f32_16x16x32_bf16 v[106:109], v[166:169], v[190:193], v[106:109]
	v_mfma_f32_16x16x32_bf16 v[98:101], v[174:177], v[190:193], v[98:101]
	v_mfma_f32_16x16x32_bf16 v[90:93], v[166:169], v[198:201], v[90:93]
	v_mfma_f32_16x16x32_bf16 v[82:85], v[174:177], v[198:201], v[82:85]
	v_mfma_f32_16x16x32_bf16 v[74:77], v[166:169], v[206:209], v[74:77]
	v_mfma_f32_16x16x32_bf16 v[66:69], v[174:177], v[206:209], v[66:69]
	v_mfma_f32_16x16x32_bf16 v[122:125], v[170:173], v[186:189], v[122:125]
	v_mfma_f32_16x16x32_bf16 v[114:117], v[178:181], v[186:189], v[114:117]
	v_mfma_f32_16x16x32_bf16 v[106:109], v[170:173], v[194:197], v[106:109]
	v_mfma_f32_16x16x32_bf16 v[98:101], v[178:181], v[194:197], v[98:101]
	v_mfma_f32_16x16x32_bf16 v[90:93], v[170:173], v[202:205], v[90:93]
	v_mfma_f32_16x16x32_bf16 v[82:85], v[178:181], v[202:205], v[82:85]
	v_mfma_f32_16x16x32_bf16 v[74:77], v[170:173], v[210:213], v[74:77]
	v_mfma_f32_16x16x32_bf16 v[66:69], v[178:181], v[210:213], v[66:69]
	s_setprio 0
	s_barrier
	s_add_i32 s22, s26, s52
	v_lshl_add_u64 v[214:215], v[214:215], 0, s[4:5]
	s_mov_b32 m0, s22
	ds_read_b128 v[182:185], v148 offset:49152
	ds_read_b128 v[186:189], v148 offset:50176
	ds_read_b128 v[190:193], v148 offset:51200
	ds_read_b128 v[194:197], v148 offset:52224
	ds_read_b128 v[198:201], v148 offset:53248
	ds_read_b128 v[202:205], v148 offset:54272
	ds_read_b128 v[206:209], v148 offset:55296
	ds_read_b128 v[210:213], v148 offset:56320
	global_load_lds_dwordx4 v[214:215], off
	s_add_i32 m0, s22, 0x2000
	s_add_u32 s22, s46, 0x80080
	v_lshl_add_u64 v[214:215], v[216:217], 0, s[4:5]
	s_addc_u32 s23, s47, 0
	s_add_i32 s26, s27, s52
	global_load_lds_dwordx4 v[214:215], off
	v_lshl_add_u64 v[214:215], s[22:23], 0, v[132:133]
	s_mov_b32 m0, s26
	s_nop 0
	global_load_lds_dwordx4 v[214:215], off
	v_lshl_add_u64 v[214:215], s[22:23], 0, v[136:137]
	s_add_i32 m0, s26, 0x2000
	s_nop 0
	global_load_lds_dwordx4 v[214:215], off
	v_lshl_add_u64 v[214:215], v[218:219], 0, s[4:5]
	s_mov_b32 m0, s59
	s_nop 0
	global_load_lds_dwordx4 v[214:215], off
	v_lshl_add_u64 v[214:215], v[220:221], 0, s[4:5]
	s_mov_b32 m0, s60
	s_nop 0
	global_load_lds_dwordx4 v[214:215], off
	s_waitcnt vmcnt(8)
	s_waitcnt lgkmcnt(0)
	s_barrier
	s_setprio 1
	s_waitcnt lgkmcnt(0)
	v_mfma_f32_16x16x32_bf16 v[62:65], v[150:153], v[182:185], v[62:65]
	v_mfma_f32_16x16x32_bf16 v[54:57], v[158:161], v[182:185], v[54:57]
	v_mfma_f32_16x16x32_bf16 v[46:49], v[150:153], v[190:193], v[46:49]
	v_mfma_f32_16x16x32_bf16 v[38:41], v[158:161], v[190:193], v[38:41]
	v_mfma_f32_16x16x32_bf16 v[30:33], v[150:153], v[198:201], v[30:33]
	v_mfma_f32_16x16x32_bf16 v[22:25], v[158:161], v[198:201], v[22:25]
	v_mfma_f32_16x16x32_bf16 v[14:17], v[150:153], v[206:209], v[14:17]
	v_mfma_f32_16x16x32_bf16 v[6:9], v[158:161], v[206:209], v[6:9]
	v_mfma_f32_16x16x32_bf16 v[62:65], v[154:157], v[186:189], v[62:65]
	v_mfma_f32_16x16x32_bf16 v[54:57], v[162:165], v[186:189], v[54:57]
	v_mfma_f32_16x16x32_bf16 v[46:49], v[154:157], v[194:197], v[46:49]
	v_mfma_f32_16x16x32_bf16 v[38:41], v[162:165], v[194:197], v[38:41]
	v_mfma_f32_16x16x32_bf16 v[30:33], v[154:157], v[202:205], v[30:33]
	v_mfma_f32_16x16x32_bf16 v[22:25], v[162:165], v[202:205], v[22:25]
	v_mfma_f32_16x16x32_bf16 v[14:17], v[154:157], v[210:213], v[14:17]
	v_mfma_f32_16x16x32_bf16 v[6:9], v[162:165], v[210:213], v[6:9]
	s_setprio 0
	s_setprio 1
	v_mfma_f32_16x16x32_bf16 v[58:61], v[166:169], v[182:185], v[58:61]
	v_mfma_f32_16x16x32_bf16 v[50:53], v[174:177], v[182:185], v[50:53]
	v_mfma_f32_16x16x32_bf16 v[42:45], v[166:169], v[190:193], v[42:45]
	v_mfma_f32_16x16x32_bf16 v[34:37], v[174:177], v[190:193], v[34:37]
	v_mfma_f32_16x16x32_bf16 v[26:29], v[166:169], v[198:201], v[26:29]
	v_mfma_f32_16x16x32_bf16 v[18:21], v[174:177], v[198:201], v[18:21]
	v_mfma_f32_16x16x32_bf16 v[10:13], v[166:169], v[206:209], v[10:13]
	v_mfma_f32_16x16x32_bf16 v[2:5], v[174:177], v[206:209], v[2:5]
	v_mfma_f32_16x16x32_bf16 v[58:61], v[170:173], v[186:189], v[58:61]
	v_mfma_f32_16x16x32_bf16 v[50:53], v[178:181], v[186:189], v[50:53]
	v_mfma_f32_16x16x32_bf16 v[42:45], v[170:173], v[194:197], v[42:45]
	v_mfma_f32_16x16x32_bf16 v[34:37], v[178:181], v[194:197], v[34:37]
	v_mfma_f32_16x16x32_bf16 v[26:29], v[170:173], v[202:205], v[26:29]
	v_mfma_f32_16x16x32_bf16 v[18:21], v[178:181], v[202:205], v[18:21]
	v_mfma_f32_16x16x32_bf16 v[10:13], v[170:173], v[210:213], v[10:13]
	v_mfma_f32_16x16x32_bf16 v[2:5], v[178:181], v[210:213], v[2:5]
	s_setprio 0
	s_add_i32 s67, s67, 2
	s_cmp_gt_u32 s67, 29
	s_mov_b64 s[22:23], s[44:45]
	s_barrier
	s_cbranch_scc0 .LBB0_1564
	s_and_b64 vcc, exec, s[6:7]
	s_cbranch_vccz .LBB0_1567
	s_barrier

.LBB0_1638:
	s_add_u32 s26, s8, s12
	s_addc_u32 s27, s9, s13
	s_add_u32 s12, s12, 0x100
	ds_read_b128 v[138:141], v88
	ds_read_b128 v[142:145], v88 offset:1024
	ds_read_b128 v[154:157], v88 offset:2048
	ds_read_b128 v[158:161], v88 offset:3072
	ds_read_b128 v[162:165], v89
	ds_read_b128 v[166:169], v89 offset:1024
	ds_read_b128 v[170:173], v89 offset:2048
	ds_read_b128 v[174:177], v89 offset:3072
	s_addc_u32 s13, s13, 0
	v_cmp_lt_u64_e32 vcc, s[12:13], v[86:87]
	s_and_b64 s[14:15], vcc, exec
	s_cselect_b32 s15, 0, 0xffffd500
	s_cselect_b32 s14, 0, -1
	s_add_u32 s12, s15, s12
	s_addc_u32 s13, s14, s13
	s_cmpk_lg_i32 s56, 0x52
	s_cselect_b32 s14, s12, 0
	s_cselect_b32 s15, s13, 0
	s_add_u32 s16, s8, s14
	s_addc_u32 s17, s9, s15
	s_add_u32 s14, s0, s14
	s_addc_u32 s15, s1, s15
	s_add_u32 s26, s26, 0x158080
	s_addc_u32 s27, s27, 0
	s_mov_b32 m0, s57
	v_lshl_add_u64 v[178:179], s[26:27], 0, v[146:147]
	ds_read_b128 v[188:191], v134
	ds_read_b128 v[192:195], v134 offset:1024
	ds_read_b128 v[196:199], v134 offset:2048
	ds_read_b128 v[200:203], v134 offset:3072
	ds_read_b128 v[204:207], v134 offset:4096
	ds_read_b128 v[208:211], v134 offset:5120
	ds_read_b128 v[212:215], v134 offset:6144
	ds_read_b128 v[216:219], v134 offset:7168
	global_load_lds_dwordx4 v[178:179], off
	v_lshl_add_u64 v[178:179], s[26:27], 0, v[150:151]
	s_mov_b32 m0, s58
	s_nop 0
	global_load_lds_dwordx4 v[178:179], off
	s_waitcnt vmcnt(8)
	s_waitcnt lgkmcnt(0)
	s_barrier
	s_setprio 1
	s_waitcnt lgkmcnt(0)
	v_mfma_f32_16x16x32_bf16 v[30:33], v[138:141], v[188:191], v[30:33]
	v_mfma_f32_16x16x32_bf16 v[58:61], v[154:157], v[188:191], v[58:61]
	v_mfma_f32_16x16x32_bf16 v[110:113], v[138:141], v[196:199], v[110:113]
	v_mfma_f32_16x16x32_bf16 v[130:133], v[154:157], v[196:199], v[130:133]
	v_mfma_f32_16x16x32_bf16 v[74:77], v[138:141], v[204:207], v[74:77]
	v_mfma_f32_16x16x32_bf16 v[66:69], v[154:157], v[204:207], v[66:69]
	v_mfma_f32_16x16x32_bf16 v[126:129], v[138:141], v[212:215], v[126:129]
	v_mfma_f32_16x16x32_bf16 v[54:57], v[154:157], v[212:215], v[54:57]
	v_mfma_f32_16x16x32_bf16 v[30:33], v[142:145], v[192:195], v[30:33]
	v_mfma_f32_16x16x32_bf16 v[58:61], v[158:161], v[192:195], v[58:61]
	v_mfma_f32_16x16x32_bf16 v[110:113], v[142:145], v[200:203], v[110:113]
	v_mfma_f32_16x16x32_bf16 v[130:133], v[158:161], v[200:203], v[130:133]
	v_mfma_f32_16x16x32_bf16 v[74:77], v[142:145], v[208:211], v[74:77]
	v_mfma_f32_16x16x32_bf16 v[66:69], v[158:161], v[208:211], v[66:69]
	v_mfma_f32_16x16x32_bf16 v[126:129], v[142:145], v[216:219], v[126:129]
	v_mfma_f32_16x16x32_bf16 v[54:57], v[158:161], v[216:219], v[54:57]
	s_setprio 0
	s_setprio 1
	v_mfma_f32_16x16x32_bf16 v[82:85], v[162:165], v[188:191], v[82:85]
	v_mfma_f32_16x16x32_bf16 v[62:65], v[170:173], v[188:191], v[62:65]
	v_mfma_f32_16x16x32_bf16 v[38:41], v[162:165], v[196:199], v[38:41]
	v_mfma_f32_16x16x32_bf16 v[26:29], v[170:173], v[196:199], v[26:29]
	v_mfma_f32_16x16x32_bf16 v[46:49], v[162:165], v[204:207], v[46:49]
	v_mfma_f32_16x16x32_bf16 v[34:37], v[170:173], v[204:207], v[34:37]
	v_mfma_f32_16x16x32_bf16 v[42:45], v[162:165], v[212:215], v[42:45]
	v_mfma_f32_16x16x32_bf16 v[70:73], v[170:173], v[212:215], v[70:73]
	v_mfma_f32_16x16x32_bf16 v[82:85], v[166:169], v[192:195], v[82:85]
	v_mfma_f32_16x16x32_bf16 v[62:65], v[174:177], v[192:195], v[62:65]
	v_mfma_f32_16x16x32_bf16 v[38:41], v[166:169], v[200:203], v[38:41]
	v_mfma_f32_16x16x32_bf16 v[26:29], v[174:177], v[200:203], v[26:29]
	v_mfma_f32_16x16x32_bf16 v[46:49], v[166:169], v[208:211], v[46:49]
	v_mfma_f32_16x16x32_bf16 v[34:37], v[174:177], v[208:211], v[34:37]
	v_mfma_f32_16x16x32_bf16 v[42:45], v[166:169], v[216:219], v[42:45]
	v_mfma_f32_16x16x32_bf16 v[70:73], v[174:177], v[216:219], v[70:73]
	s_setprio 0
	s_barrier
	s_mov_b32 m0, s59
	v_lshl_add_u64 v[178:179], s[14:15], 0, v[148:149]
	s_add_u32 s26, s14, 0x158000
	ds_read_b128 v[188:191], v134 offset:16384
	ds_read_b128 v[192:195], v134 offset:17408
	ds_read_b128 v[196:199], v134 offset:18432
	ds_read_b128 v[200:203], v134 offset:19456
	ds_read_b128 v[204:207], v134 offset:20480
	ds_read_b128 v[208:211], v134 offset:21504
	ds_read_b128 v[212:215], v134 offset:22528
	ds_read_b128 v[216:219], v134 offset:23552
	global_load_lds_dwordx4 v[178:179], off
	v_lshl_add_u64 v[220:221], s[14:15], 0, v[152:153]
	s_mov_b32 m0, s60
	s_addc_u32 s27, s15, 0
	global_load_lds_dwordx4 v[220:221], off
	v_lshl_add_u64 v[222:223], s[26:27], 0, v[148:149]
	s_mov_b32 m0, s61
	v_lshl_add_u64 v[224:225], s[16:17], 0, v[150:151]
	global_load_lds_dwordx4 v[222:223], off
	v_lshl_add_u64 v[222:223], s[26:27], 0, v[152:153]
	s_mov_b32 m0, s62
	s_nop 0
	global_load_lds_dwordx4 v[222:223], off
	v_lshl_add_u64 v[222:223], s[16:17], 0, v[146:147]
	s_mov_b32 m0, s51
	s_nop 0
	global_load_lds_dwordx4 v[222:223], off
	s_mov_b32 m0, s52
	s_nop 0
	global_load_lds_dwordx4 v[224:225], off
	s_waitcnt vmcnt(8)
	s_waitcnt lgkmcnt(0)
	s_barrier
	s_setprio 1
	s_waitcnt lgkmcnt(0)
	v_mfma_f32_16x16x32_bf16 v[102:105], v[138:141], v[188:191], v[102:105]
	v_mfma_f32_16x16x32_bf16 v[118:121], v[154:157], v[188:191], v[118:121]
	v_mfma_f32_16x16x32_bf16 v[122:125], v[138:141], v[196:199], v[122:125]
	v_mfma_f32_16x16x32_bf16 v[114:117], v[154:157], v[196:199], v[114:117]
	v_mfma_f32_16x16x32_bf16 v[98:101], v[138:141], v[204:207], v[98:101]
	v_mfma_f32_16x16x32_bf16 v[50:53], v[154:157], v[204:207], v[50:53]
	v_mfma_f32_16x16x32_bf16 v[22:25], v[138:141], v[212:215], v[22:25]
	v_mfma_f32_16x16x32_bf16 v[14:17], v[154:157], v[212:215], v[14:17]
	v_mfma_f32_16x16x32_bf16 v[102:105], v[142:145], v[192:195], v[102:105]
	v_mfma_f32_16x16x32_bf16 v[118:121], v[158:161], v[192:195], v[118:121]
	v_mfma_f32_16x16x32_bf16 v[122:125], v[142:145], v[200:203], v[122:125]
	v_mfma_f32_16x16x32_bf16 v[114:117], v[158:161], v[200:203], v[114:117]
	v_mfma_f32_16x16x32_bf16 v[98:101], v[142:145], v[208:211], v[98:101]
	v_mfma_f32_16x16x32_bf16 v[50:53], v[158:161], v[208:211], v[50:53]
	v_mfma_f32_16x16x32_bf16 v[22:25], v[142:145], v[216:219], v[22:25]
	v_mfma_f32_16x16x32_bf16 v[14:17], v[158:161], v[216:219], v[14:17]
	s_setprio 0
	s_setprio 1
	v_mfma_f32_16x16x32_bf16 v[106:109], v[162:165], v[188:191], v[106:109]
	v_mfma_f32_16x16x32_bf16 v[90:93], v[170:173], v[188:191], v[90:93]
	v_mfma_f32_16x16x32_bf16 v[94:97], v[162:165], v[196:199], v[94:97]
	v_mfma_f32_16x16x32_bf16 v[78:81], v[170:173], v[196:199], v[78:81]
	v_mfma_f32_16x16x32_bf16 v[18:21], v[162:165], v[204:207], v[18:21]
	v_mfma_f32_16x16x32_bf16 v[10:13], v[170:173], v[204:207], v[10:13]
	v_mfma_f32_16x16x32_bf16 v[6:9], v[162:165], v[212:215], v[6:9]
	v_mfma_f32_16x16x32_bf16 v[2:5], v[170:173], v[212:215], v[2:5]
	v_mfma_f32_16x16x32_bf16 v[106:109], v[166:169], v[192:195], v[106:109]
	v_mfma_f32_16x16x32_bf16 v[90:93], v[174:177], v[192:195], v[90:93]
	v_mfma_f32_16x16x32_bf16 v[94:97], v[166:169], v[200:203], v[94:97]
	v_mfma_f32_16x16x32_bf16 v[78:81], v[174:177], v[200:203], v[78:81]
	v_mfma_f32_16x16x32_bf16 v[18:21], v[166:169], v[208:211], v[18:21]
	v_mfma_f32_16x16x32_bf16 v[10:13], v[174:177], v[208:211], v[10:13]
	v_mfma_f32_16x16x32_bf16 v[6:9], v[166:169], v[216:219], v[6:9]
	v_mfma_f32_16x16x32_bf16 v[2:5], v[174:177], v[216:219], v[2:5]
	s_setprio 0
	s_barrier
	ds_read_b128 v[138:141], v135
	ds_read_b128 v[142:145], v135 offset:1024
	ds_read_b128 v[154:157], v135 offset:2048
	ds_read_b128 v[158:161], v135 offset:3072
	ds_read_b128 v[162:165], v136
	ds_read_b128 v[166:169], v136 offset:1024
	ds_read_b128 v[170:173], v136 offset:2048
	ds_read_b128 v[174:177], v136 offset:3072
	s_add_u32 s16, s16, 0x158000
	s_addc_u32 s17, s17, 0
	s_mov_b32 m0, s53
	v_lshl_add_u64 v[226:227], s[16:17], 0, v[146:147]
	ds_read_b128 v[188:191], v134 offset:32768
	ds_read_b128 v[192:195], v134 offset:33792
	ds_read_b128 v[196:199], v134 offset:34816
	ds_read_b128 v[200:203], v134 offset:35840
	ds_read_b128 v[204:207], v134 offset:36864
	ds_read_b128 v[208:211], v134 offset:37888
	ds_read_b128 v[212:215], v134 offset:38912
	ds_read_b128 v[216:219], v134 offset:39936
	global_load_lds_dwordx4 v[226:227], off
	v_lshl_add_u64 v[226:227], s[16:17], 0, v[150:151]
	s_mov_b32 m0, s54
	s_nop 0
	global_load_lds_dwordx4 v[226:227], off
	s_waitcnt vmcnt(8)
	s_waitcnt lgkmcnt(0)
	s_barrier
	s_setprio 1
	s_waitcnt lgkmcnt(0)
	v_mfma_f32_16x16x32_bf16 v[30:33], v[138:141], v[188:191], v[30:33]
	v_mfma_f32_16x16x32_bf16 v[58:61], v[154:157], v[188:191], v[58:61]
	v_mfma_f32_16x16x32_bf16 v[110:113], v[138:141], v[196:199], v[110:113]
	v_mfma_f32_16x16x32_bf16 v[130:133], v[154:157], v[196:199], v[130:133]
	v_mfma_f32_16x16x32_bf16 v[74:77], v[138:141], v[204:207], v[74:77]
	v_mfma_f32_16x16x32_bf16 v[66:69], v[154:157], v[204:207], v[66:69]
	v_mfma_f32_16x16x32_bf16 v[126:129], v[138:141], v[212:215], v[126:129]
	v_mfma_f32_16x16x32_bf16 v[54:57], v[154:157], v[212:215], v[54:57]
	v_mfma_f32_16x16x32_bf16 v[30:33], v[142:145], v[192:195], v[30:33]
	v_mfma_f32_16x16x32_bf16 v[58:61], v[158:161], v[192:195], v[58:61]
	v_mfma_f32_16x16x32_bf16 v[110:113], v[142:145], v[200:203], v[110:113]
	v_mfma_f32_16x16x32_bf16 v[130:133], v[158:161], v[200:203], v[130:133]
	v_mfma_f32_16x16x32_bf16 v[74:77], v[142:145], v[208:211], v[74:77]
	v_mfma_f32_16x16x32_bf16 v[66:69], v[158:161], v[208:211], v[66:69]
	v_mfma_f32_16x16x32_bf16 v[126:129], v[142:145], v[216:219], v[126:129]
	v_mfma_f32_16x16x32_bf16 v[54:57], v[158:161], v[216:219], v[54:57]
	s_setprio 0
	s_setprio 1
	v_mfma_f32_16x16x32_bf16 v[82:85], v[162:165], v[188:191], v[82:85]
	v_mfma_f32_16x16x32_bf16 v[62:65], v[170:173], v[188:191], v[62:65]
	v_mfma_f32_16x16x32_bf16 v[38:41], v[162:165], v[196:199], v[38:41]
	v_mfma_f32_16x16x32_bf16 v[26:29], v[170:173], v[196:199], v[26:29]
	v_mfma_f32_16x16x32_bf16 v[46:49], v[162:165], v[204:207], v[46:49]
	v_mfma_f32_16x16x32_bf16 v[34:37], v[170:173], v[204:207], v[34:37]
	v_mfma_f32_16x16x32_bf16 v[42:45], v[162:165], v[212:215], v[42:45]
	v_mfma_f32_16x16x32_bf16 v[70:73], v[170:173], v[212:215], v[70:73]
	v_mfma_f32_16x16x32_bf16 v[82:85], v[166:169], v[192:195], v[82:85]
	v_mfma_f32_16x16x32_bf16 v[62:65], v[174:177], v[192:195], v[62:65]
	v_mfma_f32_16x16x32_bf16 v[38:41], v[166:169], v[200:203], v[38:41]
	v_mfma_f32_16x16x32_bf16 v[26:29], v[174:177], v[200:203], v[26:29]
	v_mfma_f32_16x16x32_bf16 v[46:49], v[166:169], v[208:211], v[46:49]
	v_mfma_f32_16x16x32_bf16 v[34:37], v[174:177], v[208:211], v[34:37]
	v_mfma_f32_16x16x32_bf16 v[42:45], v[166:169], v[216:219], v[42:45]
	v_mfma_f32_16x16x32_bf16 v[70:73], v[174:177], v[216:219], v[70:73]
	s_setprio 0
	s_barrier
	s_mov_b32 m0, s63
	v_lshl_add_u64 v[178:179], v[178:179], 0, s[10:11]
	s_add_u32 s14, s14, 0x158080
	ds_read_b128 v[188:191], v134 offset:49152
	ds_read_b128 v[192:195], v134 offset:50176
	ds_read_b128 v[196:199], v134 offset:51200
	ds_read_b128 v[200:203], v134 offset:52224
	ds_read_b128 v[204:207], v134 offset:53248
	ds_read_b128 v[208:211], v134 offset:54272
	ds_read_b128 v[212:215], v134 offset:55296
	ds_read_b128 v[216:219], v134 offset:56320
	global_load_lds_dwordx4 v[178:179], off
	v_lshl_add_u64 v[178:179], v[220:221], 0, s[10:11]
	s_mov_b32 m0, s66
	s_addc_u32 s15, s15, 0
	global_load_lds_dwordx4 v[178:179], off
	v_lshl_add_u64 v[178:179], s[14:15], 0, v[148:149]
	s_mov_b32 m0, s67
	s_nop 0
	global_load_lds_dwordx4 v[178:179], off
	v_lshl_add_u64 v[178:179], s[14:15], 0, v[152:153]
	s_mov_b32 m0, s68
	s_nop 0
	global_load_lds_dwordx4 v[178:179], off
	v_lshl_add_u64 v[178:179], v[222:223], 0, s[10:11]
	s_mov_b32 m0, s34
	s_nop 0
	global_load_lds_dwordx4 v[178:179], off
	v_lshl_add_u64 v[178:179], v[224:225], 0, s[10:11]
	s_mov_b32 m0, s35
	s_nop 0
	global_load_lds_dwordx4 v[178:179], off
	s_waitcnt vmcnt(8)
	s_waitcnt lgkmcnt(0)
	s_barrier
	s_setprio 1
	s_waitcnt lgkmcnt(0)
	v_mfma_f32_16x16x32_bf16 v[102:105], v[138:141], v[188:191], v[102:105]
	v_mfma_f32_16x16x32_bf16 v[118:121], v[154:157], v[188:191], v[118:121]
	v_mfma_f32_16x16x32_bf16 v[122:125], v[138:141], v[196:199], v[122:125]
	v_mfma_f32_16x16x32_bf16 v[114:117], v[154:157], v[196:199], v[114:117]
	v_mfma_f32_16x16x32_bf16 v[98:101], v[138:141], v[204:207], v[98:101]
	v_mfma_f32_16x16x32_bf16 v[50:53], v[154:157], v[204:207], v[50:53]
	v_mfma_f32_16x16x32_bf16 v[22:25], v[138:141], v[212:215], v[22:25]
	v_mfma_f32_16x16x32_bf16 v[14:17], v[154:157], v[212:215], v[14:17]
	v_mfma_f32_16x16x32_bf16 v[102:105], v[142:145], v[192:195], v[102:105]
	v_mfma_f32_16x16x32_bf16 v[118:121], v[158:161], v[192:195], v[118:121]
	v_mfma_f32_16x16x32_bf16 v[122:125], v[142:145], v[200:203], v[122:125]
	v_mfma_f32_16x16x32_bf16 v[114:117], v[158:161], v[200:203], v[114:117]
	v_mfma_f32_16x16x32_bf16 v[98:101], v[142:145], v[208:211], v[98:101]
	v_mfma_f32_16x16x32_bf16 v[50:53], v[158:161], v[208:211], v[50:53]
	v_mfma_f32_16x16x32_bf16 v[22:25], v[142:145], v[216:219], v[22:25]
	v_mfma_f32_16x16x32_bf16 v[14:17], v[158:161], v[216:219], v[14:17]
	s_setprio 0
	s_setprio 1
	v_mfma_f32_16x16x32_bf16 v[106:109], v[162:165], v[188:191], v[106:109]
	v_mfma_f32_16x16x32_bf16 v[90:93], v[170:173], v[188:191], v[90:93]
	v_mfma_f32_16x16x32_bf16 v[94:97], v[162:165], v[196:199], v[94:97]
	v_mfma_f32_16x16x32_bf16 v[78:81], v[170:173], v[196:199], v[78:81]
	v_mfma_f32_16x16x32_bf16 v[18:21], v[162:165], v[204:207], v[18:21]
	v_mfma_f32_16x16x32_bf16 v[10:13], v[170:173], v[204:207], v[10:13]
	v_mfma_f32_16x16x32_bf16 v[6:9], v[162:165], v[212:215], v[6:9]
	v_mfma_f32_16x16x32_bf16 v[2:5], v[170:173], v[212:215], v[2:5]
	v_mfma_f32_16x16x32_bf16 v[106:109], v[166:169], v[192:195], v[106:109]
	v_mfma_f32_16x16x32_bf16 v[90:93], v[174:177], v[192:195], v[90:93]
	v_mfma_f32_16x16x32_bf16 v[94:97], v[166:169], v[200:203], v[94:97]
	v_mfma_f32_16x16x32_bf16 v[78:81], v[174:177], v[200:203], v[78:81]
	v_mfma_f32_16x16x32_bf16 v[18:21], v[166:169], v[208:211], v[18:21]
	v_mfma_f32_16x16x32_bf16 v[10:13], v[174:177], v[208:211], v[10:13]
	v_mfma_f32_16x16x32_bf16 v[6:9], v[166:169], v[216:219], v[6:9]
	v_mfma_f32_16x16x32_bf16 v[2:5], v[174:177], v[216:219], v[2:5]
	s_setprio 0
	s_add_i32 s56, s56, 2
	s_cmpk_gt_u32 s56, 0x53
	s_barrier
	s_cbranch_scc0 .LBB0_1638
	s_cmpk_lt_u32 s48, 0x100
	s_cbranch_scc0 .LBB0_1641
	s_barrier

.LBB0_1690:
	s_add_u32 s26, s8, s12
	s_addc_u32 s27, s9, s13
	s_add_u32 s12, s12, 0x100
	ds_read_b128 v[138:141], v88
	ds_read_b128 v[142:145], v88 offset:1024
	ds_read_b128 v[154:157], v88 offset:2048
	ds_read_b128 v[158:161], v88 offset:3072
	ds_read_b128 v[162:165], v89
	ds_read_b128 v[166:169], v89 offset:1024
	ds_read_b128 v[170:173], v89 offset:2048
	ds_read_b128 v[174:177], v89 offset:3072
	s_addc_u32 s13, s13, 0
	v_cmp_lt_u64_e32 vcc, s[12:13], v[86:87]
	s_and_b64 s[14:15], vcc, exec
	s_cselect_b32 s15, 0, 0xffffd500
	s_cselect_b32 s14, 0, -1
	s_add_u32 s12, s15, s12
	s_addc_u32 s13, s14, s13
	s_cmpk_lg_i32 s56, 0x52
	s_cselect_b32 s14, s12, 0
	s_cselect_b32 s15, s13, 0
	s_add_u32 s16, s8, s14
	s_addc_u32 s17, s9, s15
	s_add_u32 s14, s0, s14
	s_addc_u32 s15, s1, s15
	s_add_u32 s26, s26, 0x158080
	s_addc_u32 s27, s27, 0
	s_mov_b32 m0, s57
	v_lshl_add_u64 v[178:179], s[26:27], 0, v[146:147]
	ds_read_b128 v[188:191], v134
	ds_read_b128 v[192:195], v134 offset:1024
	ds_read_b128 v[196:199], v134 offset:2048
	ds_read_b128 v[200:203], v134 offset:3072
	ds_read_b128 v[204:207], v134 offset:4096
	ds_read_b128 v[208:211], v134 offset:5120
	ds_read_b128 v[212:215], v134 offset:6144
	ds_read_b128 v[216:219], v134 offset:7168
	global_load_lds_dwordx4 v[178:179], off
	v_lshl_add_u64 v[178:179], s[26:27], 0, v[150:151]
	s_mov_b32 m0, s58
	s_nop 0
	global_load_lds_dwordx4 v[178:179], off
	s_waitcnt vmcnt(8)
	s_waitcnt lgkmcnt(0)
	s_barrier
	s_setprio 1
	s_waitcnt lgkmcnt(0)
	v_mfma_f32_16x16x32_bf16 v[30:33], v[138:141], v[188:191], v[30:33]
	v_mfma_f32_16x16x32_bf16 v[58:61], v[154:157], v[188:191], v[58:61]
	v_mfma_f32_16x16x32_bf16 v[110:113], v[138:141], v[196:199], v[110:113]
	v_mfma_f32_16x16x32_bf16 v[130:133], v[154:157], v[196:199], v[130:133]
	v_mfma_f32_16x16x32_bf16 v[74:77], v[138:141], v[204:207], v[74:77]
	v_mfma_f32_16x16x32_bf16 v[66:69], v[154:157], v[204:207], v[66:69]
	v_mfma_f32_16x16x32_bf16 v[126:129], v[138:141], v[212:215], v[126:129]
	v_mfma_f32_16x16x32_bf16 v[54:57], v[154:157], v[212:215], v[54:57]
	v_mfma_f32_16x16x32_bf16 v[30:33], v[142:145], v[192:195], v[30:33]
	v_mfma_f32_16x16x32_bf16 v[58:61], v[158:161], v[192:195], v[58:61]
	v_mfma_f32_16x16x32_bf16 v[110:113], v[142:145], v[200:203], v[110:113]
	v_mfma_f32_16x16x32_bf16 v[130:133], v[158:161], v[200:203], v[130:133]
	v_mfma_f32_16x16x32_bf16 v[74:77], v[142:145], v[208:211], v[74:77]
	v_mfma_f32_16x16x32_bf16 v[66:69], v[158:161], v[208:211], v[66:69]
	v_mfma_f32_16x16x32_bf16 v[126:129], v[142:145], v[216:219], v[126:129]
	v_mfma_f32_16x16x32_bf16 v[54:57], v[158:161], v[216:219], v[54:57]
	s_setprio 0
	s_setprio 1
	v_mfma_f32_16x16x32_bf16 v[82:85], v[162:165], v[188:191], v[82:85]
	v_mfma_f32_16x16x32_bf16 v[62:65], v[170:173], v[188:191], v[62:65]
	v_mfma_f32_16x16x32_bf16 v[38:41], v[162:165], v[196:199], v[38:41]
	v_mfma_f32_16x16x32_bf16 v[26:29], v[170:173], v[196:199], v[26:29]
	v_mfma_f32_16x16x32_bf16 v[46:49], v[162:165], v[204:207], v[46:49]
	v_mfma_f32_16x16x32_bf16 v[34:37], v[170:173], v[204:207], v[34:37]
	v_mfma_f32_16x16x32_bf16 v[42:45], v[162:165], v[212:215], v[42:45]
	v_mfma_f32_16x16x32_bf16 v[70:73], v[170:173], v[212:215], v[70:73]
	v_mfma_f32_16x16x32_bf16 v[82:85], v[166:169], v[192:195], v[82:85]
	v_mfma_f32_16x16x32_bf16 v[62:65], v[174:177], v[192:195], v[62:65]
	v_mfma_f32_16x16x32_bf16 v[38:41], v[166:169], v[200:203], v[38:41]
	v_mfma_f32_16x16x32_bf16 v[26:29], v[174:177], v[200:203], v[26:29]
	v_mfma_f32_16x16x32_bf16 v[46:49], v[166:169], v[208:211], v[46:49]
	v_mfma_f32_16x16x32_bf16 v[34:37], v[174:177], v[208:211], v[34:37]
	v_mfma_f32_16x16x32_bf16 v[42:45], v[166:169], v[216:219], v[42:45]
	v_mfma_f32_16x16x32_bf16 v[70:73], v[174:177], v[216:219], v[70:73]
	s_setprio 0
	s_barrier
	s_mov_b32 m0, s59
	v_lshl_add_u64 v[178:179], s[14:15], 0, v[148:149]
	s_add_u32 s26, s14, 0x158000
	ds_read_b128 v[188:191], v134 offset:16384
	ds_read_b128 v[192:195], v134 offset:17408
	ds_read_b128 v[196:199], v134 offset:18432
	ds_read_b128 v[200:203], v134 offset:19456
	ds_read_b128 v[204:207], v134 offset:20480
	ds_read_b128 v[208:211], v134 offset:21504
	ds_read_b128 v[212:215], v134 offset:22528
	ds_read_b128 v[216:219], v134 offset:23552
	global_load_lds_dwordx4 v[178:179], off
	v_lshl_add_u64 v[184:185], s[14:15], 0, v[152:153]
	s_mov_b32 m0, s60
	s_addc_u32 s27, s15, 0
	global_load_lds_dwordx4 v[184:185], off
	v_lshl_add_u64 v[220:221], s[26:27], 0, v[148:149]
	s_mov_b32 m0, s61
	v_lshl_add_u64 v[222:223], s[16:17], 0, v[150:151]
	global_load_lds_dwordx4 v[220:221], off
	v_lshl_add_u64 v[220:221], s[26:27], 0, v[152:153]
	s_mov_b32 m0, s62
	s_nop 0
	global_load_lds_dwordx4 v[220:221], off
	v_lshl_add_u64 v[220:221], s[16:17], 0, v[146:147]
	s_mov_b32 m0, s51
	s_nop 0
	global_load_lds_dwordx4 v[220:221], off
	s_mov_b32 m0, s52
	s_nop 0
	global_load_lds_dwordx4 v[222:223], off
	s_waitcnt vmcnt(8)
	s_waitcnt lgkmcnt(0)
	s_barrier
	s_setprio 1
	s_waitcnt lgkmcnt(0)
	v_mfma_f32_16x16x32_bf16 v[102:105], v[138:141], v[188:191], v[102:105]
	v_mfma_f32_16x16x32_bf16 v[118:121], v[154:157], v[188:191], v[118:121]
	v_mfma_f32_16x16x32_bf16 v[122:125], v[138:141], v[196:199], v[122:125]
	v_mfma_f32_16x16x32_bf16 v[114:117], v[154:157], v[196:199], v[114:117]
	v_mfma_f32_16x16x32_bf16 v[98:101], v[138:141], v[204:207], v[98:101]
	v_mfma_f32_16x16x32_bf16 v[50:53], v[154:157], v[204:207], v[50:53]
	v_mfma_f32_16x16x32_bf16 v[22:25], v[138:141], v[212:215], v[22:25]
	v_mfma_f32_16x16x32_bf16 v[14:17], v[154:157], v[212:215], v[14:17]
	v_mfma_f32_16x16x32_bf16 v[102:105], v[142:145], v[192:195], v[102:105]
	v_mfma_f32_16x16x32_bf16 v[118:121], v[158:161], v[192:195], v[118:121]
	v_mfma_f32_16x16x32_bf16 v[122:125], v[142:145], v[200:203], v[122:125]
	v_mfma_f32_16x16x32_bf16 v[114:117], v[158:161], v[200:203], v[114:117]
	v_mfma_f32_16x16x32_bf16 v[98:101], v[142:145], v[208:211], v[98:101]
	v_mfma_f32_16x16x32_bf16 v[50:53], v[158:161], v[208:211], v[50:53]
	v_mfma_f32_16x16x32_bf16 v[22:25], v[142:145], v[216:219], v[22:25]
	v_mfma_f32_16x16x32_bf16 v[14:17], v[158:161], v[216:219], v[14:17]
	s_setprio 0
	s_setprio 1
	v_mfma_f32_16x16x32_bf16 v[106:109], v[162:165], v[188:191], v[106:109]
	v_mfma_f32_16x16x32_bf16 v[90:93], v[170:173], v[188:191], v[90:93]
	v_mfma_f32_16x16x32_bf16 v[94:97], v[162:165], v[196:199], v[94:97]
	v_mfma_f32_16x16x32_bf16 v[78:81], v[170:173], v[196:199], v[78:81]
	v_mfma_f32_16x16x32_bf16 v[18:21], v[162:165], v[204:207], v[18:21]
	v_mfma_f32_16x16x32_bf16 v[10:13], v[170:173], v[204:207], v[10:13]
	v_mfma_f32_16x16x32_bf16 v[6:9], v[162:165], v[212:215], v[6:9]
	v_mfma_f32_16x16x32_bf16 v[2:5], v[170:173], v[212:215], v[2:5]
	v_mfma_f32_16x16x32_bf16 v[106:109], v[166:169], v[192:195], v[106:109]
	v_mfma_f32_16x16x32_bf16 v[90:93], v[174:177], v[192:195], v[90:93]
	v_mfma_f32_16x16x32_bf16 v[94:97], v[166:169], v[200:203], v[94:97]
	v_mfma_f32_16x16x32_bf16 v[78:81], v[174:177], v[200:203], v[78:81]
	v_mfma_f32_16x16x32_bf16 v[18:21], v[166:169], v[208:211], v[18:21]
	v_mfma_f32_16x16x32_bf16 v[10:13], v[174:177], v[208:211], v[10:13]
	v_mfma_f32_16x16x32_bf16 v[6:9], v[166:169], v[216:219], v[6:9]
	v_mfma_f32_16x16x32_bf16 v[2:5], v[174:177], v[216:219], v[2:5]
	s_setprio 0
	s_barrier
	ds_read_b128 v[138:141], v135
	ds_read_b128 v[142:145], v135 offset:1024
	ds_read_b128 v[154:157], v135 offset:2048
	ds_read_b128 v[158:161], v135 offset:3072
	ds_read_b128 v[162:165], v136
	ds_read_b128 v[166:169], v136 offset:1024
	ds_read_b128 v[170:173], v136 offset:2048
	ds_read_b128 v[174:177], v136 offset:3072
	s_add_u32 s16, s16, 0x158000
	s_addc_u32 s17, s17, 0
	s_mov_b32 m0, s53
	v_lshl_add_u64 v[224:225], s[16:17], 0, v[146:147]
	ds_read_b128 v[188:191], v134 offset:32768
	ds_read_b128 v[192:195], v134 offset:33792
	ds_read_b128 v[196:199], v134 offset:34816
	ds_read_b128 v[200:203], v134 offset:35840
	ds_read_b128 v[204:207], v134 offset:36864
	ds_read_b128 v[208:211], v134 offset:37888
	ds_read_b128 v[212:215], v134 offset:38912
	ds_read_b128 v[216:219], v134 offset:39936
	global_load_lds_dwordx4 v[224:225], off
	v_lshl_add_u64 v[224:225], s[16:17], 0, v[150:151]
	s_mov_b32 m0, s54
	s_nop 0
	global_load_lds_dwordx4 v[224:225], off
	s_waitcnt vmcnt(8)
	s_waitcnt lgkmcnt(0)
	s_barrier
	s_setprio 1
	s_waitcnt lgkmcnt(0)
	v_mfma_f32_16x16x32_bf16 v[30:33], v[138:141], v[188:191], v[30:33]
	v_mfma_f32_16x16x32_bf16 v[58:61], v[154:157], v[188:191], v[58:61]
	v_mfma_f32_16x16x32_bf16 v[110:113], v[138:141], v[196:199], v[110:113]
	v_mfma_f32_16x16x32_bf16 v[130:133], v[154:157], v[196:199], v[130:133]
	v_mfma_f32_16x16x32_bf16 v[74:77], v[138:141], v[204:207], v[74:77]
	v_mfma_f32_16x16x32_bf16 v[66:69], v[154:157], v[204:207], v[66:69]
	v_mfma_f32_16x16x32_bf16 v[126:129], v[138:141], v[212:215], v[126:129]
	v_mfma_f32_16x16x32_bf16 v[54:57], v[154:157], v[212:215], v[54:57]
	v_mfma_f32_16x16x32_bf16 v[30:33], v[142:145], v[192:195], v[30:33]
	v_mfma_f32_16x16x32_bf16 v[58:61], v[158:161], v[192:195], v[58:61]
	v_mfma_f32_16x16x32_bf16 v[110:113], v[142:145], v[200:203], v[110:113]
	v_mfma_f32_16x16x32_bf16 v[130:133], v[158:161], v[200:203], v[130:133]
	v_mfma_f32_16x16x32_bf16 v[74:77], v[142:145], v[208:211], v[74:77]
	v_mfma_f32_16x16x32_bf16 v[66:69], v[158:161], v[208:211], v[66:69]
	v_mfma_f32_16x16x32_bf16 v[126:129], v[142:145], v[216:219], v[126:129]
	v_mfma_f32_16x16x32_bf16 v[54:57], v[158:161], v[216:219], v[54:57]
	s_setprio 0
	s_setprio 1
	v_mfma_f32_16x16x32_bf16 v[82:85], v[162:165], v[188:191], v[82:85]
	v_mfma_f32_16x16x32_bf16 v[62:65], v[170:173], v[188:191], v[62:65]
	v_mfma_f32_16x16x32_bf16 v[38:41], v[162:165], v[196:199], v[38:41]
	v_mfma_f32_16x16x32_bf16 v[26:29], v[170:173], v[196:199], v[26:29]
	v_mfma_f32_16x16x32_bf16 v[46:49], v[162:165], v[204:207], v[46:49]
	v_mfma_f32_16x16x32_bf16 v[34:37], v[170:173], v[204:207], v[34:37]
	v_mfma_f32_16x16x32_bf16 v[42:45], v[162:165], v[212:215], v[42:45]
	v_mfma_f32_16x16x32_bf16 v[70:73], v[170:173], v[212:215], v[70:73]
	v_mfma_f32_16x16x32_bf16 v[82:85], v[166:169], v[192:195], v[82:85]
	v_mfma_f32_16x16x32_bf16 v[62:65], v[174:177], v[192:195], v[62:65]
	v_mfma_f32_16x16x32_bf16 v[38:41], v[166:169], v[200:203], v[38:41]
	v_mfma_f32_16x16x32_bf16 v[26:29], v[174:177], v[200:203], v[26:29]
	v_mfma_f32_16x16x32_bf16 v[46:49], v[166:169], v[208:211], v[46:49]
	v_mfma_f32_16x16x32_bf16 v[34:37], v[174:177], v[208:211], v[34:37]
	v_mfma_f32_16x16x32_bf16 v[42:45], v[166:169], v[216:219], v[42:45]
	v_mfma_f32_16x16x32_bf16 v[70:73], v[174:177], v[216:219], v[70:73]
	s_setprio 0
	s_barrier
	s_mov_b32 m0, s63
	v_lshl_add_u64 v[178:179], v[178:179], 0, s[10:11]
	s_add_u32 s14, s14, 0x158080
	ds_read_b128 v[188:191], v134 offset:49152
	ds_read_b128 v[192:195], v134 offset:50176
	ds_read_b128 v[196:199], v134 offset:51200
	ds_read_b128 v[200:203], v134 offset:52224
	ds_read_b128 v[204:207], v134 offset:53248
	ds_read_b128 v[208:211], v134 offset:54272
	ds_read_b128 v[212:215], v134 offset:55296
	ds_read_b128 v[216:219], v134 offset:56320
	global_load_lds_dwordx4 v[178:179], off
	v_lshl_add_u64 v[178:179], v[184:185], 0, s[10:11]
	s_mov_b32 m0, s66
	s_addc_u32 s15, s15, 0
	global_load_lds_dwordx4 v[178:179], off
	v_lshl_add_u64 v[178:179], s[14:15], 0, v[148:149]
	s_mov_b32 m0, s67
	s_nop 0
	global_load_lds_dwordx4 v[178:179], off
	v_lshl_add_u64 v[178:179], s[14:15], 0, v[152:153]
	s_mov_b32 m0, s68
	s_nop 0
	global_load_lds_dwordx4 v[178:179], off
	v_lshl_add_u64 v[178:179], v[220:221], 0, s[10:11]
	s_mov_b32 m0, s34
	s_nop 0
	global_load_lds_dwordx4 v[178:179], off
	v_lshl_add_u64 v[178:179], v[222:223], 0, s[10:11]
	s_mov_b32 m0, s35
	s_nop 0
	global_load_lds_dwordx4 v[178:179], off
	s_waitcnt vmcnt(8)
	s_waitcnt lgkmcnt(0)
	s_barrier
	s_setprio 1
	s_waitcnt lgkmcnt(0)
	v_mfma_f32_16x16x32_bf16 v[102:105], v[138:141], v[188:191], v[102:105]
	v_mfma_f32_16x16x32_bf16 v[118:121], v[154:157], v[188:191], v[118:121]
	v_mfma_f32_16x16x32_bf16 v[122:125], v[138:141], v[196:199], v[122:125]
	v_mfma_f32_16x16x32_bf16 v[114:117], v[154:157], v[196:199], v[114:117]
	v_mfma_f32_16x16x32_bf16 v[98:101], v[138:141], v[204:207], v[98:101]
	v_mfma_f32_16x16x32_bf16 v[50:53], v[154:157], v[204:207], v[50:53]
	v_mfma_f32_16x16x32_bf16 v[22:25], v[138:141], v[212:215], v[22:25]
	v_mfma_f32_16x16x32_bf16 v[14:17], v[154:157], v[212:215], v[14:17]
	v_mfma_f32_16x16x32_bf16 v[102:105], v[142:145], v[192:195], v[102:105]
	v_mfma_f32_16x16x32_bf16 v[118:121], v[158:161], v[192:195], v[118:121]
	v_mfma_f32_16x16x32_bf16 v[122:125], v[142:145], v[200:203], v[122:125]
	v_mfma_f32_16x16x32_bf16 v[114:117], v[158:161], v[200:203], v[114:117]
	v_mfma_f32_16x16x32_bf16 v[98:101], v[142:145], v[208:211], v[98:101]
	v_mfma_f32_16x16x32_bf16 v[50:53], v[158:161], v[208:211], v[50:53]
	v_mfma_f32_16x16x32_bf16 v[22:25], v[142:145], v[216:219], v[22:25]
	v_mfma_f32_16x16x32_bf16 v[14:17], v[158:161], v[216:219], v[14:17]
	s_setprio 0
	s_setprio 1
	v_mfma_f32_16x16x32_bf16 v[106:109], v[162:165], v[188:191], v[106:109]
	v_mfma_f32_16x16x32_bf16 v[90:93], v[170:173], v[188:191], v[90:93]
	v_mfma_f32_16x16x32_bf16 v[94:97], v[162:165], v[196:199], v[94:97]
	v_mfma_f32_16x16x32_bf16 v[78:81], v[170:173], v[196:199], v[78:81]
	v_mfma_f32_16x16x32_bf16 v[18:21], v[162:165], v[204:207], v[18:21]
	v_mfma_f32_16x16x32_bf16 v[10:13], v[170:173], v[204:207], v[10:13]
	v_mfma_f32_16x16x32_bf16 v[6:9], v[162:165], v[212:215], v[6:9]
	v_mfma_f32_16x16x32_bf16 v[2:5], v[170:173], v[212:215], v[2:5]
	v_mfma_f32_16x16x32_bf16 v[106:109], v[166:169], v[192:195], v[106:109]
	v_mfma_f32_16x16x32_bf16 v[90:93], v[174:177], v[192:195], v[90:93]
	v_mfma_f32_16x16x32_bf16 v[94:97], v[166:169], v[200:203], v[94:97]
	v_mfma_f32_16x16x32_bf16 v[78:81], v[174:177], v[200:203], v[78:81]
	v_mfma_f32_16x16x32_bf16 v[18:21], v[166:169], v[208:211], v[18:21]
	v_mfma_f32_16x16x32_bf16 v[10:13], v[174:177], v[208:211], v[10:13]
	v_mfma_f32_16x16x32_bf16 v[6:9], v[166:169], v[216:219], v[6:9]
	v_mfma_f32_16x16x32_bf16 v[2:5], v[174:177], v[216:219], v[2:5]
	s_setprio 0
	s_add_i32 s56, s56, 2
	s_cmpk_gt_u32 s56, 0x53
	s_barrier
	s_cbranch_scc0 .LBB0_1690
	s_cmpk_lt_u32 s48, 0x100
	s_cbranch_scc0 .LBB0_1693
	s_barrier

.LBB0_1740:
	s_add_u32 s26, s4, s10
	s_addc_u32 s27, s5, s11
	s_add_u32 s10, s10, 0x100
	ds_read_b128 v[138:141], v133
	ds_read_b128 v[142:145], v133 offset:1024
	ds_read_b128 v[154:157], v133 offset:2048
	ds_read_b128 v[158:161], v133 offset:3072
	ds_read_b128 v[162:165], v134
	ds_read_b128 v[166:169], v134 offset:1024
	ds_read_b128 v[170:173], v134 offset:2048
	ds_read_b128 v[174:177], v134 offset:3072
	s_addc_u32 s11, s11, 0
	v_cmp_ge_u64_e32 vcc, s[10:11], v[130:131]
	s_and_b64 s[12:13], vcc, exec
	s_cselect_b32 s13, s6, 0
	s_cselect_b32 s12, 0, 0
	s_sub_u32 s10, s10, s13
	s_subb_u32 s11, s11, s12
	s_cmp_lg_u32 s44, s7
	s_cselect_b32 s12, s10, 0
	s_cselect_b32 s13, s11, 0
	s_add_u32 s14, s4, s12
	s_addc_u32 s15, s5, s13
	s_add_u32 s12, s2, s12
	s_addc_u32 s13, s3, s13
	s_add_u32 s26, s26, 0x158080
	s_addc_u32 s27, s27, 0
	s_mov_b32 m0, s45
	v_lshl_add_u64 v[210:211], s[26:27], 0, v[146:147]
	ds_read_b128 v[178:181], v135
	ds_read_b128 v[182:185], v135 offset:1024
	ds_read_b128 v[186:189], v135 offset:2048
	ds_read_b128 v[190:193], v135 offset:3072
	ds_read_b128 v[194:197], v135 offset:4096
	ds_read_b128 v[198:201], v135 offset:5120
	ds_read_b128 v[202:205], v135 offset:6144
	ds_read_b128 v[206:209], v135 offset:7168
	global_load_lds_dwordx4 v[210:211], off
	v_lshl_add_u64 v[210:211], s[26:27], 0, v[150:151]
	s_mov_b32 m0, s46
	s_nop 0
	global_load_lds_dwordx4 v[210:211], off
	s_waitcnt vmcnt(8)
	s_waitcnt lgkmcnt(0)
	s_barrier
	s_setprio 1
	s_waitcnt lgkmcnt(0)
	v_mfma_f32_16x16x32_bf16 v[126:129], v[138:141], v[178:181], v[126:129]
	v_mfma_f32_16x16x32_bf16 v[122:125], v[154:157], v[178:181], v[122:125]
	v_mfma_f32_16x16x32_bf16 v[118:121], v[138:141], v[186:189], v[118:121]
	v_mfma_f32_16x16x32_bf16 v[114:117], v[154:157], v[186:189], v[114:117]
	v_mfma_f32_16x16x32_bf16 v[102:105], v[138:141], v[194:197], v[102:105]
	v_mfma_f32_16x16x32_bf16 v[98:101], v[154:157], v[194:197], v[98:101]
	v_mfma_f32_16x16x32_bf16 v[86:89], v[138:141], v[202:205], v[86:89]
	v_mfma_f32_16x16x32_bf16 v[82:85], v[154:157], v[202:205], v[82:85]
	v_mfma_f32_16x16x32_bf16 v[126:129], v[142:145], v[182:185], v[126:129]
	v_mfma_f32_16x16x32_bf16 v[122:125], v[158:161], v[182:185], v[122:125]
	v_mfma_f32_16x16x32_bf16 v[118:121], v[142:145], v[190:193], v[118:121]
	v_mfma_f32_16x16x32_bf16 v[114:117], v[158:161], v[190:193], v[114:117]
	v_mfma_f32_16x16x32_bf16 v[102:105], v[142:145], v[198:201], v[102:105]
	v_mfma_f32_16x16x32_bf16 v[98:101], v[158:161], v[198:201], v[98:101]
	v_mfma_f32_16x16x32_bf16 v[86:89], v[142:145], v[206:209], v[86:89]
	v_mfma_f32_16x16x32_bf16 v[82:85], v[158:161], v[206:209], v[82:85]
	s_setprio 0
	s_setprio 1
	v_mfma_f32_16x16x32_bf16 v[110:113], v[162:165], v[178:181], v[110:113]
	v_mfma_f32_16x16x32_bf16 v[106:109], v[170:173], v[178:181], v[106:109]
	v_mfma_f32_16x16x32_bf16 v[94:97], v[162:165], v[186:189], v[94:97]
	v_mfma_f32_16x16x32_bf16 v[90:93], v[170:173], v[186:189], v[90:93]
	v_mfma_f32_16x16x32_bf16 v[78:81], v[162:165], v[194:197], v[78:81]
	v_mfma_f32_16x16x32_bf16 v[74:77], v[170:173], v[194:197], v[74:77]
	v_mfma_f32_16x16x32_bf16 v[70:73], v[162:165], v[202:205], v[70:73]
	v_mfma_f32_16x16x32_bf16 v[66:69], v[170:173], v[202:205], v[66:69]
	v_mfma_f32_16x16x32_bf16 v[110:113], v[166:169], v[182:185], v[110:113]
	v_mfma_f32_16x16x32_bf16 v[106:109], v[174:177], v[182:185], v[106:109]
	v_mfma_f32_16x16x32_bf16 v[94:97], v[166:169], v[190:193], v[94:97]
	v_mfma_f32_16x16x32_bf16 v[90:93], v[174:177], v[190:193], v[90:93]
	v_mfma_f32_16x16x32_bf16 v[78:81], v[166:169], v[198:201], v[78:81]
	v_mfma_f32_16x16x32_bf16 v[74:77], v[174:177], v[198:201], v[74:77]
	v_mfma_f32_16x16x32_bf16 v[70:73], v[166:169], v[206:209], v[70:73]
	v_mfma_f32_16x16x32_bf16 v[66:69], v[174:177], v[206:209], v[66:69]
	s_setprio 0
	s_barrier
	s_mov_b32 m0, s47
	v_lshl_add_u64 v[210:211], s[12:13], 0, v[148:149]
	s_add_u32 s26, s12, 0x158000
	ds_read_b128 v[178:181], v135 offset:16384
	ds_read_b128 v[182:185], v135 offset:17408
	ds_read_b128 v[186:189], v135 offset:18432
	ds_read_b128 v[190:193], v135 offset:19456
	ds_read_b128 v[194:197], v135 offset:20480
	ds_read_b128 v[198:201], v135 offset:21504
	ds_read_b128 v[202:205], v135 offset:22528
	ds_read_b128 v[206:209], v135 offset:23552
	global_load_lds_dwordx4 v[210:211], off
	v_lshl_add_u64 v[212:213], s[12:13], 0, v[152:153]
	s_mov_b32 m0, s48
	s_addc_u32 s27, s13, 0
	global_load_lds_dwordx4 v[212:213], off
	v_lshl_add_u64 v[214:215], s[26:27], 0, v[148:149]
	s_mov_b32 m0, s49
	v_lshl_add_u64 v[216:217], s[14:15], 0, v[150:151]
	global_load_lds_dwordx4 v[214:215], off
	v_lshl_add_u64 v[214:215], s[26:27], 0, v[152:153]
	s_mov_b32 m0, s50
	s_nop 0
	global_load_lds_dwordx4 v[214:215], off
	v_lshl_add_u64 v[214:215], s[14:15], 0, v[146:147]
	s_mov_b32 m0, s18
	s_nop 0
	global_load_lds_dwordx4 v[214:215], off
	s_mov_b32 m0, s19
	s_nop 0
	global_load_lds_dwordx4 v[216:217], off
	s_waitcnt vmcnt(8)
	s_waitcnt lgkmcnt(0)
	s_barrier
	s_setprio 1
	s_waitcnt lgkmcnt(0)
	v_mfma_f32_16x16x32_bf16 v[62:65], v[138:141], v[178:181], v[62:65]
	v_mfma_f32_16x16x32_bf16 v[58:61], v[154:157], v[178:181], v[58:61]
	v_mfma_f32_16x16x32_bf16 v[54:57], v[138:141], v[186:189], v[54:57]
	v_mfma_f32_16x16x32_bf16 v[50:53], v[154:157], v[186:189], v[50:53]
	v_mfma_f32_16x16x32_bf16 v[38:41], v[138:141], v[194:197], v[38:41]
	v_mfma_f32_16x16x32_bf16 v[34:37], v[154:157], v[194:197], v[34:37]
	v_mfma_f32_16x16x32_bf16 v[22:25], v[138:141], v[202:205], v[22:25]
	v_mfma_f32_16x16x32_bf16 v[18:21], v[154:157], v[202:205], v[18:21]
	v_mfma_f32_16x16x32_bf16 v[62:65], v[142:145], v[182:185], v[62:65]
	v_mfma_f32_16x16x32_bf16 v[58:61], v[158:161], v[182:185], v[58:61]
	v_mfma_f32_16x16x32_bf16 v[54:57], v[142:145], v[190:193], v[54:57]
	v_mfma_f32_16x16x32_bf16 v[50:53], v[158:161], v[190:193], v[50:53]
	v_mfma_f32_16x16x32_bf16 v[38:41], v[142:145], v[198:201], v[38:41]
	v_mfma_f32_16x16x32_bf16 v[34:37], v[158:161], v[198:201], v[34:37]
	v_mfma_f32_16x16x32_bf16 v[22:25], v[142:145], v[206:209], v[22:25]
	v_mfma_f32_16x16x32_bf16 v[18:21], v[158:161], v[206:209], v[18:21]
	s_setprio 0
	s_setprio 1
	v_mfma_f32_16x16x32_bf16 v[46:49], v[162:165], v[178:181], v[46:49]
	v_mfma_f32_16x16x32_bf16 v[42:45], v[170:173], v[178:181], v[42:45]
	v_mfma_f32_16x16x32_bf16 v[30:33], v[162:165], v[186:189], v[30:33]
	v_mfma_f32_16x16x32_bf16 v[26:29], v[170:173], v[186:189], v[26:29]
	v_mfma_f32_16x16x32_bf16 v[14:17], v[162:165], v[194:197], v[14:17]
	v_mfma_f32_16x16x32_bf16 v[10:13], v[170:173], v[194:197], v[10:13]
	v_mfma_f32_16x16x32_bf16 v[6:9], v[162:165], v[202:205], v[6:9]
	v_mfma_f32_16x16x32_bf16 v[2:5], v[170:173], v[202:205], v[2:5]
	v_mfma_f32_16x16x32_bf16 v[46:49], v[166:169], v[182:185], v[46:49]
	v_mfma_f32_16x16x32_bf16 v[42:45], v[174:177], v[182:185], v[42:45]
	v_mfma_f32_16x16x32_bf16 v[30:33], v[166:169], v[190:193], v[30:33]
	v_mfma_f32_16x16x32_bf16 v[26:29], v[174:177], v[190:193], v[26:29]
	v_mfma_f32_16x16x32_bf16 v[14:17], v[166:169], v[198:201], v[14:17]
	v_mfma_f32_16x16x32_bf16 v[10:13], v[174:177], v[198:201], v[10:13]
	v_mfma_f32_16x16x32_bf16 v[6:9], v[166:169], v[206:209], v[6:9]
	v_mfma_f32_16x16x32_bf16 v[2:5], v[174:177], v[206:209], v[2:5]
	s_setprio 0
	s_barrier
	ds_read_b128 v[138:141], v136
	ds_read_b128 v[142:145], v136 offset:1024
	ds_read_b128 v[154:157], v136 offset:2048
	ds_read_b128 v[158:161], v136 offset:3072
	ds_read_b128 v[162:165], v137
	ds_read_b128 v[166:169], v137 offset:1024
	ds_read_b128 v[170:173], v137 offset:2048
	ds_read_b128 v[174:177], v137 offset:3072
	s_add_u32 s14, s14, 0x158000
	s_addc_u32 s15, s15, 0
	s_mov_b32 m0, s21
	v_lshl_add_u64 v[218:219], s[14:15], 0, v[146:147]
	ds_read_b128 v[178:181], v135 offset:32768
	ds_read_b128 v[182:185], v135 offset:33792
	ds_read_b128 v[186:189], v135 offset:34816
	ds_read_b128 v[190:193], v135 offset:35840
	ds_read_b128 v[194:197], v135 offset:36864
	ds_read_b128 v[198:201], v135 offset:37888
	ds_read_b128 v[202:205], v135 offset:38912
	ds_read_b128 v[206:209], v135 offset:39936
	global_load_lds_dwordx4 v[218:219], off
	v_lshl_add_u64 v[218:219], s[14:15], 0, v[150:151]
	s_mov_b32 m0, s22
	s_nop 0
	global_load_lds_dwordx4 v[218:219], off
	s_waitcnt vmcnt(8)
	s_waitcnt lgkmcnt(0)
	s_barrier
	s_setprio 1
	s_waitcnt lgkmcnt(0)
	v_mfma_f32_16x16x32_bf16 v[126:129], v[138:141], v[178:181], v[126:129]
	v_mfma_f32_16x16x32_bf16 v[122:125], v[154:157], v[178:181], v[122:125]
	v_mfma_f32_16x16x32_bf16 v[118:121], v[138:141], v[186:189], v[118:121]
	v_mfma_f32_16x16x32_bf16 v[114:117], v[154:157], v[186:189], v[114:117]
	v_mfma_f32_16x16x32_bf16 v[102:105], v[138:141], v[194:197], v[102:105]
	v_mfma_f32_16x16x32_bf16 v[98:101], v[154:157], v[194:197], v[98:101]
	v_mfma_f32_16x16x32_bf16 v[86:89], v[138:141], v[202:205], v[86:89]
	v_mfma_f32_16x16x32_bf16 v[82:85], v[154:157], v[202:205], v[82:85]
	v_mfma_f32_16x16x32_bf16 v[126:129], v[142:145], v[182:185], v[126:129]
	v_mfma_f32_16x16x32_bf16 v[122:125], v[158:161], v[182:185], v[122:125]
	v_mfma_f32_16x16x32_bf16 v[118:121], v[142:145], v[190:193], v[118:121]
	v_mfma_f32_16x16x32_bf16 v[114:117], v[158:161], v[190:193], v[114:117]
	v_mfma_f32_16x16x32_bf16 v[102:105], v[142:145], v[198:201], v[102:105]
	v_mfma_f32_16x16x32_bf16 v[98:101], v[158:161], v[198:201], v[98:101]
	v_mfma_f32_16x16x32_bf16 v[86:89], v[142:145], v[206:209], v[86:89]
	v_mfma_f32_16x16x32_bf16 v[82:85], v[158:161], v[206:209], v[82:85]
	s_setprio 0
	s_setprio 1
	v_mfma_f32_16x16x32_bf16 v[110:113], v[162:165], v[178:181], v[110:113]
	v_mfma_f32_16x16x32_bf16 v[106:109], v[170:173], v[178:181], v[106:109]
	v_mfma_f32_16x16x32_bf16 v[94:97], v[162:165], v[186:189], v[94:97]
	v_mfma_f32_16x16x32_bf16 v[90:93], v[170:173], v[186:189], v[90:93]
	v_mfma_f32_16x16x32_bf16 v[78:81], v[162:165], v[194:197], v[78:81]
	v_mfma_f32_16x16x32_bf16 v[74:77], v[170:173], v[194:197], v[74:77]
	v_mfma_f32_16x16x32_bf16 v[70:73], v[162:165], v[202:205], v[70:73]
	v_mfma_f32_16x16x32_bf16 v[66:69], v[170:173], v[202:205], v[66:69]
	v_mfma_f32_16x16x32_bf16 v[110:113], v[166:169], v[182:185], v[110:113]
	v_mfma_f32_16x16x32_bf16 v[106:109], v[174:177], v[182:185], v[106:109]
	v_mfma_f32_16x16x32_bf16 v[94:97], v[166:169], v[190:193], v[94:97]
	v_mfma_f32_16x16x32_bf16 v[90:93], v[174:177], v[190:193], v[90:93]
	v_mfma_f32_16x16x32_bf16 v[78:81], v[166:169], v[198:201], v[78:81]
	v_mfma_f32_16x16x32_bf16 v[74:77], v[174:177], v[198:201], v[74:77]
	v_mfma_f32_16x16x32_bf16 v[70:73], v[166:169], v[206:209], v[70:73]
	v_mfma_f32_16x16x32_bf16 v[66:69], v[174:177], v[206:209], v[66:69]
	s_setprio 0
	s_barrier
	s_mov_b32 m0, s51
	v_lshl_add_u64 v[210:211], v[210:211], 0, s[8:9]
	s_add_u32 s12, s12, 0x158080
	ds_read_b128 v[178:181], v135 offset:49152
	ds_read_b128 v[182:185], v135 offset:50176
	ds_read_b128 v[186:189], v135 offset:51200
	ds_read_b128 v[190:193], v135 offset:52224
	ds_read_b128 v[194:197], v135 offset:53248
	ds_read_b128 v[198:201], v135 offset:54272
	ds_read_b128 v[202:205], v135 offset:55296
	ds_read_b128 v[206:209], v135 offset:56320
	global_load_lds_dwordx4 v[210:211], off
	v_lshl_add_u64 v[210:211], v[212:213], 0, s[8:9]
	s_mov_b32 m0, s52
	s_addc_u32 s13, s13, 0
	global_load_lds_dwordx4 v[210:211], off
	v_lshl_add_u64 v[210:211], s[12:13], 0, v[148:149]
	s_mov_b32 m0, s53
	s_nop 0
	global_load_lds_dwordx4 v[210:211], off
	v_lshl_add_u64 v[210:211], s[12:13], 0, v[152:153]
	s_mov_b32 m0, s54
	s_nop 0
	global_load_lds_dwordx4 v[210:211], off
	v_lshl_add_u64 v[210:211], v[214:215], 0, s[8:9]
	s_mov_b32 m0, s34
	s_nop 0
	global_load_lds_dwordx4 v[210:211], off
	v_lshl_add_u64 v[210:211], v[216:217], 0, s[8:9]
	s_mov_b32 m0, s35
	s_nop 0
	global_load_lds_dwordx4 v[210:211], off
	s_waitcnt vmcnt(8)
	s_waitcnt lgkmcnt(0)
	s_barrier
	s_setprio 1
	s_waitcnt lgkmcnt(0)
	v_mfma_f32_16x16x32_bf16 v[62:65], v[138:141], v[178:181], v[62:65]
	v_mfma_f32_16x16x32_bf16 v[58:61], v[154:157], v[178:181], v[58:61]
	v_mfma_f32_16x16x32_bf16 v[54:57], v[138:141], v[186:189], v[54:57]
	v_mfma_f32_16x16x32_bf16 v[50:53], v[154:157], v[186:189], v[50:53]
	v_mfma_f32_16x16x32_bf16 v[38:41], v[138:141], v[194:197], v[38:41]
	v_mfma_f32_16x16x32_bf16 v[34:37], v[154:157], v[194:197], v[34:37]
	v_mfma_f32_16x16x32_bf16 v[22:25], v[138:141], v[202:205], v[22:25]
	v_mfma_f32_16x16x32_bf16 v[18:21], v[154:157], v[202:205], v[18:21]
	v_mfma_f32_16x16x32_bf16 v[62:65], v[142:145], v[182:185], v[62:65]
	v_mfma_f32_16x16x32_bf16 v[58:61], v[158:161], v[182:185], v[58:61]
	v_mfma_f32_16x16x32_bf16 v[54:57], v[142:145], v[190:193], v[54:57]
	v_mfma_f32_16x16x32_bf16 v[50:53], v[158:161], v[190:193], v[50:53]
	v_mfma_f32_16x16x32_bf16 v[38:41], v[142:145], v[198:201], v[38:41]
	v_mfma_f32_16x16x32_bf16 v[34:37], v[158:161], v[198:201], v[34:37]
	v_mfma_f32_16x16x32_bf16 v[22:25], v[142:145], v[206:209], v[22:25]
	v_mfma_f32_16x16x32_bf16 v[18:21], v[158:161], v[206:209], v[18:21]
	s_setprio 0
	s_setprio 1
	v_mfma_f32_16x16x32_bf16 v[46:49], v[162:165], v[178:181], v[46:49]
	v_mfma_f32_16x16x32_bf16 v[42:45], v[170:173], v[178:181], v[42:45]
	v_mfma_f32_16x16x32_bf16 v[30:33], v[162:165], v[186:189], v[30:33]
	v_mfma_f32_16x16x32_bf16 v[26:29], v[170:173], v[186:189], v[26:29]
	v_mfma_f32_16x16x32_bf16 v[14:17], v[162:165], v[194:197], v[14:17]
	v_mfma_f32_16x16x32_bf16 v[10:13], v[170:173], v[194:197], v[10:13]
	v_mfma_f32_16x16x32_bf16 v[6:9], v[162:165], v[202:205], v[6:9]
	v_mfma_f32_16x16x32_bf16 v[2:5], v[170:173], v[202:205], v[2:5]
	v_mfma_f32_16x16x32_bf16 v[46:49], v[166:169], v[182:185], v[46:49]
	v_mfma_f32_16x16x32_bf16 v[42:45], v[174:177], v[182:185], v[42:45]
	v_mfma_f32_16x16x32_bf16 v[30:33], v[166:169], v[190:193], v[30:33]
	v_mfma_f32_16x16x32_bf16 v[26:29], v[174:177], v[190:193], v[26:29]
	v_mfma_f32_16x16x32_bf16 v[14:17], v[166:169], v[198:201], v[14:17]
	v_mfma_f32_16x16x32_bf16 v[10:13], v[174:177], v[198:201], v[10:13]
	v_mfma_f32_16x16x32_bf16 v[6:9], v[166:169], v[206:209], v[6:9]
	v_mfma_f32_16x16x32_bf16 v[2:5], v[174:177], v[206:209], v[2:5]
	s_setprio 0
	s_add_i32 s7, s7, 2
	s_cmp_ge_u32 s7, s1
	s_barrier
	s_cbranch_scc0 .LBB0_1740
	s_cmpk_lt_u32 s20, 0x100
	s_cbranch_scc0 .LBB0_1743
	s_barrier

.LBB0_2203:
	s_add_u32 s67, s22, s44
	s_addc_u32 s68, s23, s45
	s_add_u32 s26, s44, 0x100
	s_addc_u32 s27, s45, 0
	v_cmp_lt_u64_e32 vcc, s[26:27], v[142:143]
	s_and_b64 s[46:47], vcc, exec
	s_cselect_b32 s49, 0, 0xfffff000
	s_cselect_b32 s48, 0, -1
	s_add_u32 s46, s49, s26
	s_addc_u32 s47, s48, s27
	s_add_u32 s26, s49, s44
	s_addc_u32 s27, s48, s45
	ds_read_b128 v[152:155], v148
	ds_read_b128 v[156:159], v148 offset:1024
	ds_read_b128 v[160:163], v148 offset:2048
	ds_read_b128 v[164:167], v148 offset:3072
	ds_read_b128 v[168:171], v149
	ds_read_b128 v[172:175], v149 offset:1024
	ds_read_b128 v[176:179], v149 offset:2048
	ds_read_b128 v[180:183], v149 offset:3072
	s_add_u32 s44, s67, s49
	s_addc_u32 s45, s68, s48
	s_add_u32 s44, s44, 0x100
	s_addc_u32 s45, s45, 0
	s_add_u32 s26, s20, s26
	s_addc_u32 s27, s21, s27
	s_add_u32 s26, s26, 0x100
	s_addc_u32 s27, s27, 0
	s_cmp_eq_u32 s35, 28
	s_cselect_b32 s49, s3, s45
	s_cselect_b32 s48, s13, s44
	s_cselect_b32 s45, s11, s27
	s_cselect_b32 s44, s34, s26
	s_add_u32 s26, s67, 0x80080
	s_addc_u32 s27, s68, 0
	v_lshl_add_u64 v[144:145], s[26:27], 0, v[130:131]
	s_add_i32 m0, s19, 0xc000
	ds_read_b128 v[184:187], v150
	ds_read_b128 v[188:191], v150 offset:1024
	ds_read_b128 v[192:195], v150 offset:2048
	ds_read_b128 v[196:199], v150 offset:3072
	ds_read_b128 v[200:203], v150 offset:4096
	ds_read_b128 v[204:207], v150 offset:5120
	ds_read_b128 v[208:211], v150 offset:6144
	ds_read_b128 v[212:215], v150 offset:7168
	global_load_lds_dwordx4 v[144:145], off
	v_lshl_add_u64 v[144:145], s[26:27], 0, v[134:135]
	s_add_i32 m0, s19, 0xe000
	s_nop 0
	global_load_lds_dwordx4 v[144:145], off
	s_waitcnt vmcnt(8)
	s_waitcnt lgkmcnt(0)
	s_barrier
	s_setprio 1
	s_waitcnt lgkmcnt(0)
	v_mfma_f32_16x16x32_bf16 v[126:129], v[152:155], v[184:187], v[126:129]
	v_mfma_f32_16x16x32_bf16 v[122:125], v[160:163], v[184:187], v[122:125]
	v_mfma_f32_16x16x32_bf16 v[110:113], v[152:155], v[192:195], v[110:113]
	v_mfma_f32_16x16x32_bf16 v[106:109], v[160:163], v[192:195], v[106:109]
	v_mfma_f32_16x16x32_bf16 v[94:97], v[152:155], v[200:203], v[94:97]
	v_mfma_f32_16x16x32_bf16 v[90:93], v[160:163], v[200:203], v[90:93]
	v_mfma_f32_16x16x32_bf16 v[78:81], v[152:155], v[208:211], v[78:81]
	v_mfma_f32_16x16x32_bf16 v[74:77], v[160:163], v[208:211], v[74:77]
	v_mfma_f32_16x16x32_bf16 v[126:129], v[156:159], v[188:191], v[126:129]
	v_mfma_f32_16x16x32_bf16 v[122:125], v[164:167], v[188:191], v[122:125]
	v_mfma_f32_16x16x32_bf16 v[110:113], v[156:159], v[196:199], v[110:113]
	v_mfma_f32_16x16x32_bf16 v[106:109], v[164:167], v[196:199], v[106:109]
	v_mfma_f32_16x16x32_bf16 v[94:97], v[156:159], v[204:207], v[94:97]
	v_mfma_f32_16x16x32_bf16 v[90:93], v[164:167], v[204:207], v[90:93]
	v_mfma_f32_16x16x32_bf16 v[78:81], v[156:159], v[212:215], v[78:81]
	v_mfma_f32_16x16x32_bf16 v[74:77], v[164:167], v[212:215], v[74:77]
	s_setprio 0
	s_setprio 1
	v_mfma_f32_16x16x32_bf16 v[118:121], v[168:171], v[184:187], v[118:121]
	v_mfma_f32_16x16x32_bf16 v[114:117], v[176:179], v[184:187], v[114:117]
	v_mfma_f32_16x16x32_bf16 v[102:105], v[168:171], v[192:195], v[102:105]
	v_mfma_f32_16x16x32_bf16 v[98:101], v[176:179], v[192:195], v[98:101]
	v_mfma_f32_16x16x32_bf16 v[86:89], v[168:171], v[200:203], v[86:89]
	v_mfma_f32_16x16x32_bf16 v[82:85], v[176:179], v[200:203], v[82:85]
	v_mfma_f32_16x16x32_bf16 v[70:73], v[168:171], v[208:211], v[70:73]
	v_mfma_f32_16x16x32_bf16 v[66:69], v[176:179], v[208:211], v[66:69]
	v_mfma_f32_16x16x32_bf16 v[118:121], v[172:175], v[188:191], v[118:121]
	v_mfma_f32_16x16x32_bf16 v[114:117], v[180:183], v[188:191], v[114:117]
	v_mfma_f32_16x16x32_bf16 v[102:105], v[172:175], v[196:199], v[102:105]
	v_mfma_f32_16x16x32_bf16 v[98:101], v[180:183], v[196:199], v[98:101]
	v_mfma_f32_16x16x32_bf16 v[86:89], v[172:175], v[204:207], v[86:89]
	v_mfma_f32_16x16x32_bf16 v[82:85], v[180:183], v[204:207], v[82:85]
	v_mfma_f32_16x16x32_bf16 v[70:73], v[172:175], v[212:215], v[70:73]
	v_mfma_f32_16x16x32_bf16 v[66:69], v[180:183], v[212:215], v[66:69]
	s_setprio 0
	s_barrier
	s_add_i32 s26, s62, s52
	v_lshl_add_u64 v[144:145], s[44:45], 0, v[132:133]
	s_mov_b32 m0, s26
	ds_read_b128 v[184:187], v150 offset:16384
	ds_read_b128 v[188:191], v150 offset:17408
	ds_read_b128 v[192:195], v150 offset:18432
	ds_read_b128 v[196:199], v150 offset:19456
	ds_read_b128 v[200:203], v150 offset:20480
	ds_read_b128 v[204:207], v150 offset:21504
	ds_read_b128 v[208:211], v150 offset:22528
	ds_read_b128 v[212:215], v150 offset:23552
	global_load_lds_dwordx4 v[144:145], off
	s_add_i32 m0, s26, 0x2000
	s_add_u32 s26, s44, 0x80000
	v_lshl_add_u64 v[216:217], s[44:45], 0, v[136:137]
	s_addc_u32 s27, s45, 0
	s_add_i32 s67, s63, s52
	global_load_lds_dwordx4 v[216:217], off
	v_lshl_add_u64 v[218:219], s[26:27], 0, v[132:133]
	s_mov_b32 m0, s67
	v_lshl_add_u64 v[220:221], s[48:49], 0, v[134:135]
	global_load_lds_dwordx4 v[218:219], off
	v_lshl_add_u64 v[218:219], s[26:27], 0, v[136:137]
	s_add_i32 m0, s67, 0x2000
	s_nop 0
	global_load_lds_dwordx4 v[218:219], off
	v_lshl_add_u64 v[218:219], s[48:49], 0, v[130:131]
	s_mov_b32 m0, s19
	s_nop 0
	global_load_lds_dwordx4 v[218:219], off
	s_mov_b32 m0, s53
	s_nop 0
	global_load_lds_dwordx4 v[220:221], off
	s_waitcnt vmcnt(8)
	s_waitcnt lgkmcnt(0)
	s_barrier
	s_setprio 1
	s_waitcnt lgkmcnt(0)
	v_mfma_f32_16x16x32_bf16 v[62:65], v[152:155], v[184:187], v[62:65]
	v_mfma_f32_16x16x32_bf16 v[58:61], v[160:163], v[184:187], v[58:61]
	v_mfma_f32_16x16x32_bf16 v[46:49], v[152:155], v[192:195], v[46:49]
	v_mfma_f32_16x16x32_bf16 v[42:45], v[160:163], v[192:195], v[42:45]
	v_mfma_f32_16x16x32_bf16 v[30:33], v[152:155], v[200:203], v[30:33]
	v_mfma_f32_16x16x32_bf16 v[26:29], v[160:163], v[200:203], v[26:29]
	v_mfma_f32_16x16x32_bf16 v[14:17], v[152:155], v[208:211], v[14:17]
	v_mfma_f32_16x16x32_bf16 v[10:13], v[160:163], v[208:211], v[10:13]
	v_mfma_f32_16x16x32_bf16 v[62:65], v[156:159], v[188:191], v[62:65]
	v_mfma_f32_16x16x32_bf16 v[58:61], v[164:167], v[188:191], v[58:61]
	v_mfma_f32_16x16x32_bf16 v[46:49], v[156:159], v[196:199], v[46:49]
	v_mfma_f32_16x16x32_bf16 v[42:45], v[164:167], v[196:199], v[42:45]
	v_mfma_f32_16x16x32_bf16 v[30:33], v[156:159], v[204:207], v[30:33]
	v_mfma_f32_16x16x32_bf16 v[26:29], v[164:167], v[204:207], v[26:29]
	v_mfma_f32_16x16x32_bf16 v[14:17], v[156:159], v[212:215], v[14:17]
	v_mfma_f32_16x16x32_bf16 v[10:13], v[164:167], v[212:215], v[10:13]
	s_setprio 0
	s_setprio 1
	v_mfma_f32_16x16x32_bf16 v[54:57], v[168:171], v[184:187], v[54:57]
	v_mfma_f32_16x16x32_bf16 v[50:53], v[176:179], v[184:187], v[50:53]
	v_mfma_f32_16x16x32_bf16 v[38:41], v[168:171], v[192:195], v[38:41]
	v_mfma_f32_16x16x32_bf16 v[34:37], v[176:179], v[192:195], v[34:37]
	v_mfma_f32_16x16x32_bf16 v[22:25], v[168:171], v[200:203], v[22:25]
	v_mfma_f32_16x16x32_bf16 v[18:21], v[176:179], v[200:203], v[18:21]
	v_mfma_f32_16x16x32_bf16 v[6:9], v[168:171], v[208:211], v[6:9]
	v_mfma_f32_16x16x32_bf16 v[2:5], v[176:179], v[208:211], v[2:5]
	v_mfma_f32_16x16x32_bf16 v[54:57], v[172:175], v[188:191], v[54:57]
	v_mfma_f32_16x16x32_bf16 v[50:53], v[180:183], v[188:191], v[50:53]
	v_mfma_f32_16x16x32_bf16 v[38:41], v[172:175], v[196:199], v[38:41]
	v_mfma_f32_16x16x32_bf16 v[34:37], v[180:183], v[196:199], v[34:37]
	v_mfma_f32_16x16x32_bf16 v[22:25], v[172:175], v[204:207], v[22:25]
	v_mfma_f32_16x16x32_bf16 v[18:21], v[180:183], v[204:207], v[18:21]
	v_mfma_f32_16x16x32_bf16 v[6:9], v[172:175], v[212:215], v[6:9]
	v_mfma_f32_16x16x32_bf16 v[2:5], v[180:183], v[212:215], v[2:5]
	s_setprio 0
	s_barrier
	s_add_i32 s67, 0, 0x18000
	v_add_u32_e32 v151, s67, v146
	s_add_i32 s68, 0, 0x1c000
	ds_read_b128 v[152:155], v151
	ds_read_b128 v[156:159], v151 offset:1024
	ds_read_b128 v[160:163], v151 offset:2048
	ds_read_b128 v[164:167], v151 offset:3072
	v_add_u32_e32 v151, s68, v146
	ds_read_b128 v[168:171], v151
	ds_read_b128 v[172:175], v151 offset:1024
	ds_read_b128 v[176:179], v151 offset:2048
	ds_read_b128 v[180:183], v151 offset:3072
	s_add_u32 s26, s48, 0x80000
	s_addc_u32 s27, s49, 0
	s_mov_b32 m0, s54
	v_lshl_add_u64 v[222:223], s[26:27], 0, v[130:131]
	ds_read_b128 v[184:187], v150 offset:32768
	ds_read_b128 v[188:191], v150 offset:33792
	ds_read_b128 v[192:195], v150 offset:34816
	ds_read_b128 v[196:199], v150 offset:35840
	ds_read_b128 v[200:203], v150 offset:36864
	ds_read_b128 v[204:207], v150 offset:37888
	ds_read_b128 v[208:211], v150 offset:38912
	ds_read_b128 v[212:215], v150 offset:39936
	global_load_lds_dwordx4 v[222:223], off
	v_lshl_add_u64 v[222:223], s[26:27], 0, v[134:135]
	s_mov_b32 m0, s55
	s_nop 0
	global_load_lds_dwordx4 v[222:223], off
	s_waitcnt vmcnt(8)
	s_waitcnt lgkmcnt(0)
	s_barrier
	s_setprio 1
	s_waitcnt lgkmcnt(0)
	v_mfma_f32_16x16x32_bf16 v[126:129], v[152:155], v[184:187], v[126:129]
	v_mfma_f32_16x16x32_bf16 v[122:125], v[160:163], v[184:187], v[122:125]
	v_mfma_f32_16x16x32_bf16 v[110:113], v[152:155], v[192:195], v[110:113]
	v_mfma_f32_16x16x32_bf16 v[106:109], v[160:163], v[192:195], v[106:109]
	v_mfma_f32_16x16x32_bf16 v[94:97], v[152:155], v[200:203], v[94:97]
	v_mfma_f32_16x16x32_bf16 v[90:93], v[160:163], v[200:203], v[90:93]
	v_mfma_f32_16x16x32_bf16 v[78:81], v[152:155], v[208:211], v[78:81]
	v_mfma_f32_16x16x32_bf16 v[74:77], v[160:163], v[208:211], v[74:77]
	v_mfma_f32_16x16x32_bf16 v[126:129], v[156:159], v[188:191], v[126:129]
	v_mfma_f32_16x16x32_bf16 v[122:125], v[164:167], v[188:191], v[122:125]
	v_mfma_f32_16x16x32_bf16 v[110:113], v[156:159], v[196:199], v[110:113]
	v_mfma_f32_16x16x32_bf16 v[106:109], v[164:167], v[196:199], v[106:109]
	v_mfma_f32_16x16x32_bf16 v[94:97], v[156:159], v[204:207], v[94:97]
	v_mfma_f32_16x16x32_bf16 v[90:93], v[164:167], v[204:207], v[90:93]
	v_mfma_f32_16x16x32_bf16 v[78:81], v[156:159], v[212:215], v[78:81]
	v_mfma_f32_16x16x32_bf16 v[74:77], v[164:167], v[212:215], v[74:77]
	s_setprio 0
	s_setprio 1
	v_mfma_f32_16x16x32_bf16 v[118:121], v[168:171], v[184:187], v[118:121]
	v_mfma_f32_16x16x32_bf16 v[114:117], v[176:179], v[184:187], v[114:117]
	v_mfma_f32_16x16x32_bf16 v[102:105], v[168:171], v[192:195], v[102:105]
	v_mfma_f32_16x16x32_bf16 v[98:101], v[176:179], v[192:195], v[98:101]
	v_mfma_f32_16x16x32_bf16 v[86:89], v[168:171], v[200:203], v[86:89]
	v_mfma_f32_16x16x32_bf16 v[82:85], v[176:179], v[200:203], v[82:85]
	v_mfma_f32_16x16x32_bf16 v[70:73], v[168:171], v[208:211], v[70:73]
	v_mfma_f32_16x16x32_bf16 v[66:69], v[176:179], v[208:211], v[66:69]
	v_mfma_f32_16x16x32_bf16 v[118:121], v[172:175], v[188:191], v[118:121]
	v_mfma_f32_16x16x32_bf16 v[114:117], v[180:183], v[188:191], v[114:117]
	v_mfma_f32_16x16x32_bf16 v[102:105], v[172:175], v[196:199], v[102:105]
	v_mfma_f32_16x16x32_bf16 v[98:101], v[180:183], v[196:199], v[98:101]
	v_mfma_f32_16x16x32_bf16 v[86:89], v[172:175], v[204:207], v[86:89]
	v_mfma_f32_16x16x32_bf16 v[82:85], v[180:183], v[204:207], v[82:85]
	v_mfma_f32_16x16x32_bf16 v[70:73], v[172:175], v[212:215], v[70:73]
	v_mfma_f32_16x16x32_bf16 v[66:69], v[180:183], v[212:215], v[66:69]
	s_setprio 0
	s_barrier
	s_add_i32 s26, s67, s52
	v_lshl_add_u64 v[144:145], v[144:145], 0, s[6:7]
	s_mov_b32 m0, s26
	ds_read_b128 v[184:187], v150 offset:49152
	ds_read_b128 v[188:191], v150 offset:50176
	ds_read_b128 v[192:195], v150 offset:51200
	ds_read_b128 v[196:199], v150 offset:52224
	ds_read_b128 v[200:203], v150 offset:53248
	ds_read_b128 v[204:207], v150 offset:54272
	ds_read_b128 v[208:211], v150 offset:55296
	ds_read_b128 v[212:215], v150 offset:56320
	global_load_lds_dwordx4 v[144:145], off
	s_add_i32 m0, s26, 0x2000
	s_add_u32 s26, s44, 0x80080
	v_lshl_add_u64 v[144:145], v[216:217], 0, s[6:7]
	s_addc_u32 s27, s45, 0
	s_add_i32 s44, s68, s52
	global_load_lds_dwordx4 v[144:145], off
	v_lshl_add_u64 v[144:145], s[26:27], 0, v[132:133]
	s_mov_b32 m0, s44
	s_nop 0
	global_load_lds_dwordx4 v[144:145], off
	v_lshl_add_u64 v[144:145], s[26:27], 0, v[136:137]
	s_add_i32 m0, s44, 0x2000
	s_nop 0
	global_load_lds_dwordx4 v[144:145], off
	v_lshl_add_u64 v[144:145], v[218:219], 0, s[6:7]
	s_mov_b32 m0, s59
	s_nop 0
	global_load_lds_dwordx4 v[144:145], off
	v_lshl_add_u64 v[144:145], v[220:221], 0, s[6:7]
	s_mov_b32 m0, s60
	s_nop 0
	global_load_lds_dwordx4 v[144:145], off
	s_waitcnt vmcnt(8)
	s_waitcnt lgkmcnt(0)
	s_barrier
	s_setprio 1
	s_waitcnt lgkmcnt(0)
	v_mfma_f32_16x16x32_bf16 v[62:65], v[152:155], v[184:187], v[62:65]
	v_mfma_f32_16x16x32_bf16 v[58:61], v[160:163], v[184:187], v[58:61]
	v_mfma_f32_16x16x32_bf16 v[46:49], v[152:155], v[192:195], v[46:49]
	v_mfma_f32_16x16x32_bf16 v[42:45], v[160:163], v[192:195], v[42:45]
	v_mfma_f32_16x16x32_bf16 v[30:33], v[152:155], v[200:203], v[30:33]
	v_mfma_f32_16x16x32_bf16 v[26:29], v[160:163], v[200:203], v[26:29]
	v_mfma_f32_16x16x32_bf16 v[14:17], v[152:155], v[208:211], v[14:17]
	v_mfma_f32_16x16x32_bf16 v[10:13], v[160:163], v[208:211], v[10:13]
	v_mfma_f32_16x16x32_bf16 v[62:65], v[156:159], v[188:191], v[62:65]
	v_mfma_f32_16x16x32_bf16 v[58:61], v[164:167], v[188:191], v[58:61]
	v_mfma_f32_16x16x32_bf16 v[46:49], v[156:159], v[196:199], v[46:49]
	v_mfma_f32_16x16x32_bf16 v[42:45], v[164:167], v[196:199], v[42:45]
	v_mfma_f32_16x16x32_bf16 v[30:33], v[156:159], v[204:207], v[30:33]
	v_mfma_f32_16x16x32_bf16 v[26:29], v[164:167], v[204:207], v[26:29]
	v_mfma_f32_16x16x32_bf16 v[14:17], v[156:159], v[212:215], v[14:17]
	v_mfma_f32_16x16x32_bf16 v[10:13], v[164:167], v[212:215], v[10:13]
	s_setprio 0
	s_setprio 1
	v_mfma_f32_16x16x32_bf16 v[54:57], v[168:171], v[184:187], v[54:57]
	v_mfma_f32_16x16x32_bf16 v[50:53], v[176:179], v[184:187], v[50:53]
	v_mfma_f32_16x16x32_bf16 v[38:41], v[168:171], v[192:195], v[38:41]
	v_mfma_f32_16x16x32_bf16 v[34:37], v[176:179], v[192:195], v[34:37]
	v_mfma_f32_16x16x32_bf16 v[22:25], v[168:171], v[200:203], v[22:25]
	v_mfma_f32_16x16x32_bf16 v[18:21], v[176:179], v[200:203], v[18:21]
	v_mfma_f32_16x16x32_bf16 v[6:9], v[168:171], v[208:211], v[6:9]
	v_mfma_f32_16x16x32_bf16 v[2:5], v[176:179], v[208:211], v[2:5]
	v_mfma_f32_16x16x32_bf16 v[54:57], v[172:175], v[188:191], v[54:57]
	v_mfma_f32_16x16x32_bf16 v[50:53], v[180:183], v[188:191], v[50:53]
	v_mfma_f32_16x16x32_bf16 v[38:41], v[172:175], v[196:199], v[38:41]
	v_mfma_f32_16x16x32_bf16 v[34:37], v[180:183], v[196:199], v[34:37]
	v_mfma_f32_16x16x32_bf16 v[22:25], v[172:175], v[204:207], v[22:25]
	v_mfma_f32_16x16x32_bf16 v[18:21], v[180:183], v[204:207], v[18:21]
	v_mfma_f32_16x16x32_bf16 v[6:9], v[172:175], v[212:215], v[6:9]
	v_mfma_f32_16x16x32_bf16 v[2:5], v[180:183], v[212:215], v[2:5]
	s_setprio 0
	s_add_i32 s35, s35, 2
	s_cmp_gt_u32 s35, 29
	s_mov_b64 s[44:45], s[46:47]
	s_barrier
	s_cbranch_scc0 .LBB0_2203
	s_and_b64 vcc, exec, s[8:9]
	s_cbranch_vccz .LBB0_2206
	s_barrier

.LBB0_2387:
	s_add_u32 s77, s44, s46
	s_addc_u32 s80, s45, s47
	s_add_u32 s26, s46, 0x100
	s_addc_u32 s27, s47, 0
	v_cmp_lt_u64_e32 vcc, s[26:27], v[142:143]
	s_and_b64 s[48:49], vcc, exec
	s_cselect_b32 s51, 0, 0xfffffc00
	s_cselect_b32 s50, 0, -1
	s_add_u32 s48, s51, s26
	s_addc_u32 s49, s50, s27
	s_add_u32 s26, s51, s46
	s_addc_u32 s27, s50, s47
	ds_read_b128 v[160:163], v157
	ds_read_b128 v[164:167], v157 offset:1024
	ds_read_b128 v[168:171], v157 offset:2048
	ds_read_b128 v[172:175], v157 offset:3072
	ds_read_b128 v[176:179], v158
	ds_read_b128 v[180:183], v158 offset:1024
	ds_read_b128 v[184:187], v158 offset:2048
	ds_read_b128 v[188:191], v158 offset:3072
	s_add_u32 s46, s77, s51
	s_addc_u32 s47, s80, s50
	s_add_u32 s46, s46, 0x100
	s_addc_u32 s47, s47, 0
	s_add_u32 s26, s22, s26
	s_addc_u32 s27, s23, s27
	s_add_u32 s26, s26, 0x100
	s_addc_u32 s27, s27, 0
	s_cmp_eq_u32 s35, 4
	s_cselect_b32 s51, s3, s47
	s_cselect_b32 s50, s15, s46
	s_cselect_b32 s47, s13, s27
	s_cselect_b32 s46, s34, s26
	s_add_u32 s26, s77, 0x20080
	s_addc_u32 s27, s80, 0
	v_lshl_add_u64 v[144:145], s[26:27], 0, v[130:131]
	s_add_i32 m0, s21, 0xc000
	ds_read_b128 v[192:195], v159
	ds_read_b128 v[196:199], v159 offset:1024
	ds_read_b128 v[200:203], v159 offset:2048
	ds_read_b128 v[204:207], v159 offset:3072
	ds_read_b128 v[208:211], v159 offset:4096
	ds_read_b128 v[212:215], v159 offset:5120
	ds_read_b128 v[216:219], v159 offset:6144
	ds_read_b128 v[220:223], v159 offset:7168
	global_load_lds_dwordx4 v[144:145], off
	v_lshl_add_u64 v[144:145], s[26:27], 0, v[134:135]
	s_add_i32 m0, s21, 0xe000
	s_nop 0
	global_load_lds_dwordx4 v[144:145], off
	s_waitcnt vmcnt(8)
	s_waitcnt lgkmcnt(0)
	s_barrier
	s_setprio 1
	s_waitcnt lgkmcnt(0)
	v_mfma_f32_16x16x32_bf16 v[126:129], v[160:163], v[192:195], v[126:129]
	v_mfma_f32_16x16x32_bf16 v[122:125], v[168:171], v[192:195], v[122:125]
	v_mfma_f32_16x16x32_bf16 v[110:113], v[160:163], v[200:203], v[110:113]
	v_mfma_f32_16x16x32_bf16 v[106:109], v[168:171], v[200:203], v[106:109]
	v_mfma_f32_16x16x32_bf16 v[94:97], v[160:163], v[208:211], v[94:97]
	v_mfma_f32_16x16x32_bf16 v[90:93], v[168:171], v[208:211], v[90:93]
	v_mfma_f32_16x16x32_bf16 v[78:81], v[160:163], v[216:219], v[78:81]
	v_mfma_f32_16x16x32_bf16 v[74:77], v[168:171], v[216:219], v[74:77]
	v_mfma_f32_16x16x32_bf16 v[126:129], v[164:167], v[196:199], v[126:129]
	v_mfma_f32_16x16x32_bf16 v[122:125], v[172:175], v[196:199], v[122:125]
	v_mfma_f32_16x16x32_bf16 v[110:113], v[164:167], v[204:207], v[110:113]
	v_mfma_f32_16x16x32_bf16 v[106:109], v[172:175], v[204:207], v[106:109]
	v_mfma_f32_16x16x32_bf16 v[94:97], v[164:167], v[212:215], v[94:97]
	v_mfma_f32_16x16x32_bf16 v[90:93], v[172:175], v[212:215], v[90:93]
	v_mfma_f32_16x16x32_bf16 v[78:81], v[164:167], v[220:223], v[78:81]
	v_mfma_f32_16x16x32_bf16 v[74:77], v[172:175], v[220:223], v[74:77]
	s_setprio 0
	s_setprio 1
	v_mfma_f32_16x16x32_bf16 v[118:121], v[176:179], v[192:195], v[118:121]
	v_mfma_f32_16x16x32_bf16 v[114:117], v[184:187], v[192:195], v[114:117]
	v_mfma_f32_16x16x32_bf16 v[102:105], v[176:179], v[200:203], v[102:105]
	v_mfma_f32_16x16x32_bf16 v[98:101], v[184:187], v[200:203], v[98:101]
	v_mfma_f32_16x16x32_bf16 v[86:89], v[176:179], v[208:211], v[86:89]
	v_mfma_f32_16x16x32_bf16 v[82:85], v[184:187], v[208:211], v[82:85]
	v_mfma_f32_16x16x32_bf16 v[70:73], v[176:179], v[216:219], v[70:73]
	v_mfma_f32_16x16x32_bf16 v[66:69], v[184:187], v[216:219], v[66:69]
	v_mfma_f32_16x16x32_bf16 v[118:121], v[180:183], v[196:199], v[118:121]
	v_mfma_f32_16x16x32_bf16 v[114:117], v[188:191], v[196:199], v[114:117]
	v_mfma_f32_16x16x32_bf16 v[102:105], v[180:183], v[204:207], v[102:105]
	v_mfma_f32_16x16x32_bf16 v[98:101], v[188:191], v[204:207], v[98:101]
	v_mfma_f32_16x16x32_bf16 v[86:89], v[180:183], v[212:215], v[86:89]
	v_mfma_f32_16x16x32_bf16 v[82:85], v[188:191], v[212:215], v[82:85]
	v_mfma_f32_16x16x32_bf16 v[70:73], v[180:183], v[220:223], v[70:73]
	v_mfma_f32_16x16x32_bf16 v[66:69], v[188:191], v[220:223], v[66:69]
	s_setprio 0
	s_barrier
	s_add_i32 s26, s69, s58
	v_lshl_add_u64 v[144:145], s[46:47], 0, v[132:133]
	s_mov_b32 m0, s26
	ds_read_b128 v[192:195], v159 offset:16384
	ds_read_b128 v[196:199], v159 offset:17408
	ds_read_b128 v[200:203], v159 offset:18432
	ds_read_b128 v[204:207], v159 offset:19456
	ds_read_b128 v[208:211], v159 offset:20480
	ds_read_b128 v[212:215], v159 offset:21504
	ds_read_b128 v[216:219], v159 offset:22528
	ds_read_b128 v[220:223], v159 offset:23552
	global_load_lds_dwordx4 v[144:145], off
	s_add_i32 m0, s26, 0x2000
	s_add_u32 s26, s46, 0x20000
	v_lshl_add_u64 v[224:225], s[46:47], 0, v[136:137]
	s_addc_u32 s27, s47, 0
	s_add_i32 s77, s70, s58
	global_load_lds_dwordx4 v[224:225], off
	v_lshl_add_u64 v[226:227], s[26:27], 0, v[132:133]
	s_mov_b32 m0, s77
	v_lshl_add_u64 v[228:229], s[50:51], 0, v[134:135]
	global_load_lds_dwordx4 v[226:227], off
	v_lshl_add_u64 v[226:227], s[26:27], 0, v[136:137]
	s_add_i32 m0, s77, 0x2000
	s_nop 0
	global_load_lds_dwordx4 v[226:227], off
	v_lshl_add_u64 v[226:227], s[50:51], 0, v[130:131]
	s_mov_b32 m0, s21
	s_nop 0
	global_load_lds_dwordx4 v[226:227], off
	s_mov_b32 m0, s59
	s_nop 0
	global_load_lds_dwordx4 v[228:229], off
	s_waitcnt vmcnt(8)
	s_waitcnt lgkmcnt(0)
	s_barrier
	s_setprio 1
	s_waitcnt lgkmcnt(0)
	v_mfma_f32_16x16x32_bf16 v[62:65], v[160:163], v[192:195], v[62:65]
	v_mfma_f32_16x16x32_bf16 v[58:61], v[168:171], v[192:195], v[58:61]
	v_mfma_f32_16x16x32_bf16 v[46:49], v[160:163], v[200:203], v[46:49]
	v_mfma_f32_16x16x32_bf16 v[42:45], v[168:171], v[200:203], v[42:45]
	v_mfma_f32_16x16x32_bf16 v[30:33], v[160:163], v[208:211], v[30:33]
	v_mfma_f32_16x16x32_bf16 v[26:29], v[168:171], v[208:211], v[26:29]
	v_mfma_f32_16x16x32_bf16 v[14:17], v[160:163], v[216:219], v[14:17]
	v_mfma_f32_16x16x32_bf16 v[10:13], v[168:171], v[216:219], v[10:13]
	v_mfma_f32_16x16x32_bf16 v[62:65], v[164:167], v[196:199], v[62:65]
	v_mfma_f32_16x16x32_bf16 v[58:61], v[172:175], v[196:199], v[58:61]
	v_mfma_f32_16x16x32_bf16 v[46:49], v[164:167], v[204:207], v[46:49]
	v_mfma_f32_16x16x32_bf16 v[42:45], v[172:175], v[204:207], v[42:45]
	v_mfma_f32_16x16x32_bf16 v[30:33], v[164:167], v[212:215], v[30:33]
	v_mfma_f32_16x16x32_bf16 v[26:29], v[172:175], v[212:215], v[26:29]
	v_mfma_f32_16x16x32_bf16 v[14:17], v[164:167], v[220:223], v[14:17]
	v_mfma_f32_16x16x32_bf16 v[10:13], v[172:175], v[220:223], v[10:13]
	s_setprio 0
	s_setprio 1
	v_mfma_f32_16x16x32_bf16 v[54:57], v[176:179], v[192:195], v[54:57]
	v_mfma_f32_16x16x32_bf16 v[50:53], v[184:187], v[192:195], v[50:53]
	v_mfma_f32_16x16x32_bf16 v[38:41], v[176:179], v[200:203], v[38:41]
	v_mfma_f32_16x16x32_bf16 v[34:37], v[184:187], v[200:203], v[34:37]
	v_mfma_f32_16x16x32_bf16 v[22:25], v[176:179], v[208:211], v[22:25]
	v_mfma_f32_16x16x32_bf16 v[18:21], v[184:187], v[208:211], v[18:21]
	v_mfma_f32_16x16x32_bf16 v[6:9], v[176:179], v[216:219], v[6:9]
	v_mfma_f32_16x16x32_bf16 v[2:5], v[184:187], v[216:219], v[2:5]
	v_mfma_f32_16x16x32_bf16 v[54:57], v[180:183], v[196:199], v[54:57]
	v_mfma_f32_16x16x32_bf16 v[50:53], v[188:191], v[196:199], v[50:53]
	v_mfma_f32_16x16x32_bf16 v[38:41], v[180:183], v[204:207], v[38:41]
	v_mfma_f32_16x16x32_bf16 v[34:37], v[188:191], v[204:207], v[34:37]
	v_mfma_f32_16x16x32_bf16 v[22:25], v[180:183], v[212:215], v[22:25]
	v_mfma_f32_16x16x32_bf16 v[18:21], v[188:191], v[212:215], v[18:21]
	v_mfma_f32_16x16x32_bf16 v[6:9], v[180:183], v[220:223], v[6:9]
	v_mfma_f32_16x16x32_bf16 v[2:5], v[188:191], v[220:223], v[2:5]
	s_setprio 0
	s_barrier
	s_add_i32 s77, 0, 0x18000
	s_add_i32 s80, 0, 0x1c000
	v_add_u32_e32 v172, s77, v155
	v_add_u32_e32 v188, s80, v155
	ds_read_b128 v[160:163], v172
	ds_read_b128 v[164:167], v172 offset:1024
	ds_read_b128 v[168:171], v172 offset:2048
	ds_read_b128 v[172:175], v172 offset:3072
	ds_read_b128 v[176:179], v188
	ds_read_b128 v[180:183], v188 offset:1024
	ds_read_b128 v[184:187], v188 offset:2048
	ds_read_b128 v[188:191], v188 offset:3072
	s_add_u32 s26, s50, 0x20000
	s_addc_u32 s27, s51, 0
	s_mov_b32 m0, s62
	v_lshl_add_u64 v[230:231], s[26:27], 0, v[130:131]
	ds_read_b128 v[192:195], v159 offset:32768
	ds_read_b128 v[196:199], v159 offset:33792
	ds_read_b128 v[200:203], v159 offset:34816
	ds_read_b128 v[204:207], v159 offset:35840
	ds_read_b128 v[208:211], v159 offset:36864
	ds_read_b128 v[212:215], v159 offset:37888
	ds_read_b128 v[216:219], v159 offset:38912
	ds_read_b128 v[220:223], v159 offset:39936
	global_load_lds_dwordx4 v[230:231], off
	v_lshl_add_u64 v[230:231], s[26:27], 0, v[134:135]
	s_mov_b32 m0, s63
	s_nop 0
	global_load_lds_dwordx4 v[230:231], off
	s_waitcnt vmcnt(8)
	s_waitcnt lgkmcnt(0)
	s_barrier
	s_setprio 1
	s_waitcnt lgkmcnt(0)
	v_mfma_f32_16x16x32_bf16 v[126:129], v[160:163], v[192:195], v[126:129]
	v_mfma_f32_16x16x32_bf16 v[122:125], v[168:171], v[192:195], v[122:125]
	v_mfma_f32_16x16x32_bf16 v[110:113], v[160:163], v[200:203], v[110:113]
	v_mfma_f32_16x16x32_bf16 v[106:109], v[168:171], v[200:203], v[106:109]
	v_mfma_f32_16x16x32_bf16 v[94:97], v[160:163], v[208:211], v[94:97]
	v_mfma_f32_16x16x32_bf16 v[90:93], v[168:171], v[208:211], v[90:93]
	v_mfma_f32_16x16x32_bf16 v[78:81], v[160:163], v[216:219], v[78:81]
	v_mfma_f32_16x16x32_bf16 v[74:77], v[168:171], v[216:219], v[74:77]
	v_mfma_f32_16x16x32_bf16 v[126:129], v[164:167], v[196:199], v[126:129]
	v_mfma_f32_16x16x32_bf16 v[122:125], v[172:175], v[196:199], v[122:125]
	v_mfma_f32_16x16x32_bf16 v[110:113], v[164:167], v[204:207], v[110:113]
	v_mfma_f32_16x16x32_bf16 v[106:109], v[172:175], v[204:207], v[106:109]
	v_mfma_f32_16x16x32_bf16 v[94:97], v[164:167], v[212:215], v[94:97]
	v_mfma_f32_16x16x32_bf16 v[90:93], v[172:175], v[212:215], v[90:93]
	v_mfma_f32_16x16x32_bf16 v[78:81], v[164:167], v[220:223], v[78:81]
	v_mfma_f32_16x16x32_bf16 v[74:77], v[172:175], v[220:223], v[74:77]
	s_setprio 0
	s_setprio 1
	v_mfma_f32_16x16x32_bf16 v[118:121], v[176:179], v[192:195], v[118:121]
	v_mfma_f32_16x16x32_bf16 v[114:117], v[184:187], v[192:195], v[114:117]
	v_mfma_f32_16x16x32_bf16 v[102:105], v[176:179], v[200:203], v[102:105]
	v_mfma_f32_16x16x32_bf16 v[98:101], v[184:187], v[200:203], v[98:101]
	v_mfma_f32_16x16x32_bf16 v[86:89], v[176:179], v[208:211], v[86:89]
	v_mfma_f32_16x16x32_bf16 v[82:85], v[184:187], v[208:211], v[82:85]
	v_mfma_f32_16x16x32_bf16 v[70:73], v[176:179], v[216:219], v[70:73]
	v_mfma_f32_16x16x32_bf16 v[66:69], v[184:187], v[216:219], v[66:69]
	v_mfma_f32_16x16x32_bf16 v[118:121], v[180:183], v[196:199], v[118:121]
	v_mfma_f32_16x16x32_bf16 v[114:117], v[188:191], v[196:199], v[114:117]
	v_mfma_f32_16x16x32_bf16 v[102:105], v[180:183], v[204:207], v[102:105]
	v_mfma_f32_16x16x32_bf16 v[98:101], v[188:191], v[204:207], v[98:101]
	v_mfma_f32_16x16x32_bf16 v[86:89], v[180:183], v[212:215], v[86:89]
	v_mfma_f32_16x16x32_bf16 v[82:85], v[188:191], v[212:215], v[82:85]
	v_mfma_f32_16x16x32_bf16 v[70:73], v[180:183], v[220:223], v[70:73]
	v_mfma_f32_16x16x32_bf16 v[66:69], v[188:191], v[220:223], v[66:69]
	s_setprio 0
	s_barrier
	s_add_i32 s26, s77, s58
	v_lshl_add_u64 v[144:145], v[144:145], 0, s[8:9]
	s_mov_b32 m0, s26
	ds_read_b128 v[192:195], v159 offset:49152
	ds_read_b128 v[196:199], v159 offset:50176
	ds_read_b128 v[200:203], v159 offset:51200
	ds_read_b128 v[204:207], v159 offset:52224
	ds_read_b128 v[208:211], v159 offset:53248
	ds_read_b128 v[212:215], v159 offset:54272
	ds_read_b128 v[216:219], v159 offset:55296
	ds_read_b128 v[220:223], v159 offset:56320
	global_load_lds_dwordx4 v[144:145], off
	s_add_i32 m0, s26, 0x2000
	s_add_u32 s26, s46, 0x20080
	v_lshl_add_u64 v[144:145], v[224:225], 0, s[8:9]
	s_addc_u32 s27, s47, 0
	s_add_i32 s46, s80, s58
	global_load_lds_dwordx4 v[144:145], off
	v_lshl_add_u64 v[144:145], s[26:27], 0, v[132:133]
	s_mov_b32 m0, s46
	s_nop 0
	global_load_lds_dwordx4 v[144:145], off
	v_lshl_add_u64 v[144:145], s[26:27], 0, v[136:137]
	s_add_i32 m0, s46, 0x2000
	s_nop 0
	global_load_lds_dwordx4 v[144:145], off
	v_lshl_add_u64 v[144:145], v[226:227], 0, s[8:9]
	s_mov_b32 m0, s67
	s_nop 0
	global_load_lds_dwordx4 v[144:145], off
	v_lshl_add_u64 v[144:145], v[228:229], 0, s[8:9]
	s_mov_b32 m0, s68
	s_nop 0
	global_load_lds_dwordx4 v[144:145], off
	s_waitcnt vmcnt(8)
	s_waitcnt lgkmcnt(0)
	s_barrier
	s_setprio 1
	s_waitcnt lgkmcnt(0)
	v_mfma_f32_16x16x32_bf16 v[62:65], v[160:163], v[192:195], v[62:65]
	v_mfma_f32_16x16x32_bf16 v[58:61], v[168:171], v[192:195], v[58:61]
	v_mfma_f32_16x16x32_bf16 v[46:49], v[160:163], v[200:203], v[46:49]
	v_mfma_f32_16x16x32_bf16 v[42:45], v[168:171], v[200:203], v[42:45]
	v_mfma_f32_16x16x32_bf16 v[30:33], v[160:163], v[208:211], v[30:33]
	v_mfma_f32_16x16x32_bf16 v[26:29], v[168:171], v[208:211], v[26:29]
	v_mfma_f32_16x16x32_bf16 v[14:17], v[160:163], v[216:219], v[14:17]
	v_mfma_f32_16x16x32_bf16 v[10:13], v[168:171], v[216:219], v[10:13]
	v_mfma_f32_16x16x32_bf16 v[62:65], v[164:167], v[196:199], v[62:65]
	v_mfma_f32_16x16x32_bf16 v[58:61], v[172:175], v[196:199], v[58:61]
	v_mfma_f32_16x16x32_bf16 v[46:49], v[164:167], v[204:207], v[46:49]
	v_mfma_f32_16x16x32_bf16 v[42:45], v[172:175], v[204:207], v[42:45]
	v_mfma_f32_16x16x32_bf16 v[30:33], v[164:167], v[212:215], v[30:33]
	v_mfma_f32_16x16x32_bf16 v[26:29], v[172:175], v[212:215], v[26:29]
	v_mfma_f32_16x16x32_bf16 v[14:17], v[164:167], v[220:223], v[14:17]
	v_mfma_f32_16x16x32_bf16 v[10:13], v[172:175], v[220:223], v[10:13]
	s_setprio 0
	s_setprio 1
	v_mfma_f32_16x16x32_bf16 v[54:57], v[176:179], v[192:195], v[54:57]
	v_mfma_f32_16x16x32_bf16 v[50:53], v[184:187], v[192:195], v[50:53]
	v_mfma_f32_16x16x32_bf16 v[38:41], v[176:179], v[200:203], v[38:41]
	v_mfma_f32_16x16x32_bf16 v[34:37], v[184:187], v[200:203], v[34:37]
	v_mfma_f32_16x16x32_bf16 v[22:25], v[176:179], v[208:211], v[22:25]
	v_mfma_f32_16x16x32_bf16 v[18:21], v[184:187], v[208:211], v[18:21]
	v_mfma_f32_16x16x32_bf16 v[6:9], v[176:179], v[216:219], v[6:9]
	v_mfma_f32_16x16x32_bf16 v[2:5], v[184:187], v[216:219], v[2:5]
	v_mfma_f32_16x16x32_bf16 v[54:57], v[180:183], v[196:199], v[54:57]
	v_mfma_f32_16x16x32_bf16 v[50:53], v[188:191], v[196:199], v[50:53]
	v_mfma_f32_16x16x32_bf16 v[38:41], v[180:183], v[204:207], v[38:41]
	v_mfma_f32_16x16x32_bf16 v[34:37], v[188:191], v[204:207], v[34:37]
	v_mfma_f32_16x16x32_bf16 v[22:25], v[180:183], v[212:215], v[22:25]
	v_mfma_f32_16x16x32_bf16 v[18:21], v[188:191], v[212:215], v[18:21]
	v_mfma_f32_16x16x32_bf16 v[6:9], v[180:183], v[220:223], v[6:9]
	v_mfma_f32_16x16x32_bf16 v[2:5], v[188:191], v[220:223], v[2:5]
	s_setprio 0
	s_add_i32 s35, s35, 2
	s_cmp_gt_u32 s35, 5
	s_mov_b64 s[46:47], s[48:49]
	s_barrier
	s_cbranch_scc0 .LBB0_2387
	s_and_b64 vcc, exec, s[10:11]
	s_cbranch_vccz .LBB0_2390
	s_barrier

.LBB0_2726:
	s_add_u32 s26, s8, s12
	s_addc_u32 s27, s9, s13
	s_add_u32 s12, s12, 0x100
	ds_read_b128 v[138:141], v84
	ds_read_b128 v[142:145], v84 offset:1024
	ds_read_b128 v[146:149], v84 offset:2048
	ds_read_b128 v[158:161], v84 offset:3072
	ds_read_b128 v[162:165], v85
	ds_read_b128 v[166:169], v85 offset:1024
	ds_read_b128 v[170:173], v85 offset:2048
	ds_read_b128 v[174:177], v85 offset:3072
	s_addc_u32 s13, s13, 0
	v_cmp_lt_u64_e32 vcc, s[12:13], v[82:83]
	s_and_b64 s[14:15], vcc, exec
	s_cselect_b32 s15, 0, 0xfffff000
	s_cselect_b32 s14, 0, -1
	s_add_u32 s12, s15, s12
	s_addc_u32 s13, s14, s13
	s_cmp_lg_u32 s52, 28
	s_cselect_b32 s14, s12, 0
	s_cselect_b32 s15, s13, 0
	s_add_u32 s16, s8, s14
	s_addc_u32 s17, s9, s15
	s_add_u32 s14, s0, s14
	s_addc_u32 s15, s1, s15
	s_add_u32 s26, s26, 0x80080
	s_addc_u32 s27, s27, 0
	s_mov_b32 m0, s53
	v_lshl_add_u64 v[178:179], s[26:27], 0, v[150:151]
	ds_read_b128 v[186:189], v134
	ds_read_b128 v[190:193], v134 offset:1024
	ds_read_b128 v[194:197], v134 offset:2048
	ds_read_b128 v[198:201], v134 offset:3072
	ds_read_b128 v[202:205], v134 offset:4096
	ds_read_b128 v[206:209], v134 offset:5120
	ds_read_b128 v[210:213], v134 offset:6144
	ds_read_b128 v[214:217], v134 offset:7168
	global_load_lds_dwordx4 v[178:179], off
	v_lshl_add_u64 v[178:179], s[26:27], 0, v[154:155]
	s_mov_b32 m0, s54
	s_nop 0
	global_load_lds_dwordx4 v[178:179], off
	s_waitcnt vmcnt(8)
	s_waitcnt lgkmcnt(0)
	s_barrier
	s_setprio 1
	s_waitcnt lgkmcnt(0)
	v_mfma_f32_16x16x32_bf16 v[26:29], v[138:141], v[186:189], v[26:29]
	v_mfma_f32_16x16x32_bf16 v[54:57], v[146:149], v[186:189], v[54:57]
	v_mfma_f32_16x16x32_bf16 v[98:101], v[138:141], v[194:197], v[98:101]
	v_mfma_f32_16x16x32_bf16 v[118:121], v[146:149], v[194:197], v[118:121]
	v_mfma_f32_16x16x32_bf16 v[126:129], v[138:141], v[202:205], v[126:129]
	v_mfma_f32_16x16x32_bf16 v[38:41], v[146:149], v[202:205], v[38:41]
	v_mfma_f32_16x16x32_bf16 v[50:53], v[138:141], v[210:213], v[50:53]
	v_mfma_f32_16x16x32_bf16 v[66:69], v[146:149], v[210:213], v[66:69]
	v_mfma_f32_16x16x32_bf16 v[26:29], v[142:145], v[190:193], v[26:29]
	v_mfma_f32_16x16x32_bf16 v[54:57], v[158:161], v[190:193], v[54:57]
	v_mfma_f32_16x16x32_bf16 v[98:101], v[142:145], v[198:201], v[98:101]
	v_mfma_f32_16x16x32_bf16 v[118:121], v[158:161], v[198:201], v[118:121]
	v_mfma_f32_16x16x32_bf16 v[126:129], v[142:145], v[206:209], v[126:129]
	v_mfma_f32_16x16x32_bf16 v[38:41], v[158:161], v[206:209], v[38:41]
	v_mfma_f32_16x16x32_bf16 v[50:53], v[142:145], v[214:217], v[50:53]
	v_mfma_f32_16x16x32_bf16 v[66:69], v[158:161], v[214:217], v[66:69]
	s_setprio 0
	s_setprio 1
	v_mfma_f32_16x16x32_bf16 v[74:77], v[162:165], v[186:189], v[74:77]
	v_mfma_f32_16x16x32_bf16 v[62:65], v[170:173], v[186:189], v[62:65]
	v_mfma_f32_16x16x32_bf16 v[42:45], v[162:165], v[194:197], v[42:45]
	v_mfma_f32_16x16x32_bf16 v[30:33], v[170:173], v[194:197], v[30:33]
	v_mfma_f32_16x16x32_bf16 v[34:37], v[162:165], v[202:205], v[34:37]
	v_mfma_f32_16x16x32_bf16 v[46:49], v[170:173], v[202:205], v[46:49]
	v_mfma_f32_16x16x32_bf16 v[58:61], v[162:165], v[210:213], v[58:61]
	v_mfma_f32_16x16x32_bf16 v[70:73], v[170:173], v[210:213], v[70:73]
	v_mfma_f32_16x16x32_bf16 v[74:77], v[166:169], v[190:193], v[74:77]
	v_mfma_f32_16x16x32_bf16 v[62:65], v[174:177], v[190:193], v[62:65]
	v_mfma_f32_16x16x32_bf16 v[42:45], v[166:169], v[198:201], v[42:45]
	v_mfma_f32_16x16x32_bf16 v[30:33], v[174:177], v[198:201], v[30:33]
	v_mfma_f32_16x16x32_bf16 v[34:37], v[166:169], v[206:209], v[34:37]
	v_mfma_f32_16x16x32_bf16 v[46:49], v[174:177], v[206:209], v[46:49]
	v_mfma_f32_16x16x32_bf16 v[58:61], v[166:169], v[214:217], v[58:61]
	v_mfma_f32_16x16x32_bf16 v[70:73], v[174:177], v[214:217], v[70:73]
	s_setprio 0
	s_barrier
	s_mov_b32 m0, s55
	v_lshl_add_u64 v[178:179], s[14:15], 0, v[152:153]
	s_add_u32 s26, s14, 0x80000
	ds_read_b128 v[186:189], v134 offset:16384
	ds_read_b128 v[190:193], v134 offset:17408
	ds_read_b128 v[194:197], v134 offset:18432
	ds_read_b128 v[198:201], v134 offset:19456
	ds_read_b128 v[202:205], v134 offset:20480
	ds_read_b128 v[206:209], v134 offset:21504
	ds_read_b128 v[210:213], v134 offset:22528
	ds_read_b128 v[214:217], v134 offset:23552
	global_load_lds_dwordx4 v[178:179], off
	v_lshl_add_u64 v[218:219], s[14:15], 0, v[156:157]
	s_mov_b32 m0, s56
	s_addc_u32 s27, s15, 0
	global_load_lds_dwordx4 v[218:219], off
	v_lshl_add_u64 v[220:221], s[26:27], 0, v[152:153]
	s_mov_b32 m0, s57
	v_lshl_add_u64 v[222:223], s[16:17], 0, v[154:155]
	global_load_lds_dwordx4 v[220:221], off
	v_lshl_add_u64 v[220:221], s[26:27], 0, v[156:157]
	s_mov_b32 m0, s58
	s_nop 0
	global_load_lds_dwordx4 v[220:221], off
	v_lshl_add_u64 v[220:221], s[16:17], 0, v[150:151]
	s_mov_b32 m0, s47
	s_nop 0
	global_load_lds_dwordx4 v[220:221], off
	s_mov_b32 m0, s48
	s_nop 0
	global_load_lds_dwordx4 v[222:223], off
	s_waitcnt vmcnt(8)
	s_waitcnt lgkmcnt(0)
	s_barrier
	s_setprio 1
	s_waitcnt lgkmcnt(0)
	v_mfma_f32_16x16x32_bf16 v[94:97], v[138:141], v[186:189], v[94:97]
	v_mfma_f32_16x16x32_bf16 v[114:117], v[146:149], v[186:189], v[114:117]
	v_mfma_f32_16x16x32_bf16 v[122:125], v[138:141], v[194:197], v[122:125]
	v_mfma_f32_16x16x32_bf16 v[110:113], v[146:149], v[194:197], v[110:113]
	v_mfma_f32_16x16x32_bf16 v[130:133], v[138:141], v[202:205], v[130:133]
	v_mfma_f32_16x16x32_bf16 v[86:89], v[146:149], v[202:205], v[86:89]
	v_mfma_f32_16x16x32_bf16 v[18:21], v[138:141], v[210:213], v[18:21]
	v_mfma_f32_16x16x32_bf16 v[10:13], v[146:149], v[210:213], v[10:13]
	v_mfma_f32_16x16x32_bf16 v[94:97], v[142:145], v[190:193], v[94:97]
	v_mfma_f32_16x16x32_bf16 v[114:117], v[158:161], v[190:193], v[114:117]
	v_mfma_f32_16x16x32_bf16 v[122:125], v[142:145], v[198:201], v[122:125]
	v_mfma_f32_16x16x32_bf16 v[110:113], v[158:161], v[198:201], v[110:113]
	v_mfma_f32_16x16x32_bf16 v[130:133], v[142:145], v[206:209], v[130:133]
	v_mfma_f32_16x16x32_bf16 v[86:89], v[158:161], v[206:209], v[86:89]
	v_mfma_f32_16x16x32_bf16 v[18:21], v[142:145], v[214:217], v[18:21]
	v_mfma_f32_16x16x32_bf16 v[10:13], v[158:161], v[214:217], v[10:13]
	s_setprio 0
	s_setprio 1
	v_mfma_f32_16x16x32_bf16 v[106:109], v[162:165], v[186:189], v[106:109]
	v_mfma_f32_16x16x32_bf16 v[90:93], v[170:173], v[186:189], v[90:93]
	v_mfma_f32_16x16x32_bf16 v[102:105], v[162:165], v[194:197], v[102:105]
	v_mfma_f32_16x16x32_bf16 v[78:81], v[170:173], v[194:197], v[78:81]
	v_mfma_f32_16x16x32_bf16 v[22:25], v[162:165], v[202:205], v[22:25]
	v_mfma_f32_16x16x32_bf16 v[14:17], v[170:173], v[202:205], v[14:17]
	v_mfma_f32_16x16x32_bf16 v[6:9], v[162:165], v[210:213], v[6:9]
	v_mfma_f32_16x16x32_bf16 v[2:5], v[170:173], v[210:213], v[2:5]
	v_mfma_f32_16x16x32_bf16 v[106:109], v[166:169], v[190:193], v[106:109]
	v_mfma_f32_16x16x32_bf16 v[90:93], v[174:177], v[190:193], v[90:93]
	v_mfma_f32_16x16x32_bf16 v[102:105], v[166:169], v[198:201], v[102:105]
	v_mfma_f32_16x16x32_bf16 v[78:81], v[174:177], v[198:201], v[78:81]
	v_mfma_f32_16x16x32_bf16 v[22:25], v[166:169], v[206:209], v[22:25]
	v_mfma_f32_16x16x32_bf16 v[14:17], v[174:177], v[206:209], v[14:17]
	v_mfma_f32_16x16x32_bf16 v[6:9], v[166:169], v[214:217], v[6:9]
	v_mfma_f32_16x16x32_bf16 v[2:5], v[174:177], v[214:217], v[2:5]
	s_setprio 0
	s_barrier
	ds_read_b128 v[138:141], v135
	ds_read_b128 v[142:145], v135 offset:1024
	ds_read_b128 v[146:149], v135 offset:2048
	ds_read_b128 v[158:161], v135 offset:3072
	ds_read_b128 v[162:165], v136
	ds_read_b128 v[166:169], v136 offset:1024
	ds_read_b128 v[170:173], v136 offset:2048
	ds_read_b128 v[174:177], v136 offset:3072
	s_add_u32 s16, s16, 0x80000
	s_addc_u32 s17, s17, 0
	s_mov_b32 m0, s49
	v_lshl_add_u64 v[224:225], s[16:17], 0, v[150:151]
	ds_read_b128 v[186:189], v134 offset:32768
	ds_read_b128 v[190:193], v134 offset:33792
	ds_read_b128 v[194:197], v134 offset:34816
	ds_read_b128 v[198:201], v134 offset:35840
	ds_read_b128 v[202:205], v134 offset:36864
	ds_read_b128 v[206:209], v134 offset:37888
	ds_read_b128 v[210:213], v134 offset:38912
	ds_read_b128 v[214:217], v134 offset:39936
	global_load_lds_dwordx4 v[224:225], off
	v_lshl_add_u64 v[224:225], s[16:17], 0, v[154:155]
	s_mov_b32 m0, s50
	s_nop 0
	global_load_lds_dwordx4 v[224:225], off
	s_waitcnt vmcnt(8)
	s_waitcnt lgkmcnt(0)
	s_barrier
	s_setprio 1
	s_waitcnt lgkmcnt(0)
	v_mfma_f32_16x16x32_bf16 v[26:29], v[138:141], v[186:189], v[26:29]
	v_mfma_f32_16x16x32_bf16 v[54:57], v[146:149], v[186:189], v[54:57]
	v_mfma_f32_16x16x32_bf16 v[98:101], v[138:141], v[194:197], v[98:101]
	v_mfma_f32_16x16x32_bf16 v[118:121], v[146:149], v[194:197], v[118:121]
	v_mfma_f32_16x16x32_bf16 v[126:129], v[138:141], v[202:205], v[126:129]
	v_mfma_f32_16x16x32_bf16 v[38:41], v[146:149], v[202:205], v[38:41]
	v_mfma_f32_16x16x32_bf16 v[50:53], v[138:141], v[210:213], v[50:53]
	v_mfma_f32_16x16x32_bf16 v[66:69], v[146:149], v[210:213], v[66:69]
	v_mfma_f32_16x16x32_bf16 v[26:29], v[142:145], v[190:193], v[26:29]
	v_mfma_f32_16x16x32_bf16 v[54:57], v[158:161], v[190:193], v[54:57]
	v_mfma_f32_16x16x32_bf16 v[98:101], v[142:145], v[198:201], v[98:101]
	v_mfma_f32_16x16x32_bf16 v[118:121], v[158:161], v[198:201], v[118:121]
	v_mfma_f32_16x16x32_bf16 v[126:129], v[142:145], v[206:209], v[126:129]
	v_mfma_f32_16x16x32_bf16 v[38:41], v[158:161], v[206:209], v[38:41]
	v_mfma_f32_16x16x32_bf16 v[50:53], v[142:145], v[214:217], v[50:53]
	v_mfma_f32_16x16x32_bf16 v[66:69], v[158:161], v[214:217], v[66:69]
	s_setprio 0
	s_setprio 1
	v_mfma_f32_16x16x32_bf16 v[74:77], v[162:165], v[186:189], v[74:77]
	v_mfma_f32_16x16x32_bf16 v[62:65], v[170:173], v[186:189], v[62:65]
	v_mfma_f32_16x16x32_bf16 v[42:45], v[162:165], v[194:197], v[42:45]
	v_mfma_f32_16x16x32_bf16 v[30:33], v[170:173], v[194:197], v[30:33]
	v_mfma_f32_16x16x32_bf16 v[34:37], v[162:165], v[202:205], v[34:37]
	v_mfma_f32_16x16x32_bf16 v[46:49], v[170:173], v[202:205], v[46:49]
	v_mfma_f32_16x16x32_bf16 v[58:61], v[162:165], v[210:213], v[58:61]
	v_mfma_f32_16x16x32_bf16 v[70:73], v[170:173], v[210:213], v[70:73]
	v_mfma_f32_16x16x32_bf16 v[74:77], v[166:169], v[190:193], v[74:77]
	v_mfma_f32_16x16x32_bf16 v[62:65], v[174:177], v[190:193], v[62:65]
	v_mfma_f32_16x16x32_bf16 v[42:45], v[166:169], v[198:201], v[42:45]
	v_mfma_f32_16x16x32_bf16 v[30:33], v[174:177], v[198:201], v[30:33]
	v_mfma_f32_16x16x32_bf16 v[34:37], v[166:169], v[206:209], v[34:37]
	v_mfma_f32_16x16x32_bf16 v[46:49], v[174:177], v[206:209], v[46:49]
	v_mfma_f32_16x16x32_bf16 v[58:61], v[166:169], v[214:217], v[58:61]
	v_mfma_f32_16x16x32_bf16 v[70:73], v[174:177], v[214:217], v[70:73]
	s_setprio 0
	s_barrier
	s_mov_b32 m0, s59
	v_lshl_add_u64 v[178:179], v[178:179], 0, s[10:11]
	s_add_u32 s14, s14, 0x80080
	ds_read_b128 v[186:189], v134 offset:49152
	ds_read_b128 v[190:193], v134 offset:50176
	ds_read_b128 v[194:197], v134 offset:51200
	ds_read_b128 v[198:201], v134 offset:52224
	ds_read_b128 v[202:205], v134 offset:53248
	ds_read_b128 v[206:209], v134 offset:54272
	ds_read_b128 v[210:213], v134 offset:55296
	ds_read_b128 v[214:217], v134 offset:56320
	global_load_lds_dwordx4 v[178:179], off
	v_lshl_add_u64 v[178:179], v[218:219], 0, s[10:11]
	s_mov_b32 m0, s60
	s_addc_u32 s15, s15, 0
	global_load_lds_dwordx4 v[178:179], off
	v_lshl_add_u64 v[178:179], s[14:15], 0, v[152:153]
	s_mov_b32 m0, s61
	s_nop 0
	global_load_lds_dwordx4 v[178:179], off
	v_lshl_add_u64 v[178:179], s[14:15], 0, v[156:157]
	s_mov_b32 m0, s62
	s_nop 0
	global_load_lds_dwordx4 v[178:179], off
	v_lshl_add_u64 v[178:179], v[220:221], 0, s[10:11]
	s_mov_b32 m0, s34
	s_nop 0
	global_load_lds_dwordx4 v[178:179], off
	v_lshl_add_u64 v[178:179], v[222:223], 0, s[10:11]
	s_mov_b32 m0, s35
	s_nop 0
	global_load_lds_dwordx4 v[178:179], off
	s_waitcnt vmcnt(8)
	s_waitcnt lgkmcnt(0)
	s_barrier
	s_setprio 1
	s_waitcnt lgkmcnt(0)
	v_mfma_f32_16x16x32_bf16 v[94:97], v[138:141], v[186:189], v[94:97]
	v_mfma_f32_16x16x32_bf16 v[114:117], v[146:149], v[186:189], v[114:117]
	v_mfma_f32_16x16x32_bf16 v[122:125], v[138:141], v[194:197], v[122:125]
	v_mfma_f32_16x16x32_bf16 v[110:113], v[146:149], v[194:197], v[110:113]
	v_mfma_f32_16x16x32_bf16 v[130:133], v[138:141], v[202:205], v[130:133]
	v_mfma_f32_16x16x32_bf16 v[86:89], v[146:149], v[202:205], v[86:89]
	v_mfma_f32_16x16x32_bf16 v[18:21], v[138:141], v[210:213], v[18:21]
	v_mfma_f32_16x16x32_bf16 v[10:13], v[146:149], v[210:213], v[10:13]
	v_mfma_f32_16x16x32_bf16 v[94:97], v[142:145], v[190:193], v[94:97]
	v_mfma_f32_16x16x32_bf16 v[114:117], v[158:161], v[190:193], v[114:117]
	v_mfma_f32_16x16x32_bf16 v[122:125], v[142:145], v[198:201], v[122:125]
	v_mfma_f32_16x16x32_bf16 v[110:113], v[158:161], v[198:201], v[110:113]
	v_mfma_f32_16x16x32_bf16 v[130:133], v[142:145], v[206:209], v[130:133]
	v_mfma_f32_16x16x32_bf16 v[86:89], v[158:161], v[206:209], v[86:89]
	v_mfma_f32_16x16x32_bf16 v[18:21], v[142:145], v[214:217], v[18:21]
	v_mfma_f32_16x16x32_bf16 v[10:13], v[158:161], v[214:217], v[10:13]
	s_setprio 0
	s_setprio 1
	v_mfma_f32_16x16x32_bf16 v[106:109], v[162:165], v[186:189], v[106:109]
	v_mfma_f32_16x16x32_bf16 v[90:93], v[170:173], v[186:189], v[90:93]
	v_mfma_f32_16x16x32_bf16 v[102:105], v[162:165], v[194:197], v[102:105]
	v_mfma_f32_16x16x32_bf16 v[78:81], v[170:173], v[194:197], v[78:81]
	v_mfma_f32_16x16x32_bf16 v[22:25], v[162:165], v[202:205], v[22:25]
	v_mfma_f32_16x16x32_bf16 v[14:17], v[170:173], v[202:205], v[14:17]
	v_mfma_f32_16x16x32_bf16 v[6:9], v[162:165], v[210:213], v[6:9]
	v_mfma_f32_16x16x32_bf16 v[2:5], v[170:173], v[210:213], v[2:5]
	v_mfma_f32_16x16x32_bf16 v[106:109], v[166:169], v[190:193], v[106:109]
	v_mfma_f32_16x16x32_bf16 v[90:93], v[174:177], v[190:193], v[90:93]
	v_mfma_f32_16x16x32_bf16 v[102:105], v[166:169], v[198:201], v[102:105]
	v_mfma_f32_16x16x32_bf16 v[78:81], v[174:177], v[198:201], v[78:81]
	v_mfma_f32_16x16x32_bf16 v[22:25], v[166:169], v[206:209], v[22:25]
	v_mfma_f32_16x16x32_bf16 v[14:17], v[174:177], v[206:209], v[14:17]
	v_mfma_f32_16x16x32_bf16 v[6:9], v[166:169], v[214:217], v[6:9]
	v_mfma_f32_16x16x32_bf16 v[2:5], v[174:177], v[214:217], v[2:5]
	s_setprio 0
	s_add_i32 s52, s52, 2
	s_cmp_gt_u32 s52, 29
	s_barrier
	s_cbranch_scc0 .LBB0_2726
	s_cmpk_lt_u32 s44, 0x100
	s_cbranch_scc0 .LBB0_2729
	s_barrier

.LBB0_2778:
	s_add_u32 s26, s8, s12
	s_addc_u32 s27, s9, s13
	s_add_u32 s12, s12, 0x100
	ds_read_b128 v[138:141], v84
	ds_read_b128 v[142:145], v84 offset:1024
	ds_read_b128 v[146:149], v84 offset:2048
	ds_read_b128 v[158:161], v84 offset:3072
	ds_read_b128 v[162:165], v85
	ds_read_b128 v[166:169], v85 offset:1024
	ds_read_b128 v[174:177], v85 offset:2048
	ds_read_b128 v[182:185], v85 offset:3072
	s_addc_u32 s13, s13, 0
	v_cmp_lt_u64_e32 vcc, s[12:13], v[82:83]
	s_and_b64 s[14:15], vcc, exec
	s_cselect_b32 s15, 0, 0xfffff000
	s_cselect_b32 s14, 0, -1
	s_add_u32 s12, s15, s12
	s_addc_u32 s13, s14, s13
	s_cmp_lg_u32 s50, 28
	s_cselect_b32 s14, s12, 0
	s_cselect_b32 s15, s13, 0
	s_add_u32 s16, s8, s14
	s_addc_u32 s17, s9, s15
	s_add_u32 s14, s0, s14
	s_addc_u32 s15, s1, s15
	s_add_u32 s26, s26, 0x80080
	s_addc_u32 s27, s27, 0
	s_mov_b32 m0, s51
	v_lshl_add_u64 v[170:171], s[26:27], 0, v[150:151]
	ds_read_b128 v[186:189], v134
	ds_read_b128 v[190:193], v134 offset:1024
	ds_read_b128 v[194:197], v134 offset:2048
	ds_read_b128 v[198:201], v134 offset:3072
	ds_read_b128 v[202:205], v134 offset:4096
	ds_read_b128 v[206:209], v134 offset:5120
	ds_read_b128 v[210:213], v134 offset:6144
	ds_read_b128 v[214:217], v134 offset:7168
	global_load_lds_dwordx4 v[170:171], off
	v_lshl_add_u64 v[170:171], s[26:27], 0, v[154:155]
	s_mov_b32 m0, s52
	s_nop 0
	global_load_lds_dwordx4 v[170:171], off
	s_waitcnt vmcnt(8)
	s_waitcnt lgkmcnt(0)
	s_barrier
	s_setprio 1
	s_waitcnt lgkmcnt(0)
	v_mfma_f32_16x16x32_bf16 v[26:29], v[138:141], v[186:189], v[26:29]
	v_mfma_f32_16x16x32_bf16 v[54:57], v[146:149], v[186:189], v[54:57]
	v_mfma_f32_16x16x32_bf16 v[98:101], v[138:141], v[194:197], v[98:101]
	v_mfma_f32_16x16x32_bf16 v[118:121], v[146:149], v[194:197], v[118:121]
	v_mfma_f32_16x16x32_bf16 v[126:129], v[138:141], v[202:205], v[126:129]
	v_mfma_f32_16x16x32_bf16 v[38:41], v[146:149], v[202:205], v[38:41]
	v_mfma_f32_16x16x32_bf16 v[50:53], v[138:141], v[210:213], v[50:53]
	v_mfma_f32_16x16x32_bf16 v[66:69], v[146:149], v[210:213], v[66:69]
	v_mfma_f32_16x16x32_bf16 v[26:29], v[142:145], v[190:193], v[26:29]
	v_mfma_f32_16x16x32_bf16 v[54:57], v[158:161], v[190:193], v[54:57]
	v_mfma_f32_16x16x32_bf16 v[98:101], v[142:145], v[198:201], v[98:101]
	v_mfma_f32_16x16x32_bf16 v[118:121], v[158:161], v[198:201], v[118:121]
	v_mfma_f32_16x16x32_bf16 v[126:129], v[142:145], v[206:209], v[126:129]
	v_mfma_f32_16x16x32_bf16 v[38:41], v[158:161], v[206:209], v[38:41]
	v_mfma_f32_16x16x32_bf16 v[50:53], v[142:145], v[214:217], v[50:53]
	v_mfma_f32_16x16x32_bf16 v[66:69], v[158:161], v[214:217], v[66:69]
	s_setprio 0
	s_setprio 1
	v_mfma_f32_16x16x32_bf16 v[74:77], v[162:165], v[186:189], v[74:77]
	v_mfma_f32_16x16x32_bf16 v[62:65], v[174:177], v[186:189], v[62:65]
	v_mfma_f32_16x16x32_bf16 v[42:45], v[162:165], v[194:197], v[42:45]
	v_mfma_f32_16x16x32_bf16 v[30:33], v[174:177], v[194:197], v[30:33]
	v_mfma_f32_16x16x32_bf16 v[34:37], v[162:165], v[202:205], v[34:37]
	v_mfma_f32_16x16x32_bf16 v[46:49], v[174:177], v[202:205], v[46:49]
	v_mfma_f32_16x16x32_bf16 v[58:61], v[162:165], v[210:213], v[58:61]
	v_mfma_f32_16x16x32_bf16 v[70:73], v[174:177], v[210:213], v[70:73]
	v_mfma_f32_16x16x32_bf16 v[74:77], v[166:169], v[190:193], v[74:77]
	v_mfma_f32_16x16x32_bf16 v[62:65], v[182:185], v[190:193], v[62:65]
	v_mfma_f32_16x16x32_bf16 v[42:45], v[166:169], v[198:201], v[42:45]
	v_mfma_f32_16x16x32_bf16 v[30:33], v[182:185], v[198:201], v[30:33]
	v_mfma_f32_16x16x32_bf16 v[34:37], v[166:169], v[206:209], v[34:37]
	v_mfma_f32_16x16x32_bf16 v[46:49], v[182:185], v[206:209], v[46:49]
	v_mfma_f32_16x16x32_bf16 v[58:61], v[166:169], v[214:217], v[58:61]
	v_mfma_f32_16x16x32_bf16 v[70:73], v[182:185], v[214:217], v[70:73]
	s_setprio 0
	s_barrier
	s_mov_b32 m0, s53
	v_lshl_add_u64 v[170:171], s[14:15], 0, v[152:153]
	s_add_u32 s26, s14, 0x80000
	ds_read_b128 v[186:189], v134 offset:16384
	ds_read_b128 v[190:193], v134 offset:17408
	ds_read_b128 v[194:197], v134 offset:18432
	ds_read_b128 v[198:201], v134 offset:19456
	ds_read_b128 v[202:205], v134 offset:20480
	ds_read_b128 v[206:209], v134 offset:21504
	ds_read_b128 v[210:213], v134 offset:22528
	ds_read_b128 v[214:217], v134 offset:23552
	global_load_lds_dwordx4 v[170:171], off
	v_lshl_add_u64 v[178:179], s[14:15], 0, v[156:157]
	s_mov_b32 m0, s54
	s_addc_u32 s27, s15, 0
	global_load_lds_dwordx4 v[178:179], off
	v_lshl_add_u64 v[218:219], s[26:27], 0, v[152:153]
	s_mov_b32 m0, s55
	v_lshl_add_u64 v[220:221], s[16:17], 0, v[154:155]
	global_load_lds_dwordx4 v[218:219], off
	v_lshl_add_u64 v[218:219], s[26:27], 0, v[156:157]
	s_mov_b32 m0, s56
	s_nop 0
	global_load_lds_dwordx4 v[218:219], off
	v_lshl_add_u64 v[218:219], s[16:17], 0, v[150:151]
	s_mov_b32 m0, s43
	s_nop 0
	global_load_lds_dwordx4 v[218:219], off
	s_mov_b32 m0, s46
	s_nop 0
	global_load_lds_dwordx4 v[220:221], off
	s_waitcnt vmcnt(8)
	s_waitcnt lgkmcnt(0)
	s_barrier
	s_setprio 1
	s_waitcnt lgkmcnt(0)
	v_mfma_f32_16x16x32_bf16 v[94:97], v[138:141], v[186:189], v[94:97]
	v_mfma_f32_16x16x32_bf16 v[114:117], v[146:149], v[186:189], v[114:117]
	v_mfma_f32_16x16x32_bf16 v[122:125], v[138:141], v[194:197], v[122:125]
	v_mfma_f32_16x16x32_bf16 v[110:113], v[146:149], v[194:197], v[110:113]
	v_mfma_f32_16x16x32_bf16 v[130:133], v[138:141], v[202:205], v[130:133]
	v_mfma_f32_16x16x32_bf16 v[86:89], v[146:149], v[202:205], v[86:89]
	v_mfma_f32_16x16x32_bf16 v[18:21], v[138:141], v[210:213], v[18:21]
	v_mfma_f32_16x16x32_bf16 v[10:13], v[146:149], v[210:213], v[10:13]
	v_mfma_f32_16x16x32_bf16 v[94:97], v[142:145], v[190:193], v[94:97]
	v_mfma_f32_16x16x32_bf16 v[114:117], v[158:161], v[190:193], v[114:117]
	v_mfma_f32_16x16x32_bf16 v[122:125], v[142:145], v[198:201], v[122:125]
	v_mfma_f32_16x16x32_bf16 v[110:113], v[158:161], v[198:201], v[110:113]
	v_mfma_f32_16x16x32_bf16 v[130:133], v[142:145], v[206:209], v[130:133]
	v_mfma_f32_16x16x32_bf16 v[86:89], v[158:161], v[206:209], v[86:89]
	v_mfma_f32_16x16x32_bf16 v[18:21], v[142:145], v[214:217], v[18:21]
	v_mfma_f32_16x16x32_bf16 v[10:13], v[158:161], v[214:217], v[10:13]
	s_setprio 0
	s_setprio 1
	v_mfma_f32_16x16x32_bf16 v[106:109], v[162:165], v[186:189], v[106:109]
	v_mfma_f32_16x16x32_bf16 v[90:93], v[174:177], v[186:189], v[90:93]
	v_mfma_f32_16x16x32_bf16 v[102:105], v[162:165], v[194:197], v[102:105]
	v_mfma_f32_16x16x32_bf16 v[78:81], v[174:177], v[194:197], v[78:81]
	v_mfma_f32_16x16x32_bf16 v[22:25], v[162:165], v[202:205], v[22:25]
	v_mfma_f32_16x16x32_bf16 v[14:17], v[174:177], v[202:205], v[14:17]
	v_mfma_f32_16x16x32_bf16 v[6:9], v[162:165], v[210:213], v[6:9]
	v_mfma_f32_16x16x32_bf16 v[2:5], v[174:177], v[210:213], v[2:5]
	v_mfma_f32_16x16x32_bf16 v[106:109], v[166:169], v[190:193], v[106:109]
	v_mfma_f32_16x16x32_bf16 v[90:93], v[182:185], v[190:193], v[90:93]
	v_mfma_f32_16x16x32_bf16 v[102:105], v[166:169], v[198:201], v[102:105]
	v_mfma_f32_16x16x32_bf16 v[78:81], v[182:185], v[198:201], v[78:81]
	v_mfma_f32_16x16x32_bf16 v[22:25], v[166:169], v[206:209], v[22:25]
	v_mfma_f32_16x16x32_bf16 v[14:17], v[182:185], v[206:209], v[14:17]
	v_mfma_f32_16x16x32_bf16 v[6:9], v[166:169], v[214:217], v[6:9]
	v_mfma_f32_16x16x32_bf16 v[2:5], v[182:185], v[214:217], v[2:5]
	s_setprio 0
	s_barrier
	ds_read_b128 v[138:141], v135
	ds_read_b128 v[142:145], v135 offset:1024
	ds_read_b128 v[146:149], v135 offset:2048
	ds_read_b128 v[158:161], v135 offset:3072
	ds_read_b128 v[162:165], v136
	ds_read_b128 v[166:169], v136 offset:1024
	ds_read_b128 v[174:177], v136 offset:2048
	ds_read_b128 v[182:185], v136 offset:3072
	s_add_u32 s16, s16, 0x80000
	s_addc_u32 s17, s17, 0
	s_mov_b32 m0, s47
	v_lshl_add_u64 v[222:223], s[16:17], 0, v[150:151]
	ds_read_b128 v[186:189], v134 offset:32768
	ds_read_b128 v[190:193], v134 offset:33792
	ds_read_b128 v[194:197], v134 offset:34816
	ds_read_b128 v[198:201], v134 offset:35840
	ds_read_b128 v[202:205], v134 offset:36864
	ds_read_b128 v[206:209], v134 offset:37888
	ds_read_b128 v[210:213], v134 offset:38912
	ds_read_b128 v[214:217], v134 offset:39936
	global_load_lds_dwordx4 v[222:223], off
	v_lshl_add_u64 v[222:223], s[16:17], 0, v[154:155]
	s_mov_b32 m0, s48
	s_nop 0
	global_load_lds_dwordx4 v[222:223], off
	s_waitcnt vmcnt(8)
	s_waitcnt lgkmcnt(0)
	s_barrier
	s_setprio 1
	s_waitcnt lgkmcnt(0)
	v_mfma_f32_16x16x32_bf16 v[26:29], v[138:141], v[186:189], v[26:29]
	v_mfma_f32_16x16x32_bf16 v[54:57], v[146:149], v[186:189], v[54:57]
	v_mfma_f32_16x16x32_bf16 v[98:101], v[138:141], v[194:197], v[98:101]
	v_mfma_f32_16x16x32_bf16 v[118:121], v[146:149], v[194:197], v[118:121]
	v_mfma_f32_16x16x32_bf16 v[126:129], v[138:141], v[202:205], v[126:129]
	v_mfma_f32_16x16x32_bf16 v[38:41], v[146:149], v[202:205], v[38:41]
	v_mfma_f32_16x16x32_bf16 v[50:53], v[138:141], v[210:213], v[50:53]
	v_mfma_f32_16x16x32_bf16 v[66:69], v[146:149], v[210:213], v[66:69]
	v_mfma_f32_16x16x32_bf16 v[26:29], v[142:145], v[190:193], v[26:29]
	v_mfma_f32_16x16x32_bf16 v[54:57], v[158:161], v[190:193], v[54:57]
	v_mfma_f32_16x16x32_bf16 v[98:101], v[142:145], v[198:201], v[98:101]
	v_mfma_f32_16x16x32_bf16 v[118:121], v[158:161], v[198:201], v[118:121]
	v_mfma_f32_16x16x32_bf16 v[126:129], v[142:145], v[206:209], v[126:129]
	v_mfma_f32_16x16x32_bf16 v[38:41], v[158:161], v[206:209], v[38:41]
	v_mfma_f32_16x16x32_bf16 v[50:53], v[142:145], v[214:217], v[50:53]
	v_mfma_f32_16x16x32_bf16 v[66:69], v[158:161], v[214:217], v[66:69]
	s_setprio 0
	s_setprio 1
	v_mfma_f32_16x16x32_bf16 v[74:77], v[162:165], v[186:189], v[74:77]
	v_mfma_f32_16x16x32_bf16 v[62:65], v[174:177], v[186:189], v[62:65]
	v_mfma_f32_16x16x32_bf16 v[42:45], v[162:165], v[194:197], v[42:45]
	v_mfma_f32_16x16x32_bf16 v[30:33], v[174:177], v[194:197], v[30:33]
	v_mfma_f32_16x16x32_bf16 v[34:37], v[162:165], v[202:205], v[34:37]
	v_mfma_f32_16x16x32_bf16 v[46:49], v[174:177], v[202:205], v[46:49]
	v_mfma_f32_16x16x32_bf16 v[58:61], v[162:165], v[210:213], v[58:61]
	v_mfma_f32_16x16x32_bf16 v[70:73], v[174:177], v[210:213], v[70:73]
	v_mfma_f32_16x16x32_bf16 v[74:77], v[166:169], v[190:193], v[74:77]
	v_mfma_f32_16x16x32_bf16 v[62:65], v[182:185], v[190:193], v[62:65]
	v_mfma_f32_16x16x32_bf16 v[42:45], v[166:169], v[198:201], v[42:45]
	v_mfma_f32_16x16x32_bf16 v[30:33], v[182:185], v[198:201], v[30:33]
	v_mfma_f32_16x16x32_bf16 v[34:37], v[166:169], v[206:209], v[34:37]
	v_mfma_f32_16x16x32_bf16 v[46:49], v[182:185], v[206:209], v[46:49]
	v_mfma_f32_16x16x32_bf16 v[58:61], v[166:169], v[214:217], v[58:61]
	v_mfma_f32_16x16x32_bf16 v[70:73], v[182:185], v[214:217], v[70:73]
	s_setprio 0
	s_barrier
	s_mov_b32 m0, s57
	v_lshl_add_u64 v[170:171], v[170:171], 0, s[10:11]
	s_add_u32 s14, s14, 0x80080
	ds_read_b128 v[186:189], v134 offset:49152
	ds_read_b128 v[190:193], v134 offset:50176
	ds_read_b128 v[194:197], v134 offset:51200
	ds_read_b128 v[198:201], v134 offset:52224
	ds_read_b128 v[202:205], v134 offset:53248
	ds_read_b128 v[206:209], v134 offset:54272
	ds_read_b128 v[210:213], v134 offset:55296
	ds_read_b128 v[214:217], v134 offset:56320
	global_load_lds_dwordx4 v[170:171], off
	v_lshl_add_u64 v[170:171], v[178:179], 0, s[10:11]
	s_mov_b32 m0, s58
	s_addc_u32 s15, s15, 0
	global_load_lds_dwordx4 v[170:171], off
	v_lshl_add_u64 v[170:171], s[14:15], 0, v[152:153]
	s_mov_b32 m0, s59
	s_nop 0
	global_load_lds_dwordx4 v[170:171], off
	v_lshl_add_u64 v[170:171], s[14:15], 0, v[156:157]
	s_mov_b32 m0, s60
	s_nop 0
	global_load_lds_dwordx4 v[170:171], off
	v_lshl_add_u64 v[170:171], v[218:219], 0, s[10:11]
	s_mov_b32 m0, s34
	s_nop 0
	global_load_lds_dwordx4 v[170:171], off
	v_lshl_add_u64 v[170:171], v[220:221], 0, s[10:11]
	s_mov_b32 m0, s35
	s_nop 0
	global_load_lds_dwordx4 v[170:171], off
	s_waitcnt vmcnt(8)
	s_waitcnt lgkmcnt(0)
	s_barrier
	s_setprio 1
	s_waitcnt lgkmcnt(0)
	v_mfma_f32_16x16x32_bf16 v[94:97], v[138:141], v[186:189], v[94:97]
	v_mfma_f32_16x16x32_bf16 v[114:117], v[146:149], v[186:189], v[114:117]
	v_mfma_f32_16x16x32_bf16 v[122:125], v[138:141], v[194:197], v[122:125]
	v_mfma_f32_16x16x32_bf16 v[110:113], v[146:149], v[194:197], v[110:113]
	v_mfma_f32_16x16x32_bf16 v[130:133], v[138:141], v[202:205], v[130:133]
	v_mfma_f32_16x16x32_bf16 v[86:89], v[146:149], v[202:205], v[86:89]
	v_mfma_f32_16x16x32_bf16 v[18:21], v[138:141], v[210:213], v[18:21]
	v_mfma_f32_16x16x32_bf16 v[10:13], v[146:149], v[210:213], v[10:13]
	v_mfma_f32_16x16x32_bf16 v[94:97], v[142:145], v[190:193], v[94:97]
	v_mfma_f32_16x16x32_bf16 v[114:117], v[158:161], v[190:193], v[114:117]
	v_mfma_f32_16x16x32_bf16 v[122:125], v[142:145], v[198:201], v[122:125]
	v_mfma_f32_16x16x32_bf16 v[110:113], v[158:161], v[198:201], v[110:113]
	v_mfma_f32_16x16x32_bf16 v[130:133], v[142:145], v[206:209], v[130:133]
	v_mfma_f32_16x16x32_bf16 v[86:89], v[158:161], v[206:209], v[86:89]
	v_mfma_f32_16x16x32_bf16 v[18:21], v[142:145], v[214:217], v[18:21]
	v_mfma_f32_16x16x32_bf16 v[10:13], v[158:161], v[214:217], v[10:13]
	s_setprio 0
	s_setprio 1
	v_mfma_f32_16x16x32_bf16 v[106:109], v[162:165], v[186:189], v[106:109]
	v_mfma_f32_16x16x32_bf16 v[90:93], v[174:177], v[186:189], v[90:93]
	v_mfma_f32_16x16x32_bf16 v[102:105], v[162:165], v[194:197], v[102:105]
	v_mfma_f32_16x16x32_bf16 v[78:81], v[174:177], v[194:197], v[78:81]
	v_mfma_f32_16x16x32_bf16 v[22:25], v[162:165], v[202:205], v[22:25]
	v_mfma_f32_16x16x32_bf16 v[14:17], v[174:177], v[202:205], v[14:17]
	v_mfma_f32_16x16x32_bf16 v[6:9], v[162:165], v[210:213], v[6:9]
	v_mfma_f32_16x16x32_bf16 v[2:5], v[174:177], v[210:213], v[2:5]
	v_mfma_f32_16x16x32_bf16 v[106:109], v[166:169], v[190:193], v[106:109]
	v_mfma_f32_16x16x32_bf16 v[90:93], v[182:185], v[190:193], v[90:93]
	v_mfma_f32_16x16x32_bf16 v[102:105], v[166:169], v[198:201], v[102:105]
	v_mfma_f32_16x16x32_bf16 v[78:81], v[182:185], v[198:201], v[78:81]
	v_mfma_f32_16x16x32_bf16 v[22:25], v[166:169], v[206:209], v[22:25]
	v_mfma_f32_16x16x32_bf16 v[14:17], v[182:185], v[206:209], v[14:17]
	v_mfma_f32_16x16x32_bf16 v[6:9], v[166:169], v[214:217], v[6:9]
	v_mfma_f32_16x16x32_bf16 v[2:5], v[182:185], v[214:217], v[2:5]
	s_setprio 0
	s_add_i32 s50, s50, 2
	s_cmp_gt_u32 s50, 29
	s_barrier
	s_cbranch_scc0 .LBB0_2778
	s_cmpk_lt_u32 s44, 0x100
	s_cbranch_scc0 .LBB0_2781
	s_barrier

.LBB0_2886:
	s_add_u32 s24, s22, 0x100
	s_addc_u32 s25, s23, 0
	s_add_u32 s42, s22, 0xfffff100
	ds_read_b128 v[150:153], v146
	ds_read_b128 v[154:157], v146 offset:1024
	ds_read_b128 v[158:161], v146 offset:2048
	ds_read_b128 v[162:165], v146 offset:3072
	ds_read_b128 v[166:169], v147
	ds_read_b128 v[170:173], v147 offset:1024
	ds_read_b128 v[174:177], v147 offset:2048
	ds_read_b128 v[178:181], v147 offset:3072
	v_cmp_gt_u64_e32 vcc, s[24:25], v[142:143]
	s_addc_u32 s43, s23, -1
	s_and_b64 s[26:27], vcc, exec
	s_cselect_b32 s24, s42, s24
	s_cselect_b32 s25, s43, s25
	s_add_u32 s26, s20, s24
	s_addc_u32 s27, s21, s25
	s_add_u32 s42, s18, s24
	s_addc_u32 s43, s19, s25
	s_cmp_eq_u32 s62, 28
	s_cselect_b32 s45, s11, s27
	s_cselect_b32 s44, s34, s26
	s_cselect_b32 s43, s9, s43
	s_cselect_b32 s42, s35, s42
	s_add_u32 s22, s20, s22
	s_addc_u32 s23, s21, s23
	s_add_u32 s22, s22, 0x80080
	s_addc_u32 s23, s23, 0
	v_lshl_add_u64 v[214:215], s[22:23], 0, v[130:131]
	s_add_i32 m0, s17, 0xc000
	ds_read_b128 v[182:185], v148
	ds_read_b128 v[186:189], v148 offset:1024
	ds_read_b128 v[190:193], v148 offset:2048
	ds_read_b128 v[194:197], v148 offset:3072
	ds_read_b128 v[198:201], v148 offset:4096
	ds_read_b128 v[202:205], v148 offset:5120
	ds_read_b128 v[206:209], v148 offset:6144
	ds_read_b128 v[210:213], v148 offset:7168
	global_load_lds_dwordx4 v[214:215], off
	v_lshl_add_u64 v[214:215], s[22:23], 0, v[134:135]
	s_add_i32 m0, s17, 0xe000
	s_nop 0
	global_load_lds_dwordx4 v[214:215], off
	s_waitcnt vmcnt(8)
	s_waitcnt lgkmcnt(0)
	s_barrier
	s_setprio 1
	s_waitcnt lgkmcnt(0)
	v_mfma_f32_16x16x32_bf16 v[126:129], v[150:153], v[182:185], v[126:129]
	v_mfma_f32_16x16x32_bf16 v[118:121], v[158:161], v[182:185], v[118:121]
	v_mfma_f32_16x16x32_bf16 v[110:113], v[150:153], v[190:193], v[110:113]
	v_mfma_f32_16x16x32_bf16 v[102:105], v[158:161], v[190:193], v[102:105]
	v_mfma_f32_16x16x32_bf16 v[94:97], v[150:153], v[198:201], v[94:97]
	v_mfma_f32_16x16x32_bf16 v[86:89], v[158:161], v[198:201], v[86:89]
	v_mfma_f32_16x16x32_bf16 v[78:81], v[150:153], v[206:209], v[78:81]
	v_mfma_f32_16x16x32_bf16 v[70:73], v[158:161], v[206:209], v[70:73]
	v_mfma_f32_16x16x32_bf16 v[126:129], v[154:157], v[186:189], v[126:129]
	v_mfma_f32_16x16x32_bf16 v[118:121], v[162:165], v[186:189], v[118:121]
	v_mfma_f32_16x16x32_bf16 v[110:113], v[154:157], v[194:197], v[110:113]
	v_mfma_f32_16x16x32_bf16 v[102:105], v[162:165], v[194:197], v[102:105]
	v_mfma_f32_16x16x32_bf16 v[94:97], v[154:157], v[202:205], v[94:97]
	v_mfma_f32_16x16x32_bf16 v[86:89], v[162:165], v[202:205], v[86:89]
	v_mfma_f32_16x16x32_bf16 v[78:81], v[154:157], v[210:213], v[78:81]
	v_mfma_f32_16x16x32_bf16 v[70:73], v[162:165], v[210:213], v[70:73]
	s_setprio 0
	s_setprio 1
	v_mfma_f32_16x16x32_bf16 v[122:125], v[166:169], v[182:185], v[122:125]
	v_mfma_f32_16x16x32_bf16 v[114:117], v[174:177], v[182:185], v[114:117]
	v_mfma_f32_16x16x32_bf16 v[106:109], v[166:169], v[190:193], v[106:109]
	v_mfma_f32_16x16x32_bf16 v[98:101], v[174:177], v[190:193], v[98:101]
	v_mfma_f32_16x16x32_bf16 v[90:93], v[166:169], v[198:201], v[90:93]
	v_mfma_f32_16x16x32_bf16 v[82:85], v[174:177], v[198:201], v[82:85]
	v_mfma_f32_16x16x32_bf16 v[74:77], v[166:169], v[206:209], v[74:77]
	v_mfma_f32_16x16x32_bf16 v[66:69], v[174:177], v[206:209], v[66:69]
	v_mfma_f32_16x16x32_bf16 v[122:125], v[170:173], v[186:189], v[122:125]
	v_mfma_f32_16x16x32_bf16 v[114:117], v[178:181], v[186:189], v[114:117]
	v_mfma_f32_16x16x32_bf16 v[106:109], v[170:173], v[194:197], v[106:109]
	v_mfma_f32_16x16x32_bf16 v[98:101], v[178:181], v[194:197], v[98:101]
	v_mfma_f32_16x16x32_bf16 v[90:93], v[170:173], v[202:205], v[90:93]
	v_mfma_f32_16x16x32_bf16 v[82:85], v[178:181], v[202:205], v[82:85]
	v_mfma_f32_16x16x32_bf16 v[74:77], v[170:173], v[210:213], v[74:77]
	v_mfma_f32_16x16x32_bf16 v[66:69], v[178:181], v[210:213], v[66:69]
	s_setprio 0
	s_barrier
	s_add_i32 s22, s58, s48
	v_lshl_add_u64 v[214:215], s[42:43], 0, v[132:133]
	s_mov_b32 m0, s22
	ds_read_b128 v[182:185], v148 offset:16384
	ds_read_b128 v[186:189], v148 offset:17408
	ds_read_b128 v[190:193], v148 offset:18432
	ds_read_b128 v[194:197], v148 offset:19456
	ds_read_b128 v[198:201], v148 offset:20480
	ds_read_b128 v[202:205], v148 offset:21504
	ds_read_b128 v[206:209], v148 offset:22528
	ds_read_b128 v[210:213], v148 offset:23552
	global_load_lds_dwordx4 v[214:215], off
	s_add_i32 m0, s22, 0x2000
	s_add_u32 s22, s42, 0x80000
	v_lshl_add_u64 v[216:217], s[42:43], 0, v[136:137]
	s_addc_u32 s23, s43, 0
	s_add_i32 s26, s59, s48
	global_load_lds_dwordx4 v[216:217], off
	v_lshl_add_u64 v[218:219], s[22:23], 0, v[132:133]
	s_mov_b32 m0, s26
	v_lshl_add_u64 v[220:221], s[44:45], 0, v[134:135]
	global_load_lds_dwordx4 v[218:219], off
	v_lshl_add_u64 v[218:219], s[22:23], 0, v[136:137]
	s_add_i32 m0, s26, 0x2000
	s_nop 0
	global_load_lds_dwordx4 v[218:219], off
	v_lshl_add_u64 v[218:219], s[44:45], 0, v[130:131]
	s_mov_b32 m0, s17
	s_nop 0
	global_load_lds_dwordx4 v[218:219], off
	s_mov_b32 m0, s51
	s_nop 0
	global_load_lds_dwordx4 v[220:221], off
	s_waitcnt vmcnt(8)
	s_waitcnt lgkmcnt(0)
	s_barrier
	s_setprio 1
	s_waitcnt lgkmcnt(0)
	v_mfma_f32_16x16x32_bf16 v[62:65], v[150:153], v[182:185], v[62:65]
	v_mfma_f32_16x16x32_bf16 v[54:57], v[158:161], v[182:185], v[54:57]
	v_mfma_f32_16x16x32_bf16 v[46:49], v[150:153], v[190:193], v[46:49]
	v_mfma_f32_16x16x32_bf16 v[38:41], v[158:161], v[190:193], v[38:41]
	v_mfma_f32_16x16x32_bf16 v[30:33], v[150:153], v[198:201], v[30:33]
	v_mfma_f32_16x16x32_bf16 v[22:25], v[158:161], v[198:201], v[22:25]
	v_mfma_f32_16x16x32_bf16 v[14:17], v[150:153], v[206:209], v[14:17]
	v_mfma_f32_16x16x32_bf16 v[6:9], v[158:161], v[206:209], v[6:9]
	v_mfma_f32_16x16x32_bf16 v[62:65], v[154:157], v[186:189], v[62:65]
	v_mfma_f32_16x16x32_bf16 v[54:57], v[162:165], v[186:189], v[54:57]
	v_mfma_f32_16x16x32_bf16 v[46:49], v[154:157], v[194:197], v[46:49]
	v_mfma_f32_16x16x32_bf16 v[38:41], v[162:165], v[194:197], v[38:41]
	v_mfma_f32_16x16x32_bf16 v[30:33], v[154:157], v[202:205], v[30:33]
	v_mfma_f32_16x16x32_bf16 v[22:25], v[162:165], v[202:205], v[22:25]
	v_mfma_f32_16x16x32_bf16 v[14:17], v[154:157], v[210:213], v[14:17]
	v_mfma_f32_16x16x32_bf16 v[6:9], v[162:165], v[210:213], v[6:9]
	s_setprio 0
	s_setprio 1
	v_mfma_f32_16x16x32_bf16 v[58:61], v[166:169], v[182:185], v[58:61]
	v_mfma_f32_16x16x32_bf16 v[50:53], v[174:177], v[182:185], v[50:53]
	v_mfma_f32_16x16x32_bf16 v[42:45], v[166:169], v[190:193], v[42:45]
	v_mfma_f32_16x16x32_bf16 v[34:37], v[174:177], v[190:193], v[34:37]
	v_mfma_f32_16x16x32_bf16 v[26:29], v[166:169], v[198:201], v[26:29]
	v_mfma_f32_16x16x32_bf16 v[18:21], v[174:177], v[198:201], v[18:21]
	v_mfma_f32_16x16x32_bf16 v[10:13], v[166:169], v[206:209], v[10:13]
	v_mfma_f32_16x16x32_bf16 v[2:5], v[174:177], v[206:209], v[2:5]
	v_mfma_f32_16x16x32_bf16 v[58:61], v[170:173], v[186:189], v[58:61]
	v_mfma_f32_16x16x32_bf16 v[50:53], v[178:181], v[186:189], v[50:53]
	v_mfma_f32_16x16x32_bf16 v[42:45], v[170:173], v[194:197], v[42:45]
	v_mfma_f32_16x16x32_bf16 v[34:37], v[178:181], v[194:197], v[34:37]
	v_mfma_f32_16x16x32_bf16 v[26:29], v[170:173], v[202:205], v[26:29]
	v_mfma_f32_16x16x32_bf16 v[18:21], v[178:181], v[202:205], v[18:21]
	v_mfma_f32_16x16x32_bf16 v[10:13], v[170:173], v[210:213], v[10:13]
	v_mfma_f32_16x16x32_bf16 v[2:5], v[178:181], v[210:213], v[2:5]
	s_setprio 0
	s_barrier
	s_add_i32 s26, 0, 0x18000
	v_add_u32_e32 v149, s26, v144
	s_add_i32 s27, 0, 0x1c000
	ds_read_b128 v[150:153], v149
	ds_read_b128 v[154:157], v149 offset:1024
	ds_read_b128 v[158:161], v149 offset:2048
	ds_read_b128 v[162:165], v149 offset:3072
	v_add_u32_e32 v149, s27, v144
	ds_read_b128 v[166:169], v149
	ds_read_b128 v[170:173], v149 offset:1024
	ds_read_b128 v[174:177], v149 offset:2048
	ds_read_b128 v[178:181], v149 offset:3072
	s_add_u32 s22, s44, 0x80000
	s_addc_u32 s23, s45, 0
	s_mov_b32 m0, s52
	v_lshl_add_u64 v[222:223], s[22:23], 0, v[130:131]
	ds_read_b128 v[182:185], v148 offset:32768
	ds_read_b128 v[186:189], v148 offset:33792
	ds_read_b128 v[190:193], v148 offset:34816
	ds_read_b128 v[194:197], v148 offset:35840
	ds_read_b128 v[198:201], v148 offset:36864
	ds_read_b128 v[202:205], v148 offset:37888
	ds_read_b128 v[206:209], v148 offset:38912
	ds_read_b128 v[210:213], v148 offset:39936
	global_load_lds_dwordx4 v[222:223], off
	v_lshl_add_u64 v[222:223], s[22:23], 0, v[134:135]
	s_mov_b32 m0, s53
	s_nop 0
	global_load_lds_dwordx4 v[222:223], off
	s_waitcnt vmcnt(8)
	s_waitcnt lgkmcnt(0)
	s_barrier
	s_setprio 1
	s_waitcnt lgkmcnt(0)
	v_mfma_f32_16x16x32_bf16 v[126:129], v[150:153], v[182:185], v[126:129]
	v_mfma_f32_16x16x32_bf16 v[118:121], v[158:161], v[182:185], v[118:121]
	v_mfma_f32_16x16x32_bf16 v[110:113], v[150:153], v[190:193], v[110:113]
	v_mfma_f32_16x16x32_bf16 v[102:105], v[158:161], v[190:193], v[102:105]
	v_mfma_f32_16x16x32_bf16 v[94:97], v[150:153], v[198:201], v[94:97]
	v_mfma_f32_16x16x32_bf16 v[86:89], v[158:161], v[198:201], v[86:89]
	v_mfma_f32_16x16x32_bf16 v[78:81], v[150:153], v[206:209], v[78:81]
	v_mfma_f32_16x16x32_bf16 v[70:73], v[158:161], v[206:209], v[70:73]
	v_mfma_f32_16x16x32_bf16 v[126:129], v[154:157], v[186:189], v[126:129]
	v_mfma_f32_16x16x32_bf16 v[118:121], v[162:165], v[186:189], v[118:121]
	v_mfma_f32_16x16x32_bf16 v[110:113], v[154:157], v[194:197], v[110:113]
	v_mfma_f32_16x16x32_bf16 v[102:105], v[162:165], v[194:197], v[102:105]
	v_mfma_f32_16x16x32_bf16 v[94:97], v[154:157], v[202:205], v[94:97]
	v_mfma_f32_16x16x32_bf16 v[86:89], v[162:165], v[202:205], v[86:89]
	v_mfma_f32_16x16x32_bf16 v[78:81], v[154:157], v[210:213], v[78:81]
	v_mfma_f32_16x16x32_bf16 v[70:73], v[162:165], v[210:213], v[70:73]
	s_setprio 0
	s_setprio 1
	v_mfma_f32_16x16x32_bf16 v[122:125], v[166:169], v[182:185], v[122:125]
	v_mfma_f32_16x16x32_bf16 v[114:117], v[174:177], v[182:185], v[114:117]
	v_mfma_f32_16x16x32_bf16 v[106:109], v[166:169], v[190:193], v[106:109]
	v_mfma_f32_16x16x32_bf16 v[98:101], v[174:177], v[190:193], v[98:101]
	v_mfma_f32_16x16x32_bf16 v[90:93], v[166:169], v[198:201], v[90:93]
	v_mfma_f32_16x16x32_bf16 v[82:85], v[174:177], v[198:201], v[82:85]
	v_mfma_f32_16x16x32_bf16 v[74:77], v[166:169], v[206:209], v[74:77]
	v_mfma_f32_16x16x32_bf16 v[66:69], v[174:177], v[206:209], v[66:69]
	v_mfma_f32_16x16x32_bf16 v[122:125], v[170:173], v[186:189], v[122:125]
	v_mfma_f32_16x16x32_bf16 v[114:117], v[178:181], v[186:189], v[114:117]
	v_mfma_f32_16x16x32_bf16 v[106:109], v[170:173], v[194:197], v[106:109]
	v_mfma_f32_16x16x32_bf16 v[98:101], v[178:181], v[194:197], v[98:101]
	v_mfma_f32_16x16x32_bf16 v[90:93], v[170:173], v[202:205], v[90:93]
	v_mfma_f32_16x16x32_bf16 v[82:85], v[178:181], v[202:205], v[82:85]
	v_mfma_f32_16x16x32_bf16 v[74:77], v[170:173], v[210:213], v[74:77]
	v_mfma_f32_16x16x32_bf16 v[66:69], v[178:181], v[210:213], v[66:69]
	s_setprio 0
	s_barrier
	s_add_i32 s22, s26, s48
	v_lshl_add_u64 v[214:215], v[214:215], 0, s[4:5]
	s_mov_b32 m0, s22
	ds_read_b128 v[182:185], v148 offset:49152
	ds_read_b128 v[186:189], v148 offset:50176
	ds_read_b128 v[190:193], v148 offset:51200
	ds_read_b128 v[194:197], v148 offset:52224
	ds_read_b128 v[198:201], v148 offset:53248
	ds_read_b128 v[202:205], v148 offset:54272
	ds_read_b128 v[206:209], v148 offset:55296
	ds_read_b128 v[210:213], v148 offset:56320
	global_load_lds_dwordx4 v[214:215], off
	s_add_i32 m0, s22, 0x2000
	s_add_u32 s22, s42, 0x80080
	v_lshl_add_u64 v[214:215], v[216:217], 0, s[4:5]
	s_addc_u32 s23, s43, 0
	s_add_i32 s26, s27, s48
	global_load_lds_dwordx4 v[214:215], off
	v_lshl_add_u64 v[214:215], s[22:23], 0, v[132:133]
	s_mov_b32 m0, s26
	s_nop 0
	global_load_lds_dwordx4 v[214:215], off
	v_lshl_add_u64 v[214:215], s[22:23], 0, v[136:137]
	s_add_i32 m0, s26, 0x2000
	s_nop 0
	global_load_lds_dwordx4 v[214:215], off
	v_lshl_add_u64 v[214:215], v[218:219], 0, s[4:5]
	s_mov_b32 m0, s56
	s_nop 0
	global_load_lds_dwordx4 v[214:215], off
	v_lshl_add_u64 v[214:215], v[220:221], 0, s[4:5]
	s_mov_b32 m0, s57
	s_nop 0
	global_load_lds_dwordx4 v[214:215], off
	s_waitcnt vmcnt(8)
	s_waitcnt lgkmcnt(0)
	s_barrier
	s_setprio 1
	s_waitcnt lgkmcnt(0)
	v_mfma_f32_16x16x32_bf16 v[62:65], v[150:153], v[182:185], v[62:65]
	v_mfma_f32_16x16x32_bf16 v[54:57], v[158:161], v[182:185], v[54:57]
	v_mfma_f32_16x16x32_bf16 v[46:49], v[150:153], v[190:193], v[46:49]
	v_mfma_f32_16x16x32_bf16 v[38:41], v[158:161], v[190:193], v[38:41]
	v_mfma_f32_16x16x32_bf16 v[30:33], v[150:153], v[198:201], v[30:33]
	v_mfma_f32_16x16x32_bf16 v[22:25], v[158:161], v[198:201], v[22:25]
	v_mfma_f32_16x16x32_bf16 v[14:17], v[150:153], v[206:209], v[14:17]
	v_mfma_f32_16x16x32_bf16 v[6:9], v[158:161], v[206:209], v[6:9]
	v_mfma_f32_16x16x32_bf16 v[62:65], v[154:157], v[186:189], v[62:65]
	v_mfma_f32_16x16x32_bf16 v[54:57], v[162:165], v[186:189], v[54:57]
	v_mfma_f32_16x16x32_bf16 v[46:49], v[154:157], v[194:197], v[46:49]
	v_mfma_f32_16x16x32_bf16 v[38:41], v[162:165], v[194:197], v[38:41]
	v_mfma_f32_16x16x32_bf16 v[30:33], v[154:157], v[202:205], v[30:33]
	v_mfma_f32_16x16x32_bf16 v[22:25], v[162:165], v[202:205], v[22:25]
	v_mfma_f32_16x16x32_bf16 v[14:17], v[154:157], v[210:213], v[14:17]
	v_mfma_f32_16x16x32_bf16 v[6:9], v[162:165], v[210:213], v[6:9]
	s_setprio 0
	s_setprio 1
	v_mfma_f32_16x16x32_bf16 v[58:61], v[166:169], v[182:185], v[58:61]
	v_mfma_f32_16x16x32_bf16 v[50:53], v[174:177], v[182:185], v[50:53]
	v_mfma_f32_16x16x32_bf16 v[42:45], v[166:169], v[190:193], v[42:45]
	v_mfma_f32_16x16x32_bf16 v[34:37], v[174:177], v[190:193], v[34:37]
	v_mfma_f32_16x16x32_bf16 v[26:29], v[166:169], v[198:201], v[26:29]
	v_mfma_f32_16x16x32_bf16 v[18:21], v[174:177], v[198:201], v[18:21]
	v_mfma_f32_16x16x32_bf16 v[10:13], v[166:169], v[206:209], v[10:13]
	v_mfma_f32_16x16x32_bf16 v[2:5], v[174:177], v[206:209], v[2:5]
	v_mfma_f32_16x16x32_bf16 v[58:61], v[170:173], v[186:189], v[58:61]
	v_mfma_f32_16x16x32_bf16 v[50:53], v[178:181], v[186:189], v[50:53]
	v_mfma_f32_16x16x32_bf16 v[42:45], v[170:173], v[194:197], v[42:45]
	v_mfma_f32_16x16x32_bf16 v[34:37], v[178:181], v[194:197], v[34:37]
	v_mfma_f32_16x16x32_bf16 v[26:29], v[170:173], v[202:205], v[26:29]
	v_mfma_f32_16x16x32_bf16 v[18:21], v[178:181], v[202:205], v[18:21]
	v_mfma_f32_16x16x32_bf16 v[10:13], v[170:173], v[210:213], v[10:13]
	v_mfma_f32_16x16x32_bf16 v[2:5], v[178:181], v[210:213], v[2:5]
	s_setprio 0
	s_add_i32 s62, s62, 2
	s_cmp_gt_u32 s62, 29
	s_mov_b64 s[22:23], s[24:25]
	s_barrier
	s_cbranch_scc0 .LBB0_2886
	s_and_b64 vcc, exec, s[6:7]
	s_cbranch_vccz .LBB0_2889
	s_barrier

.LBB0_2967:
	s_add_u32 s34, s28, 0x100
	s_addc_u32 s35, s29, 0
	s_add_u32 s42, s28, 0xffffd600
	ds_read_b128 v[138:141], v159
	ds_read_b128 v[142:145], v159 offset:1024
	ds_read_b128 v[146:149], v159 offset:2048
	ds_read_b128 v[150:153], v159 offset:3072
	ds_read_b128 v[162:165], v160
	ds_read_b128 v[166:169], v160 offset:1024
	ds_read_b128 v[170:173], v160 offset:2048
	ds_read_b128 v[174:177], v160 offset:3072
	v_cmp_gt_u64_e32 vcc, s[34:35], v[136:137]
	s_addc_u32 s43, s29, -1
	s_and_b64 s[38:39], vcc, exec
	s_cselect_b32 s34, s42, s34
	s_cselect_b32 s35, s43, s35
	s_add_u32 s38, s30, s34
	s_addc_u32 s39, s31, s35
	s_add_u32 s72, s26, s34
	s_addc_u32 s73, s27, s35
	s_cmpk_eq_i32 s71, 0x52
	s_cselect_b32 s43, s3, s39
	s_cselect_b32 s42, s2, s38
	s_cselect_b32 s39, s25, s73
	s_cselect_b32 s38, s24, s72
	s_add_u32 s28, s30, s28
	s_addc_u32 s29, s31, s29
	s_add_u32 s28, s28, 0x158080
	s_addc_u32 s29, s29, 0
	v_lshl_add_u64 v[154:155], s[28:29], 0, v[128:129]
	s_add_i32 m0, s48, 0xc000
	ds_read_b128 v[178:181], v161
	ds_read_b128 v[182:185], v161 offset:1024
	ds_read_b128 v[186:189], v161 offset:2048
	ds_read_b128 v[190:193], v161 offset:3072
	ds_read_b128 v[194:197], v161 offset:4096
	ds_read_b128 v[198:201], v161 offset:5120
	ds_read_b128 v[202:205], v161 offset:6144
	ds_read_b128 v[206:209], v161 offset:7168
	global_load_lds_dwordx4 v[154:155], off
	v_lshl_add_u64 v[154:155], s[28:29], 0, v[130:131]
	s_add_i32 m0, s48, 0xe000
	s_nop 0
	global_load_lds_dwordx4 v[154:155], off
	s_waitcnt vmcnt(8)
	s_waitcnt lgkmcnt(0)
	s_barrier
	s_setprio 1
	s_waitcnt lgkmcnt(0)
	v_mfma_f32_16x16x32_bf16 v[124:127], v[138:141], v[178:181], v[124:127]
	v_mfma_f32_16x16x32_bf16 v[120:123], v[146:149], v[178:181], v[120:123]
	v_mfma_f32_16x16x32_bf16 v[112:115], v[138:141], v[186:189], v[112:115]
	v_mfma_f32_16x16x32_bf16 v[104:107], v[146:149], v[186:189], v[104:107]
	v_mfma_f32_16x16x32_bf16 v[100:103], v[138:141], v[194:197], v[100:103]
	v_mfma_f32_16x16x32_bf16 v[92:95], v[146:149], v[194:197], v[92:95]
	v_mfma_f32_16x16x32_bf16 v[80:83], v[138:141], v[202:205], v[80:83]
	v_mfma_f32_16x16x32_bf16 v[76:79], v[146:149], v[202:205], v[76:79]
	v_mfma_f32_16x16x32_bf16 v[124:127], v[142:145], v[182:185], v[124:127]
	v_mfma_f32_16x16x32_bf16 v[120:123], v[150:153], v[182:185], v[120:123]
	v_mfma_f32_16x16x32_bf16 v[112:115], v[142:145], v[190:193], v[112:115]
	v_mfma_f32_16x16x32_bf16 v[104:107], v[150:153], v[190:193], v[104:107]
	v_mfma_f32_16x16x32_bf16 v[100:103], v[142:145], v[198:201], v[100:103]
	v_mfma_f32_16x16x32_bf16 v[92:95], v[150:153], v[198:201], v[92:95]
	v_mfma_f32_16x16x32_bf16 v[80:83], v[142:145], v[206:209], v[80:83]
	v_mfma_f32_16x16x32_bf16 v[76:79], v[150:153], v[206:209], v[76:79]
	s_setprio 0
	s_setprio 1
	v_mfma_f32_16x16x32_bf16 v[116:119], v[162:165], v[178:181], v[116:119]
	v_mfma_f32_16x16x32_bf16 v[108:111], v[170:173], v[178:181], v[108:111]
	v_mfma_f32_16x16x32_bf16 v[96:99], v[162:165], v[186:189], v[96:99]
	v_mfma_f32_16x16x32_bf16 v[88:91], v[170:173], v[186:189], v[88:91]
	v_mfma_f32_16x16x32_bf16 v[84:87], v[162:165], v[194:197], v[84:87]
	v_mfma_f32_16x16x32_bf16 v[72:75], v[170:173], v[194:197], v[72:75]
	v_mfma_f32_16x16x32_bf16 v[68:71], v[162:165], v[202:205], v[68:71]
	v_mfma_f32_16x16x32_bf16 v[64:67], v[170:173], v[202:205], v[64:67]
	v_mfma_f32_16x16x32_bf16 v[116:119], v[166:169], v[182:185], v[116:119]
	v_mfma_f32_16x16x32_bf16 v[108:111], v[174:177], v[182:185], v[108:111]
	v_mfma_f32_16x16x32_bf16 v[96:99], v[166:169], v[190:193], v[96:99]
	v_mfma_f32_16x16x32_bf16 v[88:91], v[174:177], v[190:193], v[88:91]
	v_mfma_f32_16x16x32_bf16 v[84:87], v[166:169], v[198:201], v[84:87]
	v_mfma_f32_16x16x32_bf16 v[72:75], v[174:177], v[198:201], v[72:75]
	v_mfma_f32_16x16x32_bf16 v[68:71], v[166:169], v[206:209], v[68:71]
	v_mfma_f32_16x16x32_bf16 v[64:67], v[174:177], v[206:209], v[64:67]
	s_setprio 0
	s_barrier
	s_add_i32 s28, s58, s46
	v_lshl_add_u64 v[154:155], s[38:39], 0, v[128:129]
	s_mov_b32 m0, s28
	ds_read_b128 v[178:181], v161 offset:16384
	ds_read_b128 v[182:185], v161 offset:17408
	ds_read_b128 v[186:189], v161 offset:18432
	ds_read_b128 v[190:193], v161 offset:19456
	ds_read_b128 v[194:197], v161 offset:20480
	ds_read_b128 v[198:201], v161 offset:21504
	ds_read_b128 v[202:205], v161 offset:22528
	ds_read_b128 v[206:209], v161 offset:23552
	global_load_lds_dwordx4 v[154:155], off
	s_add_i32 m0, s28, 0x2000
	s_add_u32 s28, s38, 0x158000
	v_lshl_add_u64 v[210:211], s[38:39], 0, v[130:131]
	s_addc_u32 s29, s39, 0
	s_add_i32 s72, s59, s46
	global_load_lds_dwordx4 v[210:211], off
	v_lshl_add_u64 v[212:213], s[28:29], 0, v[128:129]
	s_mov_b32 m0, s72
	v_lshl_add_u64 v[214:215], s[42:43], 0, v[130:131]
	global_load_lds_dwordx4 v[212:213], off
	v_lshl_add_u64 v[212:213], s[28:29], 0, v[130:131]
	s_add_i32 m0, s72, 0x2000
	s_nop 0
	global_load_lds_dwordx4 v[212:213], off
	v_lshl_add_u64 v[212:213], s[42:43], 0, v[128:129]
	s_mov_b32 m0, s48
	s_nop 0
	global_load_lds_dwordx4 v[212:213], off
	s_mov_b32 m0, s49
	s_nop 0
	global_load_lds_dwordx4 v[214:215], off
	s_waitcnt vmcnt(8)
	s_waitcnt lgkmcnt(0)
	s_barrier
	s_setprio 1
	s_waitcnt lgkmcnt(0)
	v_mfma_f32_16x16x32_bf16 v[60:63], v[138:141], v[178:181], v[60:63]
	v_mfma_f32_16x16x32_bf16 v[56:59], v[146:149], v[178:181], v[56:59]
	v_mfma_f32_16x16x32_bf16 v[52:55], v[138:141], v[186:189], v[52:55]
	v_mfma_f32_16x16x32_bf16 v[44:47], v[146:149], v[186:189], v[44:47]
	v_mfma_f32_16x16x32_bf16 v[36:39], v[138:141], v[194:197], v[36:39]
	v_mfma_f32_16x16x32_bf16 v[28:31], v[146:149], v[194:197], v[28:31]
	v_mfma_f32_16x16x32_bf16 v[20:23], v[138:141], v[202:205], v[20:23]
	v_mfma_f32_16x16x32_bf16 v[12:15], v[146:149], v[202:205], v[12:15]
	v_mfma_f32_16x16x32_bf16 v[60:63], v[142:145], v[182:185], v[60:63]
	v_mfma_f32_16x16x32_bf16 v[56:59], v[150:153], v[182:185], v[56:59]
	v_mfma_f32_16x16x32_bf16 v[52:55], v[142:145], v[190:193], v[52:55]
	v_mfma_f32_16x16x32_bf16 v[44:47], v[150:153], v[190:193], v[44:47]
	v_mfma_f32_16x16x32_bf16 v[36:39], v[142:145], v[198:201], v[36:39]
	v_mfma_f32_16x16x32_bf16 v[28:31], v[150:153], v[198:201], v[28:31]
	v_mfma_f32_16x16x32_bf16 v[20:23], v[142:145], v[206:209], v[20:23]
	v_mfma_f32_16x16x32_bf16 v[12:15], v[150:153], v[206:209], v[12:15]
	s_setprio 0
	s_setprio 1
	v_mfma_f32_16x16x32_bf16 v[48:51], v[162:165], v[178:181], v[48:51]
	v_mfma_f32_16x16x32_bf16 v[40:43], v[170:173], v[178:181], v[40:43]
	v_mfma_f32_16x16x32_bf16 v[32:35], v[162:165], v[186:189], v[32:35]
	v_mfma_f32_16x16x32_bf16 v[24:27], v[170:173], v[186:189], v[24:27]
	v_mfma_f32_16x16x32_bf16 v[16:19], v[162:165], v[194:197], v[16:19]
	v_mfma_f32_16x16x32_bf16 v[8:11], v[170:173], v[194:197], v[8:11]
	v_mfma_f32_16x16x32_bf16 v[4:7], v[162:165], v[202:205], v[4:7]
	v_mfma_f32_16x16x32_bf16 v[0:3], v[170:173], v[202:205], v[0:3]
	v_mfma_f32_16x16x32_bf16 v[48:51], v[166:169], v[182:185], v[48:51]
	v_mfma_f32_16x16x32_bf16 v[40:43], v[174:177], v[182:185], v[40:43]
	v_mfma_f32_16x16x32_bf16 v[32:35], v[166:169], v[190:193], v[32:35]
	v_mfma_f32_16x16x32_bf16 v[24:27], v[174:177], v[190:193], v[24:27]
	v_mfma_f32_16x16x32_bf16 v[16:19], v[166:169], v[198:201], v[16:19]
	v_mfma_f32_16x16x32_bf16 v[8:11], v[174:177], v[198:201], v[8:11]
	v_mfma_f32_16x16x32_bf16 v[4:7], v[166:169], v[206:209], v[4:7]
	v_mfma_f32_16x16x32_bf16 v[0:3], v[174:177], v[206:209], v[0:3]
	s_setprio 0
	s_barrier
	s_add_i32 s72, 0, 0x18000
	s_add_i32 s73, 0, 0x1c000
	v_add_u32_e32 v150, s72, v157
	v_add_u32_e32 v174, s73, v157
	ds_read_b128 v[138:141], v150
	ds_read_b128 v[142:145], v150 offset:1024
	ds_read_b128 v[146:149], v150 offset:2048
	ds_read_b128 v[150:153], v150 offset:3072
	ds_read_b128 v[162:165], v174
	ds_read_b128 v[166:169], v174 offset:1024
	ds_read_b128 v[170:173], v174 offset:2048
	ds_read_b128 v[174:177], v174 offset:3072
	s_add_u32 s28, s42, 0x158000
	s_addc_u32 s29, s43, 0
	s_mov_b32 m0, s50
	v_lshl_add_u64 v[216:217], s[28:29], 0, v[128:129]
	ds_read_b128 v[178:181], v161 offset:32768
	ds_read_b128 v[182:185], v161 offset:33792
	ds_read_b128 v[186:189], v161 offset:34816
	ds_read_b128 v[190:193], v161 offset:35840
	ds_read_b128 v[194:197], v161 offset:36864
	ds_read_b128 v[198:201], v161 offset:37888
	ds_read_b128 v[202:205], v161 offset:38912
	ds_read_b128 v[206:209], v161 offset:39936
	global_load_lds_dwordx4 v[216:217], off
	v_lshl_add_u64 v[216:217], s[28:29], 0, v[130:131]
	s_mov_b32 m0, s51
	s_nop 0
	global_load_lds_dwordx4 v[216:217], off
	s_waitcnt vmcnt(8)
	s_waitcnt lgkmcnt(0)
	s_barrier
	s_setprio 1
	s_waitcnt lgkmcnt(0)
	v_mfma_f32_16x16x32_bf16 v[124:127], v[138:141], v[178:181], v[124:127]
	v_mfma_f32_16x16x32_bf16 v[120:123], v[146:149], v[178:181], v[120:123]
	v_mfma_f32_16x16x32_bf16 v[112:115], v[138:141], v[186:189], v[112:115]
	v_mfma_f32_16x16x32_bf16 v[104:107], v[146:149], v[186:189], v[104:107]
	v_mfma_f32_16x16x32_bf16 v[100:103], v[138:141], v[194:197], v[100:103]
	v_mfma_f32_16x16x32_bf16 v[92:95], v[146:149], v[194:197], v[92:95]
	v_mfma_f32_16x16x32_bf16 v[80:83], v[138:141], v[202:205], v[80:83]
	v_mfma_f32_16x16x32_bf16 v[76:79], v[146:149], v[202:205], v[76:79]
	v_mfma_f32_16x16x32_bf16 v[124:127], v[142:145], v[182:185], v[124:127]
	v_mfma_f32_16x16x32_bf16 v[120:123], v[150:153], v[182:185], v[120:123]
	v_mfma_f32_16x16x32_bf16 v[112:115], v[142:145], v[190:193], v[112:115]
	v_mfma_f32_16x16x32_bf16 v[104:107], v[150:153], v[190:193], v[104:107]
	v_mfma_f32_16x16x32_bf16 v[100:103], v[142:145], v[198:201], v[100:103]
	v_mfma_f32_16x16x32_bf16 v[92:95], v[150:153], v[198:201], v[92:95]
	v_mfma_f32_16x16x32_bf16 v[80:83], v[142:145], v[206:209], v[80:83]
	v_mfma_f32_16x16x32_bf16 v[76:79], v[150:153], v[206:209], v[76:79]
	s_setprio 0
	s_setprio 1
	v_mfma_f32_16x16x32_bf16 v[116:119], v[162:165], v[178:181], v[116:119]
	v_mfma_f32_16x16x32_bf16 v[108:111], v[170:173], v[178:181], v[108:111]
	v_mfma_f32_16x16x32_bf16 v[96:99], v[162:165], v[186:189], v[96:99]
	v_mfma_f32_16x16x32_bf16 v[88:91], v[170:173], v[186:189], v[88:91]
	v_mfma_f32_16x16x32_bf16 v[84:87], v[162:165], v[194:197], v[84:87]
	v_mfma_f32_16x16x32_bf16 v[72:75], v[170:173], v[194:197], v[72:75]
	v_mfma_f32_16x16x32_bf16 v[68:71], v[162:165], v[202:205], v[68:71]
	v_mfma_f32_16x16x32_bf16 v[64:67], v[170:173], v[202:205], v[64:67]
	v_mfma_f32_16x16x32_bf16 v[116:119], v[166:169], v[182:185], v[116:119]
	v_mfma_f32_16x16x32_bf16 v[108:111], v[174:177], v[182:185], v[108:111]
	v_mfma_f32_16x16x32_bf16 v[96:99], v[166:169], v[190:193], v[96:99]
	v_mfma_f32_16x16x32_bf16 v[88:91], v[174:177], v[190:193], v[88:91]
	v_mfma_f32_16x16x32_bf16 v[84:87], v[166:169], v[198:201], v[84:87]
	v_mfma_f32_16x16x32_bf16 v[72:75], v[174:177], v[198:201], v[72:75]
	v_mfma_f32_16x16x32_bf16 v[68:71], v[166:169], v[206:209], v[68:71]
	v_mfma_f32_16x16x32_bf16 v[64:67], v[174:177], v[206:209], v[64:67]
	s_setprio 0
	s_barrier
	s_add_i32 s28, s72, s46
	v_lshl_add_u64 v[154:155], v[154:155], 0, s[6:7]
	s_mov_b32 m0, s28
	ds_read_b128 v[178:181], v161 offset:49152
	ds_read_b128 v[182:185], v161 offset:50176
	ds_read_b128 v[186:189], v161 offset:51200
	ds_read_b128 v[190:193], v161 offset:52224
	ds_read_b128 v[194:197], v161 offset:53248
	ds_read_b128 v[198:201], v161 offset:54272
	ds_read_b128 v[202:205], v161 offset:55296
	ds_read_b128 v[206:209], v161 offset:56320
	global_load_lds_dwordx4 v[154:155], off
	s_add_i32 m0, s28, 0x2000
	s_add_u32 s28, s38, 0x158080
	v_lshl_add_u64 v[154:155], v[210:211], 0, s[6:7]
	s_addc_u32 s29, s39, 0
	s_add_i32 s38, s73, s46
	global_load_lds_dwordx4 v[154:155], off
	v_lshl_add_u64 v[154:155], s[28:29], 0, v[128:129]
	s_mov_b32 m0, s38
	s_nop 0
	global_load_lds_dwordx4 v[154:155], off
	v_lshl_add_u64 v[154:155], s[28:29], 0, v[130:131]
	s_add_i32 m0, s38, 0x2000
	s_nop 0
	global_load_lds_dwordx4 v[154:155], off
	v_lshl_add_u64 v[154:155], v[212:213], 0, s[6:7]
	s_mov_b32 m0, s56
	s_nop 0
	global_load_lds_dwordx4 v[154:155], off
	v_lshl_add_u64 v[154:155], v[214:215], 0, s[6:7]
	s_mov_b32 m0, s57
	s_nop 0
	global_load_lds_dwordx4 v[154:155], off
	s_waitcnt vmcnt(8)
	s_waitcnt lgkmcnt(0)
	s_barrier
	s_setprio 1
	s_waitcnt lgkmcnt(0)
	v_mfma_f32_16x16x32_bf16 v[60:63], v[138:141], v[178:181], v[60:63]
	v_mfma_f32_16x16x32_bf16 v[56:59], v[146:149], v[178:181], v[56:59]
	v_mfma_f32_16x16x32_bf16 v[52:55], v[138:141], v[186:189], v[52:55]
	v_mfma_f32_16x16x32_bf16 v[44:47], v[146:149], v[186:189], v[44:47]
	v_mfma_f32_16x16x32_bf16 v[36:39], v[138:141], v[194:197], v[36:39]
	v_mfma_f32_16x16x32_bf16 v[28:31], v[146:149], v[194:197], v[28:31]
	v_mfma_f32_16x16x32_bf16 v[20:23], v[138:141], v[202:205], v[20:23]
	v_mfma_f32_16x16x32_bf16 v[12:15], v[146:149], v[202:205], v[12:15]
	v_mfma_f32_16x16x32_bf16 v[60:63], v[142:145], v[182:185], v[60:63]
	v_mfma_f32_16x16x32_bf16 v[56:59], v[150:153], v[182:185], v[56:59]
	v_mfma_f32_16x16x32_bf16 v[52:55], v[142:145], v[190:193], v[52:55]
	v_mfma_f32_16x16x32_bf16 v[44:47], v[150:153], v[190:193], v[44:47]
	v_mfma_f32_16x16x32_bf16 v[36:39], v[142:145], v[198:201], v[36:39]
	v_mfma_f32_16x16x32_bf16 v[28:31], v[150:153], v[198:201], v[28:31]
	v_mfma_f32_16x16x32_bf16 v[20:23], v[142:145], v[206:209], v[20:23]
	v_mfma_f32_16x16x32_bf16 v[12:15], v[150:153], v[206:209], v[12:15]
	s_setprio 0
	s_setprio 1
	v_mfma_f32_16x16x32_bf16 v[48:51], v[162:165], v[178:181], v[48:51]
	v_mfma_f32_16x16x32_bf16 v[40:43], v[170:173], v[178:181], v[40:43]
	v_mfma_f32_16x16x32_bf16 v[32:35], v[162:165], v[186:189], v[32:35]
	v_mfma_f32_16x16x32_bf16 v[24:27], v[170:173], v[186:189], v[24:27]
	v_mfma_f32_16x16x32_bf16 v[16:19], v[162:165], v[194:197], v[16:19]
	v_mfma_f32_16x16x32_bf16 v[8:11], v[170:173], v[194:197], v[8:11]
	v_mfma_f32_16x16x32_bf16 v[4:7], v[162:165], v[202:205], v[4:7]
	v_mfma_f32_16x16x32_bf16 v[0:3], v[170:173], v[202:205], v[0:3]
	v_mfma_f32_16x16x32_bf16 v[48:51], v[166:169], v[182:185], v[48:51]
	v_mfma_f32_16x16x32_bf16 v[40:43], v[174:177], v[182:185], v[40:43]
	v_mfma_f32_16x16x32_bf16 v[32:35], v[166:169], v[190:193], v[32:35]
	v_mfma_f32_16x16x32_bf16 v[24:27], v[174:177], v[190:193], v[24:27]
	v_mfma_f32_16x16x32_bf16 v[16:19], v[166:169], v[198:201], v[16:19]
	v_mfma_f32_16x16x32_bf16 v[8:11], v[174:177], v[198:201], v[8:11]
	v_mfma_f32_16x16x32_bf16 v[4:7], v[166:169], v[206:209], v[4:7]
	v_mfma_f32_16x16x32_bf16 v[0:3], v[174:177], v[206:209], v[0:3]
	s_setprio 0
	s_add_i32 s71, s71, 2
	s_cmpk_gt_u32 s71, 0x53
	s_mov_b64 s[28:29], s[34:35]
	s_barrier
	s_cbranch_scc0 .LBB0_2967
	s_and_b64 vcc, exec, s[8:9]
	s_cbranch_vccz .LBB0_2970
	s_barrier
